# rows_update phases (6,9,13,16): loads issued 3 rows ahead (4 register sets) instead of 2
# baseline (speedup 1.0000x reference)
.LBB0_550:
	s_cmp_lt_i32 s24, 7
	s_cselect_b64 s[4:5], -1, 0
	s_cmp_gt_i32 s25, 6
	s_cselect_b64 s[6:7], -1, 0
	s_and_b64 s[4:5], s[4:5], s[6:7]
	s_andn2_b64 vcc, exec, s[4:5]
	v_lshlrev_b32_e32 v147, 4, v129
	s_cbranch_vccnz .LBB0_655
	s_mov_b64 exec, -1
	s_load_dword s3, s[0:1], 0x148
	s_add_u32 s8, s0, 0x148
	s_addc_u32 s9, s1, 0
	s_load_dwordx2 s[78:79], s[0:1], 0x30
	s_load_dwordx2 s[80:81], s[0:1], 0x38
	v_lshrrev_b32_e32 v0, 6, v129
	v_and_b32_e32 v1, 63, v129
	v_readfirstlane_b32 s68, v0
	v_lshlrev_b32_e32 v0, 4, v1
	v_lshlrev_b32_e32 v1, 3, v1
	v_mov_b32_e32 v2, 0x3a800000
	v_mov_b32_e32 v3, 0x358637bd
	s_lshl_b32 s69, s2, 3
	s_add_u32 s68, s68, s69
	s_waitcnt lgkmcnt(0)
	global_load_dwordx4 v[4:7], v0, s[78:79] offset:0
	global_load_dwordx4 v[8:11], v0, s[78:79] offset:1024
	global_load_dwordx4 v[12:15], v0, s[78:79] offset:2048
	global_load_dwordx4 v[16:19], v0, s[78:79] offset:3072
	global_load_dwordx4 v[100:103], v0, s[80:81] offset:0
	global_load_dwordx4 v[104:107], v0, s[80:81] offset:1024
	global_load_dwordx4 v[108:111], v0, s[80:81] offset:2048
	global_load_dwordx4 v[112:115], v0, s[80:81] offset:3072
	s_lshl_b32 s86, s68, 11
	s_add_u32 s70, s46, s86
	s_addc_u32 s71, s47, 0
	s_add_u32 s72, s50, s86
	s_addc_u32 s73, s51, 0
	s_mov_b64 s[74:75], s[72:73]
	s_add_u32 s76, s44, s86
	s_addc_u32 s77, s45, 0
	s_cmpk_lt_u32 s68, 0x200
	s_cselect_b32 s82, 1, 0
	global_load_dwordx2 v[20:21], v1, s[70:71] offset:0
	global_load_dwordx2 v[22:23], v1, s[70:71] offset:512
	global_load_dwordx2 v[24:25], v1, s[70:71] offset:1024
	global_load_dwordx2 v[26:27], v1, s[70:71] offset:1536
	global_load_dwordx2 v[28:29], v1, s[72:73] offset:0
	global_load_dwordx2 v[30:31], v1, s[72:73] offset:512
	global_load_dwordx2 v[32:33], v1, s[72:73] offset:1024
	global_load_dwordx2 v[34:35], v1, s[72:73] offset:1536
	s_add_u32 s70, s70, 0x400000
	s_addc_u32 s71, s71, 0
	s_add_u32 s72, s72, 0x400000
	s_addc_u32 s73, s73, 0
	global_load_dwordx2 v[36:37], v1, s[70:71] offset:0
	global_load_dwordx2 v[38:39], v1, s[70:71] offset:512
	global_load_dwordx2 v[40:41], v1, s[70:71] offset:1024
	global_load_dwordx2 v[42:43], v1, s[70:71] offset:1536
	global_load_dwordx2 v[44:45], v1, s[72:73] offset:0
	global_load_dwordx2 v[46:47], v1, s[72:73] offset:512
	global_load_dwordx2 v[48:49], v1, s[72:73] offset:1024
	global_load_dwordx2 v[50:51], v1, s[72:73] offset:1536
	s_add_u32 s70, s70, 0x400000
	s_addc_u32 s71, s71, 0
	s_add_u32 s72, s72, 0x400000
	s_addc_u32 s73, s73, 0
	global_load_dwordx2 v[52:53], v1, s[70:71] offset:0
	global_load_dwordx2 v[54:55], v1, s[70:71] offset:512
	global_load_dwordx2 v[56:57], v1, s[70:71] offset:1024
	global_load_dwordx2 v[58:59], v1, s[70:71] offset:1536
	global_load_dwordx2 v[60:61], v1, s[72:73] offset:0
	global_load_dwordx2 v[62:63], v1, s[72:73] offset:512
	global_load_dwordx2 v[64:65], v1, s[72:73] offset:1024
	global_load_dwordx2 v[66:67], v1, s[72:73] offset:1536
	s_add_u32 s70, s70, 0x400000
	s_addc_u32 s71, s71, 0
	s_add_u32 s72, s72, 0x400000
	s_addc_u32 s73, s73, 0
	global_load_dwordx2 v[184:185], v1, s[70:71] offset:0
	global_load_dwordx2 v[186:187], v1, s[70:71] offset:512
	global_load_dwordx2 v[188:189], v1, s[70:71] offset:1024
	global_load_dwordx2 v[190:191], v1, s[70:71] offset:1536
	global_load_dwordx2 v[192:193], v1, s[72:73] offset:0
	global_load_dwordx2 v[194:195], v1, s[72:73] offset:512
	global_load_dwordx2 v[196:197], v1, s[72:73] offset:1024
	global_load_dwordx2 v[198:199], v1, s[72:73] offset:1536
	s_add_u32 s70, s70, 0x400000
	s_addc_u32 s71, s71, 0
	s_add_u32 s72, s72, 0x400000
	s_addc_u32 s73, s73, 0
	s_waitcnt vmcnt(24)
	v_lshlrev_b32_e32 v68, 16, v20
	v_and_b32_e32 v69, 0xffff0000, v20
	v_lshlrev_b32_e32 v70, 16, v21
	v_and_b32_e32 v71, 0xffff0000, v21
	v_lshlrev_b32_e32 v72, 16, v22
	v_and_b32_e32 v73, 0xffff0000, v22
	v_lshlrev_b32_e32 v74, 16, v23
	v_and_b32_e32 v75, 0xffff0000, v23
	v_lshlrev_b32_e32 v76, 16, v24
	v_and_b32_e32 v77, 0xffff0000, v24
	v_lshlrev_b32_e32 v78, 16, v25
	v_and_b32_e32 v79, 0xffff0000, v25
	v_lshlrev_b32_e32 v80, 16, v26
	v_and_b32_e32 v81, 0xffff0000, v26
	v_lshlrev_b32_e32 v82, 16, v27
	v_and_b32_e32 v83, 0xffff0000, v27
	v_mul_f32_e32 v86, v68, v68
	v_mul_f32_e32 v87, v72, v72
	v_mul_f32_e32 v88, v76, v76
	v_mul_f32_e32 v89, v80, v80
	v_fmac_f32_e32 v86, v69, v69
	v_fmac_f32_e32 v87, v73, v73
	v_fmac_f32_e32 v88, v77, v77
	v_fmac_f32_e32 v89, v81, v81
	v_fmac_f32_e32 v86, v70, v70
	v_fmac_f32_e32 v87, v74, v74
	v_fmac_f32_e32 v88, v78, v78
	v_fmac_f32_e32 v89, v82, v82
	v_fmac_f32_e32 v86, v71, v71
	v_fmac_f32_e32 v87, v75, v75
	v_fmac_f32_e32 v88, v79, v79
	v_fmac_f32_e32 v89, v83, v83
	v_add_f32_e32 v84, v86, v87
	v_add_f32_e32 v84, v84, v88
	v_add_f32_e32 v84, v84, v89
	v_lshlrev_b32_e32 v160, 16, v28
	v_and_b32_e32 v161, 0xffff0000, v28
	v_add_f32_dpp v84, v84, v84 quad_perm:[1,0,3,2] row_mask:0xf bank_mask:0xf
	v_lshlrev_b32_e32 v162, 16, v29
	v_and_b32_e32 v163, 0xffff0000, v29
	v_add_f32_dpp v84, v84, v84 quad_perm:[2,3,0,1] row_mask:0xf bank_mask:0xf
	v_lshlrev_b32_e32 v164, 16, v30
	v_and_b32_e32 v165, 0xffff0000, v30
	v_add_f32_dpp v84, v84, v84 row_half_mirror row_mask:0xf bank_mask:0xf
	v_lshlrev_b32_e32 v166, 16, v31
	v_and_b32_e32 v167, 0xffff0000, v31
	v_add_f32_dpp v84, v84, v84 row_mirror row_mask:0xf bank_mask:0xf
	v_lshlrev_b32_e32 v168, 16, v32
	v_and_b32_e32 v169, 0xffff0000, v32
	v_add_f32_dpp v84, v84, v84 row_bcast:15 row_mask:0xa bank_mask:0xf
	v_lshlrev_b32_e32 v170, 16, v33
	v_and_b32_e32 v171, 0xffff0000, v33
	v_add_f32_dpp v84, v84, v84 row_bcast:31 row_mask:0xc bank_mask:0xf
	v_lshlrev_b32_e32 v172, 16, v34
	v_and_b32_e32 v173, 0xffff0000, v34
	v_lshlrev_b32_e32 v174, 16, v35
	v_and_b32_e32 v175, 0xffff0000, v35
	s_nop 0
	v_readlane_b32 s83, v84, 63
	s_nop 2
	v_fma_f32 v84, s83, v2, v3
	v_rsq_f32_e32 v84, v84
	s_nop 0
	v_mul_f32_e32 v68, v68, v84
	v_mul_f32_e32 v69, v69, v84
	v_mul_f32_e32 v70, v70, v84
	v_mul_f32_e32 v71, v71, v84
	v_mul_f32_e32 v72, v72, v84
	v_mul_f32_e32 v73, v73, v84
	v_mul_f32_e32 v74, v74, v84
	v_mul_f32_e32 v75, v75, v84
	v_mul_f32_e32 v76, v76, v84
	v_mul_f32_e32 v77, v77, v84
	v_mul_f32_e32 v78, v78, v84
	v_mul_f32_e32 v79, v79, v84
	v_mul_f32_e32 v80, v80, v84
	v_mul_f32_e32 v81, v81, v84
	v_mul_f32_e32 v82, v82, v84
	v_mul_f32_e32 v83, v83, v84
	v_fma_f32 v68, v68, v4, v160
	v_fma_f32 v69, v69, v5, v161
	v_fma_f32 v70, v70, v6, v162
	v_fma_f32 v71, v71, v7, v163
	v_fma_f32 v72, v72, v8, v164
	v_fma_f32 v73, v73, v9, v165
	v_fma_f32 v74, v74, v10, v166
	v_fma_f32 v75, v75, v11, v167
	v_fma_f32 v76, v76, v12, v168
	v_fma_f32 v77, v77, v13, v169
	v_fma_f32 v78, v78, v14, v170
	v_fma_f32 v79, v79, v15, v171
	v_fma_f32 v80, v80, v16, v172
	v_fma_f32 v81, v81, v17, v173
	v_fma_f32 v82, v82, v18, v174
	v_fma_f32 v83, v83, v19, v175
	v_mul_f32_e32 v86, v68, v68
	v_mul_f32_e32 v87, v72, v72
	v_mul_f32_e32 v88, v76, v76
	v_mul_f32_e32 v89, v80, v80
	v_fmac_f32_e32 v86, v69, v69
	v_fmac_f32_e32 v87, v73, v73
	v_fmac_f32_e32 v88, v77, v77
	v_fmac_f32_e32 v89, v81, v81
	v_fmac_f32_e32 v86, v70, v70
	v_fmac_f32_e32 v87, v74, v74
	v_fmac_f32_e32 v88, v78, v78
	v_fmac_f32_e32 v89, v82, v82
	v_fmac_f32_e32 v86, v71, v71
	v_fmac_f32_e32 v87, v75, v75
	v_fmac_f32_e32 v88, v79, v79
	v_fmac_f32_e32 v89, v83, v83
	v_add_f32_e32 v85, v86, v87
	v_add_f32_e32 v85, v85, v88
	v_add_f32_e32 v85, v85, v89
	v_cvt_pk_bf16_f32 v90, v68, v69
	v_cvt_pk_bf16_f32 v91, v70, v71
	v_add_f32_dpp v85, v85, v85 quad_perm:[1,0,3,2] row_mask:0xf bank_mask:0xf
	v_cvt_pk_bf16_f32 v92, v72, v73
	v_cvt_pk_bf16_f32 v93, v74, v75
	v_add_f32_dpp v85, v85, v85 quad_perm:[2,3,0,1] row_mask:0xf bank_mask:0xf
	v_cvt_pk_bf16_f32 v94, v76, v77
	v_cvt_pk_bf16_f32 v95, v78, v79
	v_add_f32_dpp v85, v85, v85 row_half_mirror row_mask:0xf bank_mask:0xf
	v_cvt_pk_bf16_f32 v96, v80, v81
	v_cvt_pk_bf16_f32 v97, v82, v83
	v_add_f32_dpp v85, v85, v85 row_mirror row_mask:0xf bank_mask:0xf
	s_nop 1
	v_add_f32_dpp v85, v85, v85 row_bcast:15 row_mask:0xa bank_mask:0xf
	s_nop 1
	v_add_f32_dpp v85, v85, v85 row_bcast:31 row_mask:0xc bank_mask:0xf
	global_store_dwordx2 v1, v[90:91], s[74:75] offset:0
	global_store_dwordx2 v1, v[92:93], s[74:75] offset:512
	global_store_dwordx2 v1, v[94:95], s[74:75] offset:1024
	global_store_dwordx2 v1, v[96:97], s[74:75] offset:1536
	v_readlane_b32 s84, v85, 63
	s_add_u32 s74, s74, 0x400000
	s_addc_u32 s75, s75, 0
	s_nop 0
	v_fma_f32 v85, s84, v2, v3
	v_rsq_f32_e32 v85, v85
	s_nop 0
	v_mul_f32_e32 v68, v68, v85
	v_mul_f32_e32 v69, v69, v85
	v_mul_f32_e32 v70, v70, v85
	v_mul_f32_e32 v71, v71, v85
	v_mul_f32_e32 v72, v72, v85
	v_mul_f32_e32 v73, v73, v85
	v_mul_f32_e32 v74, v74, v85
	v_mul_f32_e32 v75, v75, v85
	v_mul_f32_e32 v76, v76, v85
	v_mul_f32_e32 v77, v77, v85
	v_mul_f32_e32 v78, v78, v85
	v_mul_f32_e32 v79, v79, v85
	v_mul_f32_e32 v80, v80, v85
	v_mul_f32_e32 v81, v81, v85
	v_mul_f32_e32 v82, v82, v85
	v_mul_f32_e32 v83, v83, v85
	v_mul_f32_e32 v68, v68, v100
	v_mul_f32_e32 v69, v69, v101
	v_mul_f32_e32 v70, v70, v102
	v_mul_f32_e32 v71, v71, v103
	v_mul_f32_e32 v72, v72, v104
	v_mul_f32_e32 v73, v73, v105
	v_mul_f32_e32 v74, v74, v106
	v_mul_f32_e32 v75, v75, v107
	v_mul_f32_e32 v76, v76, v108
	v_mul_f32_e32 v77, v77, v109
	v_mul_f32_e32 v78, v78, v110
	v_mul_f32_e32 v79, v79, v111
	v_mul_f32_e32 v80, v80, v112
	v_mul_f32_e32 v81, v81, v113
	v_mul_f32_e32 v82, v82, v114
	v_mul_f32_e32 v83, v83, v115
	v_cvt_pk_bf16_f32 v176, v68, v69
	v_cvt_pk_bf16_f32 v177, v70, v71
	v_cvt_pk_bf16_f32 v178, v72, v73
	v_cvt_pk_bf16_f32 v179, v74, v75
	v_cvt_pk_bf16_f32 v180, v76, v77
	v_cvt_pk_bf16_f32 v181, v78, v79
	v_cvt_pk_bf16_f32 v182, v80, v81
	v_cvt_pk_bf16_f32 v183, v82, v83
	global_store_dwordx2 v1, v[176:177], s[76:77] offset:0
	global_store_dwordx2 v1, v[178:179], s[76:77] offset:512
	global_store_dwordx2 v1, v[180:181], s[76:77] offset:1024
	global_store_dwordx2 v1, v[182:183], s[76:77] offset:1536
	s_add_u32 s76, s76, 0x400000
	s_addc_u32 s77, s77, 0
	global_load_dwordx2 v[20:21], v1, s[70:71] offset:0
	global_load_dwordx2 v[22:23], v1, s[70:71] offset:512
	global_load_dwordx2 v[24:25], v1, s[70:71] offset:1024
	global_load_dwordx2 v[26:27], v1, s[70:71] offset:1536
	global_load_dwordx2 v[28:29], v1, s[72:73] offset:0
	global_load_dwordx2 v[30:31], v1, s[72:73] offset:512
	global_load_dwordx2 v[32:33], v1, s[72:73] offset:1024
	global_load_dwordx2 v[34:35], v1, s[72:73] offset:1536
	s_add_u32 s70, s70, 0x400000
	s_addc_u32 s71, s71, 0
	s_add_u32 s72, s72, 0x400000
	s_addc_u32 s73, s73, 0
	s_waitcnt vmcnt(32)
	v_lshlrev_b32_e32 v68, 16, v36
	v_and_b32_e32 v69, 0xffff0000, v36
	v_lshlrev_b32_e32 v70, 16, v37
	v_and_b32_e32 v71, 0xffff0000, v37
	v_lshlrev_b32_e32 v72, 16, v38
	v_and_b32_e32 v73, 0xffff0000, v38
	v_lshlrev_b32_e32 v74, 16, v39
	v_and_b32_e32 v75, 0xffff0000, v39
	v_lshlrev_b32_e32 v76, 16, v40
	v_and_b32_e32 v77, 0xffff0000, v40
	v_lshlrev_b32_e32 v78, 16, v41
	v_and_b32_e32 v79, 0xffff0000, v41
	v_lshlrev_b32_e32 v80, 16, v42
	v_and_b32_e32 v81, 0xffff0000, v42
	v_lshlrev_b32_e32 v82, 16, v43
	v_and_b32_e32 v83, 0xffff0000, v43
	v_mul_f32_e32 v86, v68, v68
	v_mul_f32_e32 v87, v72, v72
	v_mul_f32_e32 v88, v76, v76
	v_mul_f32_e32 v89, v80, v80
	v_fmac_f32_e32 v86, v69, v69
	v_fmac_f32_e32 v87, v73, v73
	v_fmac_f32_e32 v88, v77, v77
	v_fmac_f32_e32 v89, v81, v81
	v_fmac_f32_e32 v86, v70, v70
	v_fmac_f32_e32 v87, v74, v74
	v_fmac_f32_e32 v88, v78, v78
	v_fmac_f32_e32 v89, v82, v82
	v_fmac_f32_e32 v86, v71, v71
	v_fmac_f32_e32 v87, v75, v75
	v_fmac_f32_e32 v88, v79, v79
	v_fmac_f32_e32 v89, v83, v83
	v_add_f32_e32 v84, v86, v87
	v_add_f32_e32 v84, v84, v88
	v_add_f32_e32 v84, v84, v89
	v_lshlrev_b32_e32 v160, 16, v44
	v_and_b32_e32 v161, 0xffff0000, v44
	v_add_f32_dpp v84, v84, v84 quad_perm:[1,0,3,2] row_mask:0xf bank_mask:0xf
	v_lshlrev_b32_e32 v162, 16, v45
	v_and_b32_e32 v163, 0xffff0000, v45
	v_add_f32_dpp v84, v84, v84 quad_perm:[2,3,0,1] row_mask:0xf bank_mask:0xf
	v_lshlrev_b32_e32 v164, 16, v46
	v_and_b32_e32 v165, 0xffff0000, v46
	v_add_f32_dpp v84, v84, v84 row_half_mirror row_mask:0xf bank_mask:0xf
	v_lshlrev_b32_e32 v166, 16, v47
	v_and_b32_e32 v167, 0xffff0000, v47
	v_add_f32_dpp v84, v84, v84 row_mirror row_mask:0xf bank_mask:0xf
	v_lshlrev_b32_e32 v168, 16, v48
	v_and_b32_e32 v169, 0xffff0000, v48
	v_add_f32_dpp v84, v84, v84 row_bcast:15 row_mask:0xa bank_mask:0xf
	v_lshlrev_b32_e32 v170, 16, v49
	v_and_b32_e32 v171, 0xffff0000, v49
	v_add_f32_dpp v84, v84, v84 row_bcast:31 row_mask:0xc bank_mask:0xf
	v_lshlrev_b32_e32 v172, 16, v50
	v_and_b32_e32 v173, 0xffff0000, v50
	v_lshlrev_b32_e32 v174, 16, v51
	v_and_b32_e32 v175, 0xffff0000, v51
	s_nop 0
	v_readlane_b32 s83, v84, 63
	s_nop 2
	v_fma_f32 v84, s83, v2, v3
	v_rsq_f32_e32 v84, v84
	s_nop 0
	v_mul_f32_e32 v68, v68, v84
	v_mul_f32_e32 v69, v69, v84
	v_mul_f32_e32 v70, v70, v84
	v_mul_f32_e32 v71, v71, v84
	v_mul_f32_e32 v72, v72, v84
	v_mul_f32_e32 v73, v73, v84
	v_mul_f32_e32 v74, v74, v84
	v_mul_f32_e32 v75, v75, v84
	v_mul_f32_e32 v76, v76, v84
	v_mul_f32_e32 v77, v77, v84
	v_mul_f32_e32 v78, v78, v84
	v_mul_f32_e32 v79, v79, v84
	v_mul_f32_e32 v80, v80, v84
	v_mul_f32_e32 v81, v81, v84
	v_mul_f32_e32 v82, v82, v84
	v_mul_f32_e32 v83, v83, v84
	v_fma_f32 v68, v68, v4, v160
	v_fma_f32 v69, v69, v5, v161
	v_fma_f32 v70, v70, v6, v162
	v_fma_f32 v71, v71, v7, v163
	v_fma_f32 v72, v72, v8, v164
	v_fma_f32 v73, v73, v9, v165
	v_fma_f32 v74, v74, v10, v166
	v_fma_f32 v75, v75, v11, v167
	v_fma_f32 v76, v76, v12, v168
	v_fma_f32 v77, v77, v13, v169
	v_fma_f32 v78, v78, v14, v170
	v_fma_f32 v79, v79, v15, v171
	v_fma_f32 v80, v80, v16, v172
	v_fma_f32 v81, v81, v17, v173
	v_fma_f32 v82, v82, v18, v174
	v_fma_f32 v83, v83, v19, v175
	v_mul_f32_e32 v86, v68, v68
	v_mul_f32_e32 v87, v72, v72
	v_mul_f32_e32 v88, v76, v76
	v_mul_f32_e32 v89, v80, v80
	v_fmac_f32_e32 v86, v69, v69
	v_fmac_f32_e32 v87, v73, v73
	v_fmac_f32_e32 v88, v77, v77
	v_fmac_f32_e32 v89, v81, v81
	v_fmac_f32_e32 v86, v70, v70
	v_fmac_f32_e32 v87, v74, v74
	v_fmac_f32_e32 v88, v78, v78
	v_fmac_f32_e32 v89, v82, v82
	v_fmac_f32_e32 v86, v71, v71
	v_fmac_f32_e32 v87, v75, v75
	v_fmac_f32_e32 v88, v79, v79
	v_fmac_f32_e32 v89, v83, v83
	v_add_f32_e32 v85, v86, v87
	v_add_f32_e32 v85, v85, v88
	v_add_f32_e32 v85, v85, v89
	v_cvt_pk_bf16_f32 v90, v68, v69
	v_cvt_pk_bf16_f32 v91, v70, v71
	v_add_f32_dpp v85, v85, v85 quad_perm:[1,0,3,2] row_mask:0xf bank_mask:0xf
	v_cvt_pk_bf16_f32 v92, v72, v73
	v_cvt_pk_bf16_f32 v93, v74, v75
	v_add_f32_dpp v85, v85, v85 quad_perm:[2,3,0,1] row_mask:0xf bank_mask:0xf
	v_cvt_pk_bf16_f32 v94, v76, v77
	v_cvt_pk_bf16_f32 v95, v78, v79
	v_add_f32_dpp v85, v85, v85 row_half_mirror row_mask:0xf bank_mask:0xf
	v_cvt_pk_bf16_f32 v96, v80, v81
	v_cvt_pk_bf16_f32 v97, v82, v83
	v_add_f32_dpp v85, v85, v85 row_mirror row_mask:0xf bank_mask:0xf
	s_nop 1
	v_add_f32_dpp v85, v85, v85 row_bcast:15 row_mask:0xa bank_mask:0xf
	s_nop 1
	v_add_f32_dpp v85, v85, v85 row_bcast:31 row_mask:0xc bank_mask:0xf
	global_store_dwordx2 v1, v[90:91], s[74:75] offset:0
	global_store_dwordx2 v1, v[92:93], s[74:75] offset:512
	global_store_dwordx2 v1, v[94:95], s[74:75] offset:1024
	global_store_dwordx2 v1, v[96:97], s[74:75] offset:1536
	v_readlane_b32 s84, v85, 63
	s_add_u32 s74, s74, 0x400000
	s_addc_u32 s75, s75, 0
	s_nop 0
	v_fma_f32 v85, s84, v2, v3
	v_rsq_f32_e32 v85, v85
	s_nop 0
	v_mul_f32_e32 v68, v68, v85
	v_mul_f32_e32 v69, v69, v85
	v_mul_f32_e32 v70, v70, v85
	v_mul_f32_e32 v71, v71, v85
	v_mul_f32_e32 v72, v72, v85
	v_mul_f32_e32 v73, v73, v85
	v_mul_f32_e32 v74, v74, v85
	v_mul_f32_e32 v75, v75, v85
	v_mul_f32_e32 v76, v76, v85
	v_mul_f32_e32 v77, v77, v85
	v_mul_f32_e32 v78, v78, v85
	v_mul_f32_e32 v79, v79, v85
	v_mul_f32_e32 v80, v80, v85
	v_mul_f32_e32 v81, v81, v85
	v_mul_f32_e32 v82, v82, v85
	v_mul_f32_e32 v83, v83, v85
	v_mul_f32_e32 v68, v68, v100
	v_mul_f32_e32 v69, v69, v101
	v_mul_f32_e32 v70, v70, v102
	v_mul_f32_e32 v71, v71, v103
	v_mul_f32_e32 v72, v72, v104
	v_mul_f32_e32 v73, v73, v105
	v_mul_f32_e32 v74, v74, v106
	v_mul_f32_e32 v75, v75, v107
	v_mul_f32_e32 v76, v76, v108
	v_mul_f32_e32 v77, v77, v109
	v_mul_f32_e32 v78, v78, v110
	v_mul_f32_e32 v79, v79, v111
	v_mul_f32_e32 v80, v80, v112
	v_mul_f32_e32 v81, v81, v113
	v_mul_f32_e32 v82, v82, v114
	v_mul_f32_e32 v83, v83, v115
	v_cvt_pk_bf16_f32 v176, v68, v69
	v_cvt_pk_bf16_f32 v177, v70, v71
	v_cvt_pk_bf16_f32 v178, v72, v73
	v_cvt_pk_bf16_f32 v179, v74, v75
	v_cvt_pk_bf16_f32 v180, v76, v77
	v_cvt_pk_bf16_f32 v181, v78, v79
	v_cvt_pk_bf16_f32 v182, v80, v81
	v_cvt_pk_bf16_f32 v183, v82, v83
	global_store_dwordx2 v1, v[176:177], s[76:77] offset:0
	global_store_dwordx2 v1, v[178:179], s[76:77] offset:512
	global_store_dwordx2 v1, v[180:181], s[76:77] offset:1024
	global_store_dwordx2 v1, v[182:183], s[76:77] offset:1536
	s_add_u32 s76, s76, 0x400000
	s_addc_u32 s77, s77, 0
	global_load_dwordx2 v[36:37], v1, s[70:71] offset:0
	global_load_dwordx2 v[38:39], v1, s[70:71] offset:512
	global_load_dwordx2 v[40:41], v1, s[70:71] offset:1024
	global_load_dwordx2 v[42:43], v1, s[70:71] offset:1536
	global_load_dwordx2 v[44:45], v1, s[72:73] offset:0
	global_load_dwordx2 v[46:47], v1, s[72:73] offset:512
	global_load_dwordx2 v[48:49], v1, s[72:73] offset:1024
	global_load_dwordx2 v[50:51], v1, s[72:73] offset:1536
	s_add_u32 s70, s70, 0x400000
	s_addc_u32 s71, s71, 0
	s_add_u32 s72, s72, 0x400000
	s_addc_u32 s73, s73, 0
	s_waitcnt vmcnt(40)
	v_lshlrev_b32_e32 v68, 16, v52
	v_and_b32_e32 v69, 0xffff0000, v52
	v_lshlrev_b32_e32 v70, 16, v53
	v_and_b32_e32 v71, 0xffff0000, v53
	v_lshlrev_b32_e32 v72, 16, v54
	v_and_b32_e32 v73, 0xffff0000, v54
	v_lshlrev_b32_e32 v74, 16, v55
	v_and_b32_e32 v75, 0xffff0000, v55
	v_lshlrev_b32_e32 v76, 16, v56
	v_and_b32_e32 v77, 0xffff0000, v56
	v_lshlrev_b32_e32 v78, 16, v57
	v_and_b32_e32 v79, 0xffff0000, v57
	v_lshlrev_b32_e32 v80, 16, v58
	v_and_b32_e32 v81, 0xffff0000, v58
	v_lshlrev_b32_e32 v82, 16, v59
	v_and_b32_e32 v83, 0xffff0000, v59
	v_mul_f32_e32 v86, v68, v68
	v_mul_f32_e32 v87, v72, v72
	v_mul_f32_e32 v88, v76, v76
	v_mul_f32_e32 v89, v80, v80
	v_fmac_f32_e32 v86, v69, v69
	v_fmac_f32_e32 v87, v73, v73
	v_fmac_f32_e32 v88, v77, v77
	v_fmac_f32_e32 v89, v81, v81
	v_fmac_f32_e32 v86, v70, v70
	v_fmac_f32_e32 v87, v74, v74
	v_fmac_f32_e32 v88, v78, v78
	v_fmac_f32_e32 v89, v82, v82
	v_fmac_f32_e32 v86, v71, v71
	v_fmac_f32_e32 v87, v75, v75
	v_fmac_f32_e32 v88, v79, v79
	v_fmac_f32_e32 v89, v83, v83
	v_add_f32_e32 v84, v86, v87
	v_add_f32_e32 v84, v84, v88
	v_add_f32_e32 v84, v84, v89
	v_lshlrev_b32_e32 v160, 16, v60
	v_and_b32_e32 v161, 0xffff0000, v60
	v_add_f32_dpp v84, v84, v84 quad_perm:[1,0,3,2] row_mask:0xf bank_mask:0xf
	v_lshlrev_b32_e32 v162, 16, v61
	v_and_b32_e32 v163, 0xffff0000, v61
	v_add_f32_dpp v84, v84, v84 quad_perm:[2,3,0,1] row_mask:0xf bank_mask:0xf
	v_lshlrev_b32_e32 v164, 16, v62
	v_and_b32_e32 v165, 0xffff0000, v62
	v_add_f32_dpp v84, v84, v84 row_half_mirror row_mask:0xf bank_mask:0xf
	v_lshlrev_b32_e32 v166, 16, v63
	v_and_b32_e32 v167, 0xffff0000, v63
	v_add_f32_dpp v84, v84, v84 row_mirror row_mask:0xf bank_mask:0xf
	v_lshlrev_b32_e32 v168, 16, v64
	v_and_b32_e32 v169, 0xffff0000, v64
	v_add_f32_dpp v84, v84, v84 row_bcast:15 row_mask:0xa bank_mask:0xf
	v_lshlrev_b32_e32 v170, 16, v65
	v_and_b32_e32 v171, 0xffff0000, v65
	v_add_f32_dpp v84, v84, v84 row_bcast:31 row_mask:0xc bank_mask:0xf
	v_lshlrev_b32_e32 v172, 16, v66
	v_and_b32_e32 v173, 0xffff0000, v66
	v_lshlrev_b32_e32 v174, 16, v67
	v_and_b32_e32 v175, 0xffff0000, v67
	s_nop 0
	v_readlane_b32 s83, v84, 63
	s_nop 2
	v_fma_f32 v84, s83, v2, v3
	v_rsq_f32_e32 v84, v84
	s_nop 0
	v_mul_f32_e32 v68, v68, v84
	v_mul_f32_e32 v69, v69, v84
	v_mul_f32_e32 v70, v70, v84
	v_mul_f32_e32 v71, v71, v84
	v_mul_f32_e32 v72, v72, v84
	v_mul_f32_e32 v73, v73, v84
	v_mul_f32_e32 v74, v74, v84
	v_mul_f32_e32 v75, v75, v84
	v_mul_f32_e32 v76, v76, v84
	v_mul_f32_e32 v77, v77, v84
	v_mul_f32_e32 v78, v78, v84
	v_mul_f32_e32 v79, v79, v84
	v_mul_f32_e32 v80, v80, v84
	v_mul_f32_e32 v81, v81, v84
	v_mul_f32_e32 v82, v82, v84
	v_mul_f32_e32 v83, v83, v84
	v_fma_f32 v68, v68, v4, v160
	v_fma_f32 v69, v69, v5, v161
	v_fma_f32 v70, v70, v6, v162
	v_fma_f32 v71, v71, v7, v163
	v_fma_f32 v72, v72, v8, v164
	v_fma_f32 v73, v73, v9, v165
	v_fma_f32 v74, v74, v10, v166
	v_fma_f32 v75, v75, v11, v167
	v_fma_f32 v76, v76, v12, v168
	v_fma_f32 v77, v77, v13, v169
	v_fma_f32 v78, v78, v14, v170
	v_fma_f32 v79, v79, v15, v171
	v_fma_f32 v80, v80, v16, v172
	v_fma_f32 v81, v81, v17, v173
	v_fma_f32 v82, v82, v18, v174
	v_fma_f32 v83, v83, v19, v175
	v_mul_f32_e32 v86, v68, v68
	v_mul_f32_e32 v87, v72, v72
	v_mul_f32_e32 v88, v76, v76
	v_mul_f32_e32 v89, v80, v80
	v_fmac_f32_e32 v86, v69, v69
	v_fmac_f32_e32 v87, v73, v73
	v_fmac_f32_e32 v88, v77, v77
	v_fmac_f32_e32 v89, v81, v81
	v_fmac_f32_e32 v86, v70, v70
	v_fmac_f32_e32 v87, v74, v74
	v_fmac_f32_e32 v88, v78, v78
	v_fmac_f32_e32 v89, v82, v82
	v_fmac_f32_e32 v86, v71, v71
	v_fmac_f32_e32 v87, v75, v75
	v_fmac_f32_e32 v88, v79, v79
	v_fmac_f32_e32 v89, v83, v83
	v_add_f32_e32 v85, v86, v87
	v_add_f32_e32 v85, v85, v88
	v_add_f32_e32 v85, v85, v89
	v_cvt_pk_bf16_f32 v90, v68, v69
	v_cvt_pk_bf16_f32 v91, v70, v71
	v_add_f32_dpp v85, v85, v85 quad_perm:[1,0,3,2] row_mask:0xf bank_mask:0xf
	v_cvt_pk_bf16_f32 v92, v72, v73
	v_cvt_pk_bf16_f32 v93, v74, v75
	v_add_f32_dpp v85, v85, v85 quad_perm:[2,3,0,1] row_mask:0xf bank_mask:0xf
	v_cvt_pk_bf16_f32 v94, v76, v77
	v_cvt_pk_bf16_f32 v95, v78, v79
	v_add_f32_dpp v85, v85, v85 row_half_mirror row_mask:0xf bank_mask:0xf
	v_cvt_pk_bf16_f32 v96, v80, v81
	v_cvt_pk_bf16_f32 v97, v82, v83
	v_add_f32_dpp v85, v85, v85 row_mirror row_mask:0xf bank_mask:0xf
	s_nop 1
	v_add_f32_dpp v85, v85, v85 row_bcast:15 row_mask:0xa bank_mask:0xf
	s_nop 1
	v_add_f32_dpp v85, v85, v85 row_bcast:31 row_mask:0xc bank_mask:0xf
	global_store_dwordx2 v1, v[90:91], s[74:75] offset:0
	global_store_dwordx2 v1, v[92:93], s[74:75] offset:512
	global_store_dwordx2 v1, v[94:95], s[74:75] offset:1024
	global_store_dwordx2 v1, v[96:97], s[74:75] offset:1536
	v_readlane_b32 s84, v85, 63
	s_add_u32 s74, s74, 0x400000
	s_addc_u32 s75, s75, 0
	s_nop 0
	v_fma_f32 v85, s84, v2, v3
	v_rsq_f32_e32 v85, v85
	s_nop 0
	v_mul_f32_e32 v68, v68, v85
	v_mul_f32_e32 v69, v69, v85
	v_mul_f32_e32 v70, v70, v85
	v_mul_f32_e32 v71, v71, v85
	v_mul_f32_e32 v72, v72, v85
	v_mul_f32_e32 v73, v73, v85
	v_mul_f32_e32 v74, v74, v85
	v_mul_f32_e32 v75, v75, v85
	v_mul_f32_e32 v76, v76, v85
	v_mul_f32_e32 v77, v77, v85
	v_mul_f32_e32 v78, v78, v85
	v_mul_f32_e32 v79, v79, v85
	v_mul_f32_e32 v80, v80, v85
	v_mul_f32_e32 v81, v81, v85
	v_mul_f32_e32 v82, v82, v85
	v_mul_f32_e32 v83, v83, v85
	v_mul_f32_e32 v68, v68, v100
	v_mul_f32_e32 v69, v69, v101
	v_mul_f32_e32 v70, v70, v102
	v_mul_f32_e32 v71, v71, v103
	v_mul_f32_e32 v72, v72, v104
	v_mul_f32_e32 v73, v73, v105
	v_mul_f32_e32 v74, v74, v106
	v_mul_f32_e32 v75, v75, v107
	v_mul_f32_e32 v76, v76, v108
	v_mul_f32_e32 v77, v77, v109
	v_mul_f32_e32 v78, v78, v110
	v_mul_f32_e32 v79, v79, v111
	v_mul_f32_e32 v80, v80, v112
	v_mul_f32_e32 v81, v81, v113
	v_mul_f32_e32 v82, v82, v114
	v_mul_f32_e32 v83, v83, v115
	v_cvt_pk_bf16_f32 v176, v68, v69
	v_cvt_pk_bf16_f32 v177, v70, v71
	v_cvt_pk_bf16_f32 v178, v72, v73
	v_cvt_pk_bf16_f32 v179, v74, v75
	v_cvt_pk_bf16_f32 v180, v76, v77
	v_cvt_pk_bf16_f32 v181, v78, v79
	v_cvt_pk_bf16_f32 v182, v80, v81
	v_cvt_pk_bf16_f32 v183, v82, v83
	global_store_dwordx2 v1, v[176:177], s[76:77] offset:0
	global_store_dwordx2 v1, v[178:179], s[76:77] offset:512
	global_store_dwordx2 v1, v[180:181], s[76:77] offset:1024
	global_store_dwordx2 v1, v[182:183], s[76:77] offset:1536
	s_add_u32 s76, s76, 0x400000
	s_addc_u32 s77, s77, 0
	global_load_dwordx2 v[52:53], v1, s[70:71] offset:0
	global_load_dwordx2 v[54:55], v1, s[70:71] offset:512
	global_load_dwordx2 v[56:57], v1, s[70:71] offset:1024
	global_load_dwordx2 v[58:59], v1, s[70:71] offset:1536
	global_load_dwordx2 v[60:61], v1, s[72:73] offset:0
	global_load_dwordx2 v[62:63], v1, s[72:73] offset:512
	global_load_dwordx2 v[64:65], v1, s[72:73] offset:1024
	global_load_dwordx2 v[66:67], v1, s[72:73] offset:1536
	s_add_u32 s70, s70, 0x400000
	s_addc_u32 s71, s71, 0
	s_add_u32 s72, s72, 0x400000
	s_addc_u32 s73, s73, 0
	s_waitcnt vmcnt(48)
	v_lshlrev_b32_e32 v68, 16, v184
	v_and_b32_e32 v69, 0xffff0000, v184
	v_lshlrev_b32_e32 v70, 16, v185
	v_and_b32_e32 v71, 0xffff0000, v185
	v_lshlrev_b32_e32 v72, 16, v186
	v_and_b32_e32 v73, 0xffff0000, v186
	v_lshlrev_b32_e32 v74, 16, v187
	v_and_b32_e32 v75, 0xffff0000, v187
	v_lshlrev_b32_e32 v76, 16, v188
	v_and_b32_e32 v77, 0xffff0000, v188
	v_lshlrev_b32_e32 v78, 16, v189
	v_and_b32_e32 v79, 0xffff0000, v189
	v_lshlrev_b32_e32 v80, 16, v190
	v_and_b32_e32 v81, 0xffff0000, v190
	v_lshlrev_b32_e32 v82, 16, v191
	v_and_b32_e32 v83, 0xffff0000, v191
	v_mul_f32_e32 v86, v68, v68
	v_mul_f32_e32 v87, v72, v72
	v_mul_f32_e32 v88, v76, v76
	v_mul_f32_e32 v89, v80, v80
	v_fmac_f32_e32 v86, v69, v69
	v_fmac_f32_e32 v87, v73, v73
	v_fmac_f32_e32 v88, v77, v77
	v_fmac_f32_e32 v89, v81, v81
	v_fmac_f32_e32 v86, v70, v70
	v_fmac_f32_e32 v87, v74, v74
	v_fmac_f32_e32 v88, v78, v78
	v_fmac_f32_e32 v89, v82, v82
	v_fmac_f32_e32 v86, v71, v71
	v_fmac_f32_e32 v87, v75, v75
	v_fmac_f32_e32 v88, v79, v79
	v_fmac_f32_e32 v89, v83, v83
	v_add_f32_e32 v84, v86, v87
	v_add_f32_e32 v84, v84, v88
	v_add_f32_e32 v84, v84, v89
	v_lshlrev_b32_e32 v160, 16, v192
	v_and_b32_e32 v161, 0xffff0000, v192
	v_add_f32_dpp v84, v84, v84 quad_perm:[1,0,3,2] row_mask:0xf bank_mask:0xf
	v_lshlrev_b32_e32 v162, 16, v193
	v_and_b32_e32 v163, 0xffff0000, v193
	v_add_f32_dpp v84, v84, v84 quad_perm:[2,3,0,1] row_mask:0xf bank_mask:0xf
	v_lshlrev_b32_e32 v164, 16, v194
	v_and_b32_e32 v165, 0xffff0000, v194
	v_add_f32_dpp v84, v84, v84 row_half_mirror row_mask:0xf bank_mask:0xf
	v_lshlrev_b32_e32 v166, 16, v195
	v_and_b32_e32 v167, 0xffff0000, v195
	v_add_f32_dpp v84, v84, v84 row_mirror row_mask:0xf bank_mask:0xf
	v_lshlrev_b32_e32 v168, 16, v196
	v_and_b32_e32 v169, 0xffff0000, v196
	v_add_f32_dpp v84, v84, v84 row_bcast:15 row_mask:0xa bank_mask:0xf
	v_lshlrev_b32_e32 v170, 16, v197
	v_and_b32_e32 v171, 0xffff0000, v197
	v_add_f32_dpp v84, v84, v84 row_bcast:31 row_mask:0xc bank_mask:0xf
	v_lshlrev_b32_e32 v172, 16, v198
	v_and_b32_e32 v173, 0xffff0000, v198
	v_lshlrev_b32_e32 v174, 16, v199
	v_and_b32_e32 v175, 0xffff0000, v199
	s_nop 0
	v_readlane_b32 s83, v84, 63
	s_nop 2
	v_fma_f32 v84, s83, v2, v3
	v_rsq_f32_e32 v84, v84
	s_nop 0
	v_mul_f32_e32 v68, v68, v84
	v_mul_f32_e32 v69, v69, v84
	v_mul_f32_e32 v70, v70, v84
	v_mul_f32_e32 v71, v71, v84
	v_mul_f32_e32 v72, v72, v84
	v_mul_f32_e32 v73, v73, v84
	v_mul_f32_e32 v74, v74, v84
	v_mul_f32_e32 v75, v75, v84
	v_mul_f32_e32 v76, v76, v84
	v_mul_f32_e32 v77, v77, v84
	v_mul_f32_e32 v78, v78, v84
	v_mul_f32_e32 v79, v79, v84
	v_mul_f32_e32 v80, v80, v84
	v_mul_f32_e32 v81, v81, v84
	v_mul_f32_e32 v82, v82, v84
	v_mul_f32_e32 v83, v83, v84
	v_fma_f32 v68, v68, v4, v160
	v_fma_f32 v69, v69, v5, v161
	v_fma_f32 v70, v70, v6, v162
	v_fma_f32 v71, v71, v7, v163
	v_fma_f32 v72, v72, v8, v164
	v_fma_f32 v73, v73, v9, v165
	v_fma_f32 v74, v74, v10, v166
	v_fma_f32 v75, v75, v11, v167
	v_fma_f32 v76, v76, v12, v168
	v_fma_f32 v77, v77, v13, v169
	v_fma_f32 v78, v78, v14, v170
	v_fma_f32 v79, v79, v15, v171
	v_fma_f32 v80, v80, v16, v172
	v_fma_f32 v81, v81, v17, v173
	v_fma_f32 v82, v82, v18, v174
	v_fma_f32 v83, v83, v19, v175
	v_mul_f32_e32 v86, v68, v68
	v_mul_f32_e32 v87, v72, v72
	v_mul_f32_e32 v88, v76, v76
	v_mul_f32_e32 v89, v80, v80
	v_fmac_f32_e32 v86, v69, v69
	v_fmac_f32_e32 v87, v73, v73
	v_fmac_f32_e32 v88, v77, v77
	v_fmac_f32_e32 v89, v81, v81
	v_fmac_f32_e32 v86, v70, v70
	v_fmac_f32_e32 v87, v74, v74
	v_fmac_f32_e32 v88, v78, v78
	v_fmac_f32_e32 v89, v82, v82
	v_fmac_f32_e32 v86, v71, v71
	v_fmac_f32_e32 v87, v75, v75
	v_fmac_f32_e32 v88, v79, v79
	v_fmac_f32_e32 v89, v83, v83
	v_add_f32_e32 v85, v86, v87
	v_add_f32_e32 v85, v85, v88
	v_add_f32_e32 v85, v85, v89
	v_cvt_pk_bf16_f32 v90, v68, v69
	v_cvt_pk_bf16_f32 v91, v70, v71
	v_add_f32_dpp v85, v85, v85 quad_perm:[1,0,3,2] row_mask:0xf bank_mask:0xf
	v_cvt_pk_bf16_f32 v92, v72, v73
	v_cvt_pk_bf16_f32 v93, v74, v75
	v_add_f32_dpp v85, v85, v85 quad_perm:[2,3,0,1] row_mask:0xf bank_mask:0xf
	v_cvt_pk_bf16_f32 v94, v76, v77
	v_cvt_pk_bf16_f32 v95, v78, v79
	v_add_f32_dpp v85, v85, v85 row_half_mirror row_mask:0xf bank_mask:0xf
	v_cvt_pk_bf16_f32 v96, v80, v81
	v_cvt_pk_bf16_f32 v97, v82, v83
	v_add_f32_dpp v85, v85, v85 row_mirror row_mask:0xf bank_mask:0xf
	s_nop 1
	v_add_f32_dpp v85, v85, v85 row_bcast:15 row_mask:0xa bank_mask:0xf
	s_nop 1
	v_add_f32_dpp v85, v85, v85 row_bcast:31 row_mask:0xc bank_mask:0xf
	global_store_dwordx2 v1, v[90:91], s[74:75] offset:0
	global_store_dwordx2 v1, v[92:93], s[74:75] offset:512
	global_store_dwordx2 v1, v[94:95], s[74:75] offset:1024
	global_store_dwordx2 v1, v[96:97], s[74:75] offset:1536
	v_readlane_b32 s84, v85, 63
	s_add_u32 s74, s74, 0x400000
	s_addc_u32 s75, s75, 0
	s_nop 0
	v_fma_f32 v85, s84, v2, v3
	v_rsq_f32_e32 v85, v85
	s_nop 0
	v_mul_f32_e32 v68, v68, v85
	v_mul_f32_e32 v69, v69, v85
	v_mul_f32_e32 v70, v70, v85
	v_mul_f32_e32 v71, v71, v85
	v_mul_f32_e32 v72, v72, v85
	v_mul_f32_e32 v73, v73, v85
	v_mul_f32_e32 v74, v74, v85
	v_mul_f32_e32 v75, v75, v85
	v_mul_f32_e32 v76, v76, v85
	v_mul_f32_e32 v77, v77, v85
	v_mul_f32_e32 v78, v78, v85
	v_mul_f32_e32 v79, v79, v85
	v_mul_f32_e32 v80, v80, v85
	v_mul_f32_e32 v81, v81, v85
	v_mul_f32_e32 v82, v82, v85
	v_mul_f32_e32 v83, v83, v85
	v_mul_f32_e32 v68, v68, v100
	v_mul_f32_e32 v69, v69, v101
	v_mul_f32_e32 v70, v70, v102
	v_mul_f32_e32 v71, v71, v103
	v_mul_f32_e32 v72, v72, v104
	v_mul_f32_e32 v73, v73, v105
	v_mul_f32_e32 v74, v74, v106
	v_mul_f32_e32 v75, v75, v107
	v_mul_f32_e32 v76, v76, v108
	v_mul_f32_e32 v77, v77, v109
	v_mul_f32_e32 v78, v78, v110
	v_mul_f32_e32 v79, v79, v111
	v_mul_f32_e32 v80, v80, v112
	v_mul_f32_e32 v81, v81, v113
	v_mul_f32_e32 v82, v82, v114
	v_mul_f32_e32 v83, v83, v115
	v_cvt_pk_bf16_f32 v176, v68, v69
	v_cvt_pk_bf16_f32 v177, v70, v71
	v_cvt_pk_bf16_f32 v178, v72, v73
	v_cvt_pk_bf16_f32 v179, v74, v75
	v_cvt_pk_bf16_f32 v180, v76, v77
	v_cvt_pk_bf16_f32 v181, v78, v79
	v_cvt_pk_bf16_f32 v182, v80, v81
	v_cvt_pk_bf16_f32 v183, v82, v83
	global_store_dwordx2 v1, v[176:177], s[76:77] offset:0
	global_store_dwordx2 v1, v[178:179], s[76:77] offset:512
	global_store_dwordx2 v1, v[180:181], s[76:77] offset:1024
	global_store_dwordx2 v1, v[182:183], s[76:77] offset:1536
	s_add_u32 s76, s76, 0x400000
	s_addc_u32 s77, s77, 0
	global_load_dwordx2 v[184:185], v1, s[70:71] offset:0
	global_load_dwordx2 v[186:187], v1, s[70:71] offset:512
	global_load_dwordx2 v[188:189], v1, s[70:71] offset:1024
	global_load_dwordx2 v[190:191], v1, s[70:71] offset:1536
	global_load_dwordx2 v[192:193], v1, s[72:73] offset:0
	global_load_dwordx2 v[194:195], v1, s[72:73] offset:512
	global_load_dwordx2 v[196:197], v1, s[72:73] offset:1024
	global_load_dwordx2 v[198:199], v1, s[72:73] offset:1536
	s_add_u32 s70, s70, 0x400000
	s_addc_u32 s71, s71, 0
	s_add_u32 s72, s72, 0x400000
	s_addc_u32 s73, s73, 0
	s_waitcnt vmcnt(48)
	v_lshlrev_b32_e32 v68, 16, v20
	v_and_b32_e32 v69, 0xffff0000, v20
	v_lshlrev_b32_e32 v70, 16, v21
	v_and_b32_e32 v71, 0xffff0000, v21
	v_lshlrev_b32_e32 v72, 16, v22
	v_and_b32_e32 v73, 0xffff0000, v22
	v_lshlrev_b32_e32 v74, 16, v23
	v_and_b32_e32 v75, 0xffff0000, v23
	v_lshlrev_b32_e32 v76, 16, v24
	v_and_b32_e32 v77, 0xffff0000, v24
	v_lshlrev_b32_e32 v78, 16, v25
	v_and_b32_e32 v79, 0xffff0000, v25
	v_lshlrev_b32_e32 v80, 16, v26
	v_and_b32_e32 v81, 0xffff0000, v26
	v_lshlrev_b32_e32 v82, 16, v27
	v_and_b32_e32 v83, 0xffff0000, v27
	v_mul_f32_e32 v86, v68, v68
	v_mul_f32_e32 v87, v72, v72
	v_mul_f32_e32 v88, v76, v76
	v_mul_f32_e32 v89, v80, v80
	v_fmac_f32_e32 v86, v69, v69
	v_fmac_f32_e32 v87, v73, v73
	v_fmac_f32_e32 v88, v77, v77
	v_fmac_f32_e32 v89, v81, v81
	v_fmac_f32_e32 v86, v70, v70
	v_fmac_f32_e32 v87, v74, v74
	v_fmac_f32_e32 v88, v78, v78
	v_fmac_f32_e32 v89, v82, v82
	v_fmac_f32_e32 v86, v71, v71
	v_fmac_f32_e32 v87, v75, v75
	v_fmac_f32_e32 v88, v79, v79
	v_fmac_f32_e32 v89, v83, v83
	v_add_f32_e32 v84, v86, v87
	v_add_f32_e32 v84, v84, v88
	v_add_f32_e32 v84, v84, v89
	v_lshlrev_b32_e32 v160, 16, v28
	v_and_b32_e32 v161, 0xffff0000, v28
	v_add_f32_dpp v84, v84, v84 quad_perm:[1,0,3,2] row_mask:0xf bank_mask:0xf
	v_lshlrev_b32_e32 v162, 16, v29
	v_and_b32_e32 v163, 0xffff0000, v29
	v_add_f32_dpp v84, v84, v84 quad_perm:[2,3,0,1] row_mask:0xf bank_mask:0xf
	v_lshlrev_b32_e32 v164, 16, v30
	v_and_b32_e32 v165, 0xffff0000, v30
	v_add_f32_dpp v84, v84, v84 row_half_mirror row_mask:0xf bank_mask:0xf
	v_lshlrev_b32_e32 v166, 16, v31
	v_and_b32_e32 v167, 0xffff0000, v31
	v_add_f32_dpp v84, v84, v84 row_mirror row_mask:0xf bank_mask:0xf
	v_lshlrev_b32_e32 v168, 16, v32
	v_and_b32_e32 v169, 0xffff0000, v32
	v_add_f32_dpp v84, v84, v84 row_bcast:15 row_mask:0xa bank_mask:0xf
	v_lshlrev_b32_e32 v170, 16, v33
	v_and_b32_e32 v171, 0xffff0000, v33
	v_add_f32_dpp v84, v84, v84 row_bcast:31 row_mask:0xc bank_mask:0xf
	v_lshlrev_b32_e32 v172, 16, v34
	v_and_b32_e32 v173, 0xffff0000, v34
	v_lshlrev_b32_e32 v174, 16, v35
	v_and_b32_e32 v175, 0xffff0000, v35
	s_nop 0
	v_readlane_b32 s83, v84, 63
	s_nop 2
	v_fma_f32 v84, s83, v2, v3
	v_rsq_f32_e32 v84, v84
	s_nop 0
	v_mul_f32_e32 v68, v68, v84
	v_mul_f32_e32 v69, v69, v84
	v_mul_f32_e32 v70, v70, v84
	v_mul_f32_e32 v71, v71, v84
	v_mul_f32_e32 v72, v72, v84
	v_mul_f32_e32 v73, v73, v84
	v_mul_f32_e32 v74, v74, v84
	v_mul_f32_e32 v75, v75, v84
	v_mul_f32_e32 v76, v76, v84
	v_mul_f32_e32 v77, v77, v84
	v_mul_f32_e32 v78, v78, v84
	v_mul_f32_e32 v79, v79, v84
	v_mul_f32_e32 v80, v80, v84
	v_mul_f32_e32 v81, v81, v84
	v_mul_f32_e32 v82, v82, v84
	v_mul_f32_e32 v83, v83, v84
	v_fma_f32 v68, v68, v4, v160
	v_fma_f32 v69, v69, v5, v161
	v_fma_f32 v70, v70, v6, v162
	v_fma_f32 v71, v71, v7, v163
	v_fma_f32 v72, v72, v8, v164
	v_fma_f32 v73, v73, v9, v165
	v_fma_f32 v74, v74, v10, v166
	v_fma_f32 v75, v75, v11, v167
	v_fma_f32 v76, v76, v12, v168
	v_fma_f32 v77, v77, v13, v169
	v_fma_f32 v78, v78, v14, v170
	v_fma_f32 v79, v79, v15, v171
	v_fma_f32 v80, v80, v16, v172
	v_fma_f32 v81, v81, v17, v173
	v_fma_f32 v82, v82, v18, v174
	v_fma_f32 v83, v83, v19, v175
	v_mul_f32_e32 v86, v68, v68
	v_mul_f32_e32 v87, v72, v72
	v_mul_f32_e32 v88, v76, v76
	v_mul_f32_e32 v89, v80, v80
	v_fmac_f32_e32 v86, v69, v69
	v_fmac_f32_e32 v87, v73, v73
	v_fmac_f32_e32 v88, v77, v77
	v_fmac_f32_e32 v89, v81, v81
	v_fmac_f32_e32 v86, v70, v70
	v_fmac_f32_e32 v87, v74, v74
	v_fmac_f32_e32 v88, v78, v78
	v_fmac_f32_e32 v89, v82, v82
	v_fmac_f32_e32 v86, v71, v71
	v_fmac_f32_e32 v87, v75, v75
	v_fmac_f32_e32 v88, v79, v79
	v_fmac_f32_e32 v89, v83, v83
	v_add_f32_e32 v85, v86, v87
	v_add_f32_e32 v85, v85, v88
	v_add_f32_e32 v85, v85, v89
	v_cvt_pk_bf16_f32 v90, v68, v69
	v_cvt_pk_bf16_f32 v91, v70, v71
	v_add_f32_dpp v85, v85, v85 quad_perm:[1,0,3,2] row_mask:0xf bank_mask:0xf
	v_cvt_pk_bf16_f32 v92, v72, v73
	v_cvt_pk_bf16_f32 v93, v74, v75
	v_add_f32_dpp v85, v85, v85 quad_perm:[2,3,0,1] row_mask:0xf bank_mask:0xf
	v_cvt_pk_bf16_f32 v94, v76, v77
	v_cvt_pk_bf16_f32 v95, v78, v79
	v_add_f32_dpp v85, v85, v85 row_half_mirror row_mask:0xf bank_mask:0xf
	v_cvt_pk_bf16_f32 v96, v80, v81
	v_cvt_pk_bf16_f32 v97, v82, v83
	v_add_f32_dpp v85, v85, v85 row_mirror row_mask:0xf bank_mask:0xf
	s_nop 1
	v_add_f32_dpp v85, v85, v85 row_bcast:15 row_mask:0xa bank_mask:0xf
	s_nop 1
	v_add_f32_dpp v85, v85, v85 row_bcast:31 row_mask:0xc bank_mask:0xf
	global_store_dwordx2 v1, v[90:91], s[74:75] offset:0
	global_store_dwordx2 v1, v[92:93], s[74:75] offset:512
	global_store_dwordx2 v1, v[94:95], s[74:75] offset:1024
	global_store_dwordx2 v1, v[96:97], s[74:75] offset:1536
	v_readlane_b32 s84, v85, 63
	s_add_u32 s74, s74, 0x400000
	s_addc_u32 s75, s75, 0
	s_nop 0
	v_fma_f32 v85, s84, v2, v3
	v_rsq_f32_e32 v85, v85
	s_nop 0
	v_mul_f32_e32 v68, v68, v85
	v_mul_f32_e32 v69, v69, v85
	v_mul_f32_e32 v70, v70, v85
	v_mul_f32_e32 v71, v71, v85
	v_mul_f32_e32 v72, v72, v85
	v_mul_f32_e32 v73, v73, v85
	v_mul_f32_e32 v74, v74, v85
	v_mul_f32_e32 v75, v75, v85
	v_mul_f32_e32 v76, v76, v85
	v_mul_f32_e32 v77, v77, v85
	v_mul_f32_e32 v78, v78, v85
	v_mul_f32_e32 v79, v79, v85
	v_mul_f32_e32 v80, v80, v85
	v_mul_f32_e32 v81, v81, v85
	v_mul_f32_e32 v82, v82, v85
	v_mul_f32_e32 v83, v83, v85
	v_mul_f32_e32 v68, v68, v100
	v_mul_f32_e32 v69, v69, v101
	v_mul_f32_e32 v70, v70, v102
	v_mul_f32_e32 v71, v71, v103
	v_mul_f32_e32 v72, v72, v104
	v_mul_f32_e32 v73, v73, v105
	v_mul_f32_e32 v74, v74, v106
	v_mul_f32_e32 v75, v75, v107
	v_mul_f32_e32 v76, v76, v108
	v_mul_f32_e32 v77, v77, v109
	v_mul_f32_e32 v78, v78, v110
	v_mul_f32_e32 v79, v79, v111
	v_mul_f32_e32 v80, v80, v112
	v_mul_f32_e32 v81, v81, v113
	v_mul_f32_e32 v82, v82, v114
	v_mul_f32_e32 v83, v83, v115
	v_cvt_pk_bf16_f32 v176, v68, v69
	v_cvt_pk_bf16_f32 v177, v70, v71
	v_cvt_pk_bf16_f32 v178, v72, v73
	v_cvt_pk_bf16_f32 v179, v74, v75
	v_cvt_pk_bf16_f32 v180, v76, v77
	v_cvt_pk_bf16_f32 v181, v78, v79
	v_cvt_pk_bf16_f32 v182, v80, v81
	v_cvt_pk_bf16_f32 v183, v82, v83
	global_store_dwordx2 v1, v[176:177], s[76:77] offset:0
	global_store_dwordx2 v1, v[178:179], s[76:77] offset:512
	global_store_dwordx2 v1, v[180:181], s[76:77] offset:1024
	global_store_dwordx2 v1, v[182:183], s[76:77] offset:1536
	s_add_u32 s76, s76, 0x400000
	s_addc_u32 s77, s77, 0
	s_cmp_eq_u32 s82, 0
	s_cbranch_scc0 .Lrows_p6_r8ok
	s_sub_u32 s70, s70, 0x400000
	s_subb_u32 s71, s71, 0
	s_sub_u32 s72, s72, 0x400000
	s_subb_u32 s73, s73, 0
.Lrows_p6_r8ok:
	global_load_dwordx2 v[20:21], v1, s[70:71] offset:0
	global_load_dwordx2 v[22:23], v1, s[70:71] offset:512
	global_load_dwordx2 v[24:25], v1, s[70:71] offset:1024
	global_load_dwordx2 v[26:27], v1, s[70:71] offset:1536
	global_load_dwordx2 v[28:29], v1, s[72:73] offset:0
	global_load_dwordx2 v[30:31], v1, s[72:73] offset:512
	global_load_dwordx2 v[32:33], v1, s[72:73] offset:1024
	global_load_dwordx2 v[34:35], v1, s[72:73] offset:1536
	s_add_u32 s70, s70, 0x400000
	s_addc_u32 s71, s71, 0
	s_add_u32 s72, s72, 0x400000
	s_addc_u32 s73, s73, 0
	s_waitcnt vmcnt(48)
	v_lshlrev_b32_e32 v68, 16, v36
	v_and_b32_e32 v69, 0xffff0000, v36
	v_lshlrev_b32_e32 v70, 16, v37
	v_and_b32_e32 v71, 0xffff0000, v37
	v_lshlrev_b32_e32 v72, 16, v38
	v_and_b32_e32 v73, 0xffff0000, v38
	v_lshlrev_b32_e32 v74, 16, v39
	v_and_b32_e32 v75, 0xffff0000, v39
	v_lshlrev_b32_e32 v76, 16, v40
	v_and_b32_e32 v77, 0xffff0000, v40
	v_lshlrev_b32_e32 v78, 16, v41
	v_and_b32_e32 v79, 0xffff0000, v41
	v_lshlrev_b32_e32 v80, 16, v42
	v_and_b32_e32 v81, 0xffff0000, v42
	v_lshlrev_b32_e32 v82, 16, v43
	v_and_b32_e32 v83, 0xffff0000, v43
	v_mul_f32_e32 v86, v68, v68
	v_mul_f32_e32 v87, v72, v72
	v_mul_f32_e32 v88, v76, v76
	v_mul_f32_e32 v89, v80, v80
	v_fmac_f32_e32 v86, v69, v69
	v_fmac_f32_e32 v87, v73, v73
	v_fmac_f32_e32 v88, v77, v77
	v_fmac_f32_e32 v89, v81, v81
	v_fmac_f32_e32 v86, v70, v70
	v_fmac_f32_e32 v87, v74, v74
	v_fmac_f32_e32 v88, v78, v78
	v_fmac_f32_e32 v89, v82, v82
	v_fmac_f32_e32 v86, v71, v71
	v_fmac_f32_e32 v87, v75, v75
	v_fmac_f32_e32 v88, v79, v79
	v_fmac_f32_e32 v89, v83, v83
	v_add_f32_e32 v84, v86, v87
	v_add_f32_e32 v84, v84, v88
	v_add_f32_e32 v84, v84, v89
	v_lshlrev_b32_e32 v160, 16, v44
	v_and_b32_e32 v161, 0xffff0000, v44
	v_add_f32_dpp v84, v84, v84 quad_perm:[1,0,3,2] row_mask:0xf bank_mask:0xf
	v_lshlrev_b32_e32 v162, 16, v45
	v_and_b32_e32 v163, 0xffff0000, v45
	v_add_f32_dpp v84, v84, v84 quad_perm:[2,3,0,1] row_mask:0xf bank_mask:0xf
	v_lshlrev_b32_e32 v164, 16, v46
	v_and_b32_e32 v165, 0xffff0000, v46
	v_add_f32_dpp v84, v84, v84 row_half_mirror row_mask:0xf bank_mask:0xf
	v_lshlrev_b32_e32 v166, 16, v47
	v_and_b32_e32 v167, 0xffff0000, v47
	v_add_f32_dpp v84, v84, v84 row_mirror row_mask:0xf bank_mask:0xf
	v_lshlrev_b32_e32 v168, 16, v48
	v_and_b32_e32 v169, 0xffff0000, v48
	v_add_f32_dpp v84, v84, v84 row_bcast:15 row_mask:0xa bank_mask:0xf
	v_lshlrev_b32_e32 v170, 16, v49
	v_and_b32_e32 v171, 0xffff0000, v49
	v_add_f32_dpp v84, v84, v84 row_bcast:31 row_mask:0xc bank_mask:0xf
	v_lshlrev_b32_e32 v172, 16, v50
	v_and_b32_e32 v173, 0xffff0000, v50
	v_lshlrev_b32_e32 v174, 16, v51
	v_and_b32_e32 v175, 0xffff0000, v51
	s_nop 0
	v_readlane_b32 s83, v84, 63
	s_nop 2
	v_fma_f32 v84, s83, v2, v3
	v_rsq_f32_e32 v84, v84
	s_nop 0
	v_mul_f32_e32 v68, v68, v84
	v_mul_f32_e32 v69, v69, v84
	v_mul_f32_e32 v70, v70, v84
	v_mul_f32_e32 v71, v71, v84
	v_mul_f32_e32 v72, v72, v84
	v_mul_f32_e32 v73, v73, v84
	v_mul_f32_e32 v74, v74, v84
	v_mul_f32_e32 v75, v75, v84
	v_mul_f32_e32 v76, v76, v84
	v_mul_f32_e32 v77, v77, v84
	v_mul_f32_e32 v78, v78, v84
	v_mul_f32_e32 v79, v79, v84
	v_mul_f32_e32 v80, v80, v84
	v_mul_f32_e32 v81, v81, v84
	v_mul_f32_e32 v82, v82, v84
	v_mul_f32_e32 v83, v83, v84
	v_fma_f32 v68, v68, v4, v160
	v_fma_f32 v69, v69, v5, v161
	v_fma_f32 v70, v70, v6, v162
	v_fma_f32 v71, v71, v7, v163
	v_fma_f32 v72, v72, v8, v164
	v_fma_f32 v73, v73, v9, v165
	v_fma_f32 v74, v74, v10, v166
	v_fma_f32 v75, v75, v11, v167
	v_fma_f32 v76, v76, v12, v168
	v_fma_f32 v77, v77, v13, v169
	v_fma_f32 v78, v78, v14, v170
	v_fma_f32 v79, v79, v15, v171
	v_fma_f32 v80, v80, v16, v172
	v_fma_f32 v81, v81, v17, v173
	v_fma_f32 v82, v82, v18, v174
	v_fma_f32 v83, v83, v19, v175
	v_mul_f32_e32 v86, v68, v68
	v_mul_f32_e32 v87, v72, v72
	v_mul_f32_e32 v88, v76, v76
	v_mul_f32_e32 v89, v80, v80
	v_fmac_f32_e32 v86, v69, v69
	v_fmac_f32_e32 v87, v73, v73
	v_fmac_f32_e32 v88, v77, v77
	v_fmac_f32_e32 v89, v81, v81
	v_fmac_f32_e32 v86, v70, v70
	v_fmac_f32_e32 v87, v74, v74
	v_fmac_f32_e32 v88, v78, v78
	v_fmac_f32_e32 v89, v82, v82
	v_fmac_f32_e32 v86, v71, v71
	v_fmac_f32_e32 v87, v75, v75
	v_fmac_f32_e32 v88, v79, v79
	v_fmac_f32_e32 v89, v83, v83
	v_add_f32_e32 v85, v86, v87
	v_add_f32_e32 v85, v85, v88
	v_add_f32_e32 v85, v85, v89
	v_cvt_pk_bf16_f32 v90, v68, v69
	v_cvt_pk_bf16_f32 v91, v70, v71
	v_add_f32_dpp v85, v85, v85 quad_perm:[1,0,3,2] row_mask:0xf bank_mask:0xf
	v_cvt_pk_bf16_f32 v92, v72, v73
	v_cvt_pk_bf16_f32 v93, v74, v75
	v_add_f32_dpp v85, v85, v85 quad_perm:[2,3,0,1] row_mask:0xf bank_mask:0xf
	v_cvt_pk_bf16_f32 v94, v76, v77
	v_cvt_pk_bf16_f32 v95, v78, v79
	v_add_f32_dpp v85, v85, v85 row_half_mirror row_mask:0xf bank_mask:0xf
	v_cvt_pk_bf16_f32 v96, v80, v81
	v_cvt_pk_bf16_f32 v97, v82, v83
	v_add_f32_dpp v85, v85, v85 row_mirror row_mask:0xf bank_mask:0xf
	s_nop 1
	v_add_f32_dpp v85, v85, v85 row_bcast:15 row_mask:0xa bank_mask:0xf
	s_nop 1
	v_add_f32_dpp v85, v85, v85 row_bcast:31 row_mask:0xc bank_mask:0xf
	global_store_dwordx2 v1, v[90:91], s[74:75] offset:0
	global_store_dwordx2 v1, v[92:93], s[74:75] offset:512
	global_store_dwordx2 v1, v[94:95], s[74:75] offset:1024
	global_store_dwordx2 v1, v[96:97], s[74:75] offset:1536
	v_readlane_b32 s84, v85, 63
	s_add_u32 s74, s74, 0x400000
	s_addc_u32 s75, s75, 0
	s_nop 0
	v_fma_f32 v85, s84, v2, v3
	v_rsq_f32_e32 v85, v85
	s_nop 0
	v_mul_f32_e32 v68, v68, v85
	v_mul_f32_e32 v69, v69, v85
	v_mul_f32_e32 v70, v70, v85
	v_mul_f32_e32 v71, v71, v85
	v_mul_f32_e32 v72, v72, v85
	v_mul_f32_e32 v73, v73, v85
	v_mul_f32_e32 v74, v74, v85
	v_mul_f32_e32 v75, v75, v85
	v_mul_f32_e32 v76, v76, v85
	v_mul_f32_e32 v77, v77, v85
	v_mul_f32_e32 v78, v78, v85
	v_mul_f32_e32 v79, v79, v85
	v_mul_f32_e32 v80, v80, v85
	v_mul_f32_e32 v81, v81, v85
	v_mul_f32_e32 v82, v82, v85
	v_mul_f32_e32 v83, v83, v85
	v_mul_f32_e32 v68, v68, v100
	v_mul_f32_e32 v69, v69, v101
	v_mul_f32_e32 v70, v70, v102
	v_mul_f32_e32 v71, v71, v103
	v_mul_f32_e32 v72, v72, v104
	v_mul_f32_e32 v73, v73, v105
	v_mul_f32_e32 v74, v74, v106
	v_mul_f32_e32 v75, v75, v107
	v_mul_f32_e32 v76, v76, v108
	v_mul_f32_e32 v77, v77, v109
	v_mul_f32_e32 v78, v78, v110
	v_mul_f32_e32 v79, v79, v111
	v_mul_f32_e32 v80, v80, v112
	v_mul_f32_e32 v81, v81, v113
	v_mul_f32_e32 v82, v82, v114
	v_mul_f32_e32 v83, v83, v115
	v_cvt_pk_bf16_f32 v176, v68, v69
	v_cvt_pk_bf16_f32 v177, v70, v71
	v_cvt_pk_bf16_f32 v178, v72, v73
	v_cvt_pk_bf16_f32 v179, v74, v75
	v_cvt_pk_bf16_f32 v180, v76, v77
	v_cvt_pk_bf16_f32 v181, v78, v79
	v_cvt_pk_bf16_f32 v182, v80, v81
	v_cvt_pk_bf16_f32 v183, v82, v83
	global_store_dwordx2 v1, v[176:177], s[76:77] offset:0
	global_store_dwordx2 v1, v[178:179], s[76:77] offset:512
	global_store_dwordx2 v1, v[180:181], s[76:77] offset:1024
	global_store_dwordx2 v1, v[182:183], s[76:77] offset:1536
	s_add_u32 s76, s76, 0x400000
	s_addc_u32 s77, s77, 0
	s_waitcnt vmcnt(40)
	v_lshlrev_b32_e32 v68, 16, v52
	v_and_b32_e32 v69, 0xffff0000, v52
	v_lshlrev_b32_e32 v70, 16, v53
	v_and_b32_e32 v71, 0xffff0000, v53
	v_lshlrev_b32_e32 v72, 16, v54
	v_and_b32_e32 v73, 0xffff0000, v54
	v_lshlrev_b32_e32 v74, 16, v55
	v_and_b32_e32 v75, 0xffff0000, v55
	v_lshlrev_b32_e32 v76, 16, v56
	v_and_b32_e32 v77, 0xffff0000, v56
	v_lshlrev_b32_e32 v78, 16, v57
	v_and_b32_e32 v79, 0xffff0000, v57
	v_lshlrev_b32_e32 v80, 16, v58
	v_and_b32_e32 v81, 0xffff0000, v58
	v_lshlrev_b32_e32 v82, 16, v59
	v_and_b32_e32 v83, 0xffff0000, v59
	v_mul_f32_e32 v86, v68, v68
	v_mul_f32_e32 v87, v72, v72
	v_mul_f32_e32 v88, v76, v76
	v_mul_f32_e32 v89, v80, v80
	v_fmac_f32_e32 v86, v69, v69
	v_fmac_f32_e32 v87, v73, v73
	v_fmac_f32_e32 v88, v77, v77
	v_fmac_f32_e32 v89, v81, v81
	v_fmac_f32_e32 v86, v70, v70
	v_fmac_f32_e32 v87, v74, v74
	v_fmac_f32_e32 v88, v78, v78
	v_fmac_f32_e32 v89, v82, v82
	v_fmac_f32_e32 v86, v71, v71
	v_fmac_f32_e32 v87, v75, v75
	v_fmac_f32_e32 v88, v79, v79
	v_fmac_f32_e32 v89, v83, v83
	v_add_f32_e32 v84, v86, v87
	v_add_f32_e32 v84, v84, v88
	v_add_f32_e32 v84, v84, v89
	v_lshlrev_b32_e32 v160, 16, v60
	v_and_b32_e32 v161, 0xffff0000, v60
	v_add_f32_dpp v84, v84, v84 quad_perm:[1,0,3,2] row_mask:0xf bank_mask:0xf
	v_lshlrev_b32_e32 v162, 16, v61
	v_and_b32_e32 v163, 0xffff0000, v61
	v_add_f32_dpp v84, v84, v84 quad_perm:[2,3,0,1] row_mask:0xf bank_mask:0xf
	v_lshlrev_b32_e32 v164, 16, v62
	v_and_b32_e32 v165, 0xffff0000, v62
	v_add_f32_dpp v84, v84, v84 row_half_mirror row_mask:0xf bank_mask:0xf
	v_lshlrev_b32_e32 v166, 16, v63
	v_and_b32_e32 v167, 0xffff0000, v63
	v_add_f32_dpp v84, v84, v84 row_mirror row_mask:0xf bank_mask:0xf
	v_lshlrev_b32_e32 v168, 16, v64
	v_and_b32_e32 v169, 0xffff0000, v64
	v_add_f32_dpp v84, v84, v84 row_bcast:15 row_mask:0xa bank_mask:0xf
	v_lshlrev_b32_e32 v170, 16, v65
	v_and_b32_e32 v171, 0xffff0000, v65
	v_add_f32_dpp v84, v84, v84 row_bcast:31 row_mask:0xc bank_mask:0xf
	v_lshlrev_b32_e32 v172, 16, v66
	v_and_b32_e32 v173, 0xffff0000, v66
	v_lshlrev_b32_e32 v174, 16, v67
	v_and_b32_e32 v175, 0xffff0000, v67
	s_nop 0
	v_readlane_b32 s83, v84, 63
	s_nop 2
	v_fma_f32 v84, s83, v2, v3
	v_rsq_f32_e32 v84, v84
	s_nop 0
	v_mul_f32_e32 v68, v68, v84
	v_mul_f32_e32 v69, v69, v84
	v_mul_f32_e32 v70, v70, v84
	v_mul_f32_e32 v71, v71, v84
	v_mul_f32_e32 v72, v72, v84
	v_mul_f32_e32 v73, v73, v84
	v_mul_f32_e32 v74, v74, v84
	v_mul_f32_e32 v75, v75, v84
	v_mul_f32_e32 v76, v76, v84
	v_mul_f32_e32 v77, v77, v84
	v_mul_f32_e32 v78, v78, v84
	v_mul_f32_e32 v79, v79, v84
	v_mul_f32_e32 v80, v80, v84
	v_mul_f32_e32 v81, v81, v84
	v_mul_f32_e32 v82, v82, v84
	v_mul_f32_e32 v83, v83, v84
	v_fma_f32 v68, v68, v4, v160
	v_fma_f32 v69, v69, v5, v161
	v_fma_f32 v70, v70, v6, v162
	v_fma_f32 v71, v71, v7, v163
	v_fma_f32 v72, v72, v8, v164
	v_fma_f32 v73, v73, v9, v165
	v_fma_f32 v74, v74, v10, v166
	v_fma_f32 v75, v75, v11, v167
	v_fma_f32 v76, v76, v12, v168
	v_fma_f32 v77, v77, v13, v169
	v_fma_f32 v78, v78, v14, v170
	v_fma_f32 v79, v79, v15, v171
	v_fma_f32 v80, v80, v16, v172
	v_fma_f32 v81, v81, v17, v173
	v_fma_f32 v82, v82, v18, v174
	v_fma_f32 v83, v83, v19, v175
	v_mul_f32_e32 v86, v68, v68
	v_mul_f32_e32 v87, v72, v72
	v_mul_f32_e32 v88, v76, v76
	v_mul_f32_e32 v89, v80, v80
	v_fmac_f32_e32 v86, v69, v69
	v_fmac_f32_e32 v87, v73, v73
	v_fmac_f32_e32 v88, v77, v77
	v_fmac_f32_e32 v89, v81, v81
	v_fmac_f32_e32 v86, v70, v70
	v_fmac_f32_e32 v87, v74, v74
	v_fmac_f32_e32 v88, v78, v78
	v_fmac_f32_e32 v89, v82, v82
	v_fmac_f32_e32 v86, v71, v71
	v_fmac_f32_e32 v87, v75, v75
	v_fmac_f32_e32 v88, v79, v79
	v_fmac_f32_e32 v89, v83, v83
	v_add_f32_e32 v85, v86, v87
	v_add_f32_e32 v85, v85, v88
	v_add_f32_e32 v85, v85, v89
	v_cvt_pk_bf16_f32 v90, v68, v69
	v_cvt_pk_bf16_f32 v91, v70, v71
	v_add_f32_dpp v85, v85, v85 quad_perm:[1,0,3,2] row_mask:0xf bank_mask:0xf
	v_cvt_pk_bf16_f32 v92, v72, v73
	v_cvt_pk_bf16_f32 v93, v74, v75
	v_add_f32_dpp v85, v85, v85 quad_perm:[2,3,0,1] row_mask:0xf bank_mask:0xf
	v_cvt_pk_bf16_f32 v94, v76, v77
	v_cvt_pk_bf16_f32 v95, v78, v79
	v_add_f32_dpp v85, v85, v85 row_half_mirror row_mask:0xf bank_mask:0xf
	v_cvt_pk_bf16_f32 v96, v80, v81
	v_cvt_pk_bf16_f32 v97, v82, v83
	v_add_f32_dpp v85, v85, v85 row_mirror row_mask:0xf bank_mask:0xf
	s_nop 1
	v_add_f32_dpp v85, v85, v85 row_bcast:15 row_mask:0xa bank_mask:0xf
	s_nop 1
	v_add_f32_dpp v85, v85, v85 row_bcast:31 row_mask:0xc bank_mask:0xf
	global_store_dwordx2 v1, v[90:91], s[74:75] offset:0
	global_store_dwordx2 v1, v[92:93], s[74:75] offset:512
	global_store_dwordx2 v1, v[94:95], s[74:75] offset:1024
	global_store_dwordx2 v1, v[96:97], s[74:75] offset:1536
	v_readlane_b32 s84, v85, 63
	s_add_u32 s74, s74, 0x400000
	s_addc_u32 s75, s75, 0
	s_nop 0
	v_fma_f32 v85, s84, v2, v3
	v_rsq_f32_e32 v85, v85
	s_nop 0
	v_mul_f32_e32 v68, v68, v85
	v_mul_f32_e32 v69, v69, v85
	v_mul_f32_e32 v70, v70, v85
	v_mul_f32_e32 v71, v71, v85
	v_mul_f32_e32 v72, v72, v85
	v_mul_f32_e32 v73, v73, v85
	v_mul_f32_e32 v74, v74, v85
	v_mul_f32_e32 v75, v75, v85
	v_mul_f32_e32 v76, v76, v85
	v_mul_f32_e32 v77, v77, v85
	v_mul_f32_e32 v78, v78, v85
	v_mul_f32_e32 v79, v79, v85
	v_mul_f32_e32 v80, v80, v85
	v_mul_f32_e32 v81, v81, v85
	v_mul_f32_e32 v82, v82, v85
	v_mul_f32_e32 v83, v83, v85
	v_mul_f32_e32 v68, v68, v100
	v_mul_f32_e32 v69, v69, v101
	v_mul_f32_e32 v70, v70, v102
	v_mul_f32_e32 v71, v71, v103
	v_mul_f32_e32 v72, v72, v104
	v_mul_f32_e32 v73, v73, v105
	v_mul_f32_e32 v74, v74, v106
	v_mul_f32_e32 v75, v75, v107
	v_mul_f32_e32 v76, v76, v108
	v_mul_f32_e32 v77, v77, v109
	v_mul_f32_e32 v78, v78, v110
	v_mul_f32_e32 v79, v79, v111
	v_mul_f32_e32 v80, v80, v112
	v_mul_f32_e32 v81, v81, v113
	v_mul_f32_e32 v82, v82, v114
	v_mul_f32_e32 v83, v83, v115
	v_cvt_pk_bf16_f32 v176, v68, v69
	v_cvt_pk_bf16_f32 v177, v70, v71
	v_cvt_pk_bf16_f32 v178, v72, v73
	v_cvt_pk_bf16_f32 v179, v74, v75
	v_cvt_pk_bf16_f32 v180, v76, v77
	v_cvt_pk_bf16_f32 v181, v78, v79
	v_cvt_pk_bf16_f32 v182, v80, v81
	v_cvt_pk_bf16_f32 v183, v82, v83
	global_store_dwordx2 v1, v[176:177], s[76:77] offset:0
	global_store_dwordx2 v1, v[178:179], s[76:77] offset:512
	global_store_dwordx2 v1, v[180:181], s[76:77] offset:1024
	global_store_dwordx2 v1, v[182:183], s[76:77] offset:1536
	s_add_u32 s76, s76, 0x400000
	s_addc_u32 s77, s77, 0
	s_waitcnt vmcnt(32)
	v_lshlrev_b32_e32 v68, 16, v184
	v_and_b32_e32 v69, 0xffff0000, v184
	v_lshlrev_b32_e32 v70, 16, v185
	v_and_b32_e32 v71, 0xffff0000, v185
	v_lshlrev_b32_e32 v72, 16, v186
	v_and_b32_e32 v73, 0xffff0000, v186
	v_lshlrev_b32_e32 v74, 16, v187
	v_and_b32_e32 v75, 0xffff0000, v187
	v_lshlrev_b32_e32 v76, 16, v188
	v_and_b32_e32 v77, 0xffff0000, v188
	v_lshlrev_b32_e32 v78, 16, v189
	v_and_b32_e32 v79, 0xffff0000, v189
	v_lshlrev_b32_e32 v80, 16, v190
	v_and_b32_e32 v81, 0xffff0000, v190
	v_lshlrev_b32_e32 v82, 16, v191
	v_and_b32_e32 v83, 0xffff0000, v191
	v_mul_f32_e32 v86, v68, v68
	v_mul_f32_e32 v87, v72, v72
	v_mul_f32_e32 v88, v76, v76
	v_mul_f32_e32 v89, v80, v80
	v_fmac_f32_e32 v86, v69, v69
	v_fmac_f32_e32 v87, v73, v73
	v_fmac_f32_e32 v88, v77, v77
	v_fmac_f32_e32 v89, v81, v81
	v_fmac_f32_e32 v86, v70, v70
	v_fmac_f32_e32 v87, v74, v74
	v_fmac_f32_e32 v88, v78, v78
	v_fmac_f32_e32 v89, v82, v82
	v_fmac_f32_e32 v86, v71, v71
	v_fmac_f32_e32 v87, v75, v75
	v_fmac_f32_e32 v88, v79, v79
	v_fmac_f32_e32 v89, v83, v83
	v_add_f32_e32 v84, v86, v87
	v_add_f32_e32 v84, v84, v88
	v_add_f32_e32 v84, v84, v89
	v_lshlrev_b32_e32 v160, 16, v192
	v_and_b32_e32 v161, 0xffff0000, v192
	v_add_f32_dpp v84, v84, v84 quad_perm:[1,0,3,2] row_mask:0xf bank_mask:0xf
	v_lshlrev_b32_e32 v162, 16, v193
	v_and_b32_e32 v163, 0xffff0000, v193
	v_add_f32_dpp v84, v84, v84 quad_perm:[2,3,0,1] row_mask:0xf bank_mask:0xf
	v_lshlrev_b32_e32 v164, 16, v194
	v_and_b32_e32 v165, 0xffff0000, v194
	v_add_f32_dpp v84, v84, v84 row_half_mirror row_mask:0xf bank_mask:0xf
	v_lshlrev_b32_e32 v166, 16, v195
	v_and_b32_e32 v167, 0xffff0000, v195
	v_add_f32_dpp v84, v84, v84 row_mirror row_mask:0xf bank_mask:0xf
	v_lshlrev_b32_e32 v168, 16, v196
	v_and_b32_e32 v169, 0xffff0000, v196
	v_add_f32_dpp v84, v84, v84 row_bcast:15 row_mask:0xa bank_mask:0xf
	v_lshlrev_b32_e32 v170, 16, v197
	v_and_b32_e32 v171, 0xffff0000, v197
	v_add_f32_dpp v84, v84, v84 row_bcast:31 row_mask:0xc bank_mask:0xf
	v_lshlrev_b32_e32 v172, 16, v198
	v_and_b32_e32 v173, 0xffff0000, v198
	v_lshlrev_b32_e32 v174, 16, v199
	v_and_b32_e32 v175, 0xffff0000, v199
	s_nop 0
	v_readlane_b32 s83, v84, 63
	s_nop 2
	v_fma_f32 v84, s83, v2, v3
	v_rsq_f32_e32 v84, v84
	s_nop 0
	v_mul_f32_e32 v68, v68, v84
	v_mul_f32_e32 v69, v69, v84
	v_mul_f32_e32 v70, v70, v84
	v_mul_f32_e32 v71, v71, v84
	v_mul_f32_e32 v72, v72, v84
	v_mul_f32_e32 v73, v73, v84
	v_mul_f32_e32 v74, v74, v84
	v_mul_f32_e32 v75, v75, v84
	v_mul_f32_e32 v76, v76, v84
	v_mul_f32_e32 v77, v77, v84
	v_mul_f32_e32 v78, v78, v84
	v_mul_f32_e32 v79, v79, v84
	v_mul_f32_e32 v80, v80, v84
	v_mul_f32_e32 v81, v81, v84
	v_mul_f32_e32 v82, v82, v84
	v_mul_f32_e32 v83, v83, v84
	v_fma_f32 v68, v68, v4, v160
	v_fma_f32 v69, v69, v5, v161
	v_fma_f32 v70, v70, v6, v162
	v_fma_f32 v71, v71, v7, v163
	v_fma_f32 v72, v72, v8, v164
	v_fma_f32 v73, v73, v9, v165
	v_fma_f32 v74, v74, v10, v166
	v_fma_f32 v75, v75, v11, v167
	v_fma_f32 v76, v76, v12, v168
	v_fma_f32 v77, v77, v13, v169
	v_fma_f32 v78, v78, v14, v170
	v_fma_f32 v79, v79, v15, v171
	v_fma_f32 v80, v80, v16, v172
	v_fma_f32 v81, v81, v17, v173
	v_fma_f32 v82, v82, v18, v174
	v_fma_f32 v83, v83, v19, v175
	v_mul_f32_e32 v86, v68, v68
	v_mul_f32_e32 v87, v72, v72
	v_mul_f32_e32 v88, v76, v76
	v_mul_f32_e32 v89, v80, v80
	v_fmac_f32_e32 v86, v69, v69
	v_fmac_f32_e32 v87, v73, v73
	v_fmac_f32_e32 v88, v77, v77
	v_fmac_f32_e32 v89, v81, v81
	v_fmac_f32_e32 v86, v70, v70
	v_fmac_f32_e32 v87, v74, v74
	v_fmac_f32_e32 v88, v78, v78
	v_fmac_f32_e32 v89, v82, v82
	v_fmac_f32_e32 v86, v71, v71
	v_fmac_f32_e32 v87, v75, v75
	v_fmac_f32_e32 v88, v79, v79
	v_fmac_f32_e32 v89, v83, v83
	v_add_f32_e32 v85, v86, v87
	v_add_f32_e32 v85, v85, v88
	v_add_f32_e32 v85, v85, v89
	v_cvt_pk_bf16_f32 v90, v68, v69
	v_cvt_pk_bf16_f32 v91, v70, v71
	v_add_f32_dpp v85, v85, v85 quad_perm:[1,0,3,2] row_mask:0xf bank_mask:0xf
	v_cvt_pk_bf16_f32 v92, v72, v73
	v_cvt_pk_bf16_f32 v93, v74, v75
	v_add_f32_dpp v85, v85, v85 quad_perm:[2,3,0,1] row_mask:0xf bank_mask:0xf
	v_cvt_pk_bf16_f32 v94, v76, v77
	v_cvt_pk_bf16_f32 v95, v78, v79
	v_add_f32_dpp v85, v85, v85 row_half_mirror row_mask:0xf bank_mask:0xf
	v_cvt_pk_bf16_f32 v96, v80, v81
	v_cvt_pk_bf16_f32 v97, v82, v83
	v_add_f32_dpp v85, v85, v85 row_mirror row_mask:0xf bank_mask:0xf
	s_nop 1
	v_add_f32_dpp v85, v85, v85 row_bcast:15 row_mask:0xa bank_mask:0xf
	s_nop 1
	v_add_f32_dpp v85, v85, v85 row_bcast:31 row_mask:0xc bank_mask:0xf
	global_store_dwordx2 v1, v[90:91], s[74:75] offset:0
	global_store_dwordx2 v1, v[92:93], s[74:75] offset:512
	global_store_dwordx2 v1, v[94:95], s[74:75] offset:1024
	global_store_dwordx2 v1, v[96:97], s[74:75] offset:1536
	v_readlane_b32 s84, v85, 63
	s_add_u32 s74, s74, 0x400000
	s_addc_u32 s75, s75, 0
	s_nop 0
	v_fma_f32 v85, s84, v2, v3
	v_rsq_f32_e32 v85, v85
	s_nop 0
	v_mul_f32_e32 v68, v68, v85
	v_mul_f32_e32 v69, v69, v85
	v_mul_f32_e32 v70, v70, v85
	v_mul_f32_e32 v71, v71, v85
	v_mul_f32_e32 v72, v72, v85
	v_mul_f32_e32 v73, v73, v85
	v_mul_f32_e32 v74, v74, v85
	v_mul_f32_e32 v75, v75, v85
	v_mul_f32_e32 v76, v76, v85
	v_mul_f32_e32 v77, v77, v85
	v_mul_f32_e32 v78, v78, v85
	v_mul_f32_e32 v79, v79, v85
	v_mul_f32_e32 v80, v80, v85
	v_mul_f32_e32 v81, v81, v85
	v_mul_f32_e32 v82, v82, v85
	v_mul_f32_e32 v83, v83, v85
	v_mul_f32_e32 v68, v68, v100
	v_mul_f32_e32 v69, v69, v101
	v_mul_f32_e32 v70, v70, v102
	v_mul_f32_e32 v71, v71, v103
	v_mul_f32_e32 v72, v72, v104
	v_mul_f32_e32 v73, v73, v105
	v_mul_f32_e32 v74, v74, v106
	v_mul_f32_e32 v75, v75, v107
	v_mul_f32_e32 v76, v76, v108
	v_mul_f32_e32 v77, v77, v109
	v_mul_f32_e32 v78, v78, v110
	v_mul_f32_e32 v79, v79, v111
	v_mul_f32_e32 v80, v80, v112
	v_mul_f32_e32 v81, v81, v113
	v_mul_f32_e32 v82, v82, v114
	v_mul_f32_e32 v83, v83, v115
	v_cvt_pk_bf16_f32 v176, v68, v69
	v_cvt_pk_bf16_f32 v177, v70, v71
	v_cvt_pk_bf16_f32 v178, v72, v73
	v_cvt_pk_bf16_f32 v179, v74, v75
	v_cvt_pk_bf16_f32 v180, v76, v77
	v_cvt_pk_bf16_f32 v181, v78, v79
	v_cvt_pk_bf16_f32 v182, v80, v81
	v_cvt_pk_bf16_f32 v183, v82, v83
	global_store_dwordx2 v1, v[176:177], s[76:77] offset:0
	global_store_dwordx2 v1, v[178:179], s[76:77] offset:512
	global_store_dwordx2 v1, v[180:181], s[76:77] offset:1024
	global_store_dwordx2 v1, v[182:183], s[76:77] offset:1536
	s_add_u32 s76, s76, 0x400000
	s_addc_u32 s77, s77, 0
	s_cmp_eq_u32 s82, 0
	s_cbranch_scc1 .Lrows_p6_done
	s_waitcnt vmcnt(24)
	v_lshlrev_b32_e32 v68, 16, v20
	v_and_b32_e32 v69, 0xffff0000, v20
	v_lshlrev_b32_e32 v70, 16, v21
	v_and_b32_e32 v71, 0xffff0000, v21
	v_lshlrev_b32_e32 v72, 16, v22
	v_and_b32_e32 v73, 0xffff0000, v22
	v_lshlrev_b32_e32 v74, 16, v23
	v_and_b32_e32 v75, 0xffff0000, v23
	v_lshlrev_b32_e32 v76, 16, v24
	v_and_b32_e32 v77, 0xffff0000, v24
	v_lshlrev_b32_e32 v78, 16, v25
	v_and_b32_e32 v79, 0xffff0000, v25
	v_lshlrev_b32_e32 v80, 16, v26
	v_and_b32_e32 v81, 0xffff0000, v26
	v_lshlrev_b32_e32 v82, 16, v27
	v_and_b32_e32 v83, 0xffff0000, v27
	v_mul_f32_e32 v86, v68, v68
	v_mul_f32_e32 v87, v72, v72
	v_mul_f32_e32 v88, v76, v76
	v_mul_f32_e32 v89, v80, v80
	v_fmac_f32_e32 v86, v69, v69
	v_fmac_f32_e32 v87, v73, v73
	v_fmac_f32_e32 v88, v77, v77
	v_fmac_f32_e32 v89, v81, v81
	v_fmac_f32_e32 v86, v70, v70
	v_fmac_f32_e32 v87, v74, v74
	v_fmac_f32_e32 v88, v78, v78
	v_fmac_f32_e32 v89, v82, v82
	v_fmac_f32_e32 v86, v71, v71
	v_fmac_f32_e32 v87, v75, v75
	v_fmac_f32_e32 v88, v79, v79
	v_fmac_f32_e32 v89, v83, v83
	v_add_f32_e32 v84, v86, v87
	v_add_f32_e32 v84, v84, v88
	v_add_f32_e32 v84, v84, v89
	v_lshlrev_b32_e32 v160, 16, v28
	v_and_b32_e32 v161, 0xffff0000, v28
	v_add_f32_dpp v84, v84, v84 quad_perm:[1,0,3,2] row_mask:0xf bank_mask:0xf
	v_lshlrev_b32_e32 v162, 16, v29
	v_and_b32_e32 v163, 0xffff0000, v29
	v_add_f32_dpp v84, v84, v84 quad_perm:[2,3,0,1] row_mask:0xf bank_mask:0xf
	v_lshlrev_b32_e32 v164, 16, v30
	v_and_b32_e32 v165, 0xffff0000, v30
	v_add_f32_dpp v84, v84, v84 row_half_mirror row_mask:0xf bank_mask:0xf
	v_lshlrev_b32_e32 v166, 16, v31
	v_and_b32_e32 v167, 0xffff0000, v31
	v_add_f32_dpp v84, v84, v84 row_mirror row_mask:0xf bank_mask:0xf
	v_lshlrev_b32_e32 v168, 16, v32
	v_and_b32_e32 v169, 0xffff0000, v32
	v_add_f32_dpp v84, v84, v84 row_bcast:15 row_mask:0xa bank_mask:0xf
	v_lshlrev_b32_e32 v170, 16, v33
	v_and_b32_e32 v171, 0xffff0000, v33
	v_add_f32_dpp v84, v84, v84 row_bcast:31 row_mask:0xc bank_mask:0xf
	v_lshlrev_b32_e32 v172, 16, v34
	v_and_b32_e32 v173, 0xffff0000, v34
	v_lshlrev_b32_e32 v174, 16, v35
	v_and_b32_e32 v175, 0xffff0000, v35
	s_nop 0
	v_readlane_b32 s83, v84, 63
	s_nop 2
	v_fma_f32 v84, s83, v2, v3
	v_rsq_f32_e32 v84, v84
	s_nop 0
	v_mul_f32_e32 v68, v68, v84
	v_mul_f32_e32 v69, v69, v84
	v_mul_f32_e32 v70, v70, v84
	v_mul_f32_e32 v71, v71, v84
	v_mul_f32_e32 v72, v72, v84
	v_mul_f32_e32 v73, v73, v84
	v_mul_f32_e32 v74, v74, v84
	v_mul_f32_e32 v75, v75, v84
	v_mul_f32_e32 v76, v76, v84
	v_mul_f32_e32 v77, v77, v84
	v_mul_f32_e32 v78, v78, v84
	v_mul_f32_e32 v79, v79, v84
	v_mul_f32_e32 v80, v80, v84
	v_mul_f32_e32 v81, v81, v84
	v_mul_f32_e32 v82, v82, v84
	v_mul_f32_e32 v83, v83, v84
	v_fma_f32 v68, v68, v4, v160
	v_fma_f32 v69, v69, v5, v161
	v_fma_f32 v70, v70, v6, v162
	v_fma_f32 v71, v71, v7, v163
	v_fma_f32 v72, v72, v8, v164
	v_fma_f32 v73, v73, v9, v165
	v_fma_f32 v74, v74, v10, v166
	v_fma_f32 v75, v75, v11, v167
	v_fma_f32 v76, v76, v12, v168
	v_fma_f32 v77, v77, v13, v169
	v_fma_f32 v78, v78, v14, v170
	v_fma_f32 v79, v79, v15, v171
	v_fma_f32 v80, v80, v16, v172
	v_fma_f32 v81, v81, v17, v173
	v_fma_f32 v82, v82, v18, v174
	v_fma_f32 v83, v83, v19, v175
	v_mul_f32_e32 v86, v68, v68
	v_mul_f32_e32 v87, v72, v72
	v_mul_f32_e32 v88, v76, v76
	v_mul_f32_e32 v89, v80, v80
	v_fmac_f32_e32 v86, v69, v69
	v_fmac_f32_e32 v87, v73, v73
	v_fmac_f32_e32 v88, v77, v77
	v_fmac_f32_e32 v89, v81, v81
	v_fmac_f32_e32 v86, v70, v70
	v_fmac_f32_e32 v87, v74, v74
	v_fmac_f32_e32 v88, v78, v78
	v_fmac_f32_e32 v89, v82, v82
	v_fmac_f32_e32 v86, v71, v71
	v_fmac_f32_e32 v87, v75, v75
	v_fmac_f32_e32 v88, v79, v79
	v_fmac_f32_e32 v89, v83, v83
	v_add_f32_e32 v85, v86, v87
	v_add_f32_e32 v85, v85, v88
	v_add_f32_e32 v85, v85, v89
	v_cvt_pk_bf16_f32 v90, v68, v69
	v_cvt_pk_bf16_f32 v91, v70, v71
	v_add_f32_dpp v85, v85, v85 quad_perm:[1,0,3,2] row_mask:0xf bank_mask:0xf
	v_cvt_pk_bf16_f32 v92, v72, v73
	v_cvt_pk_bf16_f32 v93, v74, v75
	v_add_f32_dpp v85, v85, v85 quad_perm:[2,3,0,1] row_mask:0xf bank_mask:0xf
	v_cvt_pk_bf16_f32 v94, v76, v77
	v_cvt_pk_bf16_f32 v95, v78, v79
	v_add_f32_dpp v85, v85, v85 row_half_mirror row_mask:0xf bank_mask:0xf
	v_cvt_pk_bf16_f32 v96, v80, v81
	v_cvt_pk_bf16_f32 v97, v82, v83
	v_add_f32_dpp v85, v85, v85 row_mirror row_mask:0xf bank_mask:0xf
	s_nop 1
	v_add_f32_dpp v85, v85, v85 row_bcast:15 row_mask:0xa bank_mask:0xf
	s_nop 1
	v_add_f32_dpp v85, v85, v85 row_bcast:31 row_mask:0xc bank_mask:0xf
	global_store_dwordx2 v1, v[90:91], s[74:75] offset:0
	global_store_dwordx2 v1, v[92:93], s[74:75] offset:512
	global_store_dwordx2 v1, v[94:95], s[74:75] offset:1024
	global_store_dwordx2 v1, v[96:97], s[74:75] offset:1536
	v_readlane_b32 s84, v85, 63
	s_add_u32 s74, s74, 0x400000
	s_addc_u32 s75, s75, 0
	s_nop 0
	v_fma_f32 v85, s84, v2, v3
	v_rsq_f32_e32 v85, v85
	s_nop 0
	v_mul_f32_e32 v68, v68, v85
	v_mul_f32_e32 v69, v69, v85
	v_mul_f32_e32 v70, v70, v85
	v_mul_f32_e32 v71, v71, v85
	v_mul_f32_e32 v72, v72, v85
	v_mul_f32_e32 v73, v73, v85
	v_mul_f32_e32 v74, v74, v85
	v_mul_f32_e32 v75, v75, v85
	v_mul_f32_e32 v76, v76, v85
	v_mul_f32_e32 v77, v77, v85
	v_mul_f32_e32 v78, v78, v85
	v_mul_f32_e32 v79, v79, v85
	v_mul_f32_e32 v80, v80, v85
	v_mul_f32_e32 v81, v81, v85
	v_mul_f32_e32 v82, v82, v85
	v_mul_f32_e32 v83, v83, v85
	v_mul_f32_e32 v68, v68, v100
	v_mul_f32_e32 v69, v69, v101
	v_mul_f32_e32 v70, v70, v102
	v_mul_f32_e32 v71, v71, v103
	v_mul_f32_e32 v72, v72, v104
	v_mul_f32_e32 v73, v73, v105
	v_mul_f32_e32 v74, v74, v106
	v_mul_f32_e32 v75, v75, v107
	v_mul_f32_e32 v76, v76, v108
	v_mul_f32_e32 v77, v77, v109
	v_mul_f32_e32 v78, v78, v110
	v_mul_f32_e32 v79, v79, v111
	v_mul_f32_e32 v80, v80, v112
	v_mul_f32_e32 v81, v81, v113
	v_mul_f32_e32 v82, v82, v114
	v_mul_f32_e32 v83, v83, v115
	v_cvt_pk_bf16_f32 v176, v68, v69
	v_cvt_pk_bf16_f32 v177, v70, v71
	v_cvt_pk_bf16_f32 v178, v72, v73
	v_cvt_pk_bf16_f32 v179, v74, v75
	v_cvt_pk_bf16_f32 v180, v76, v77
	v_cvt_pk_bf16_f32 v181, v78, v79
	v_cvt_pk_bf16_f32 v182, v80, v81
	v_cvt_pk_bf16_f32 v183, v82, v83
	global_store_dwordx2 v1, v[176:177], s[76:77] offset:0
	global_store_dwordx2 v1, v[178:179], s[76:77] offset:512
	global_store_dwordx2 v1, v[180:181], s[76:77] offset:1024
	global_store_dwordx2 v1, v[182:183], s[76:77] offset:1536
	s_add_u32 s76, s76, 0x400000
	s_addc_u32 s77, s77, 0

.LBB0_842:
	s_cmp_lt_i32 s24, 10
	s_cselect_b64 s[4:5], -1, 0
	s_cmp_gt_i32 s25, 9
	s_cselect_b64 s[6:7], -1, 0
	s_and_b64 s[4:5], s[4:5], s[6:7]
	s_andn2_b64 vcc, exec, s[4:5]
	s_cbranch_vccnz .LBB0_904
	s_mov_b64 exec, -1
	s_load_dword s3, s[0:1], 0x148
	s_add_u32 s6, s0, 0x148
	s_addc_u32 s7, s1, 0
	s_load_dwordx2 s[78:79], s[0:1], 0x40
	s_load_dwordx2 s[80:81], s[0:1], 0x28
	v_lshrrev_b32_e32 v0, 6, v129
	v_and_b32_e32 v1, 63, v129
	v_readfirstlane_b32 s68, v0
	v_lshlrev_b32_e32 v0, 4, v1
	v_lshlrev_b32_e32 v1, 3, v1
	v_mov_b32_e32 v2, 0x3a800000
	v_mov_b32_e32 v3, 0x358637bd
	s_lshl_b32 s69, s2, 3
	s_add_u32 s68, s68, s69
	s_waitcnt lgkmcnt(0)
	s_add_u32 s80, s80, 0x1000
	s_addc_u32 s81, s81, 0
	global_load_dwordx4 v[4:7], v0, s[78:79] offset:0
	global_load_dwordx4 v[8:11], v0, s[78:79] offset:1024
	global_load_dwordx4 v[12:15], v0, s[78:79] offset:2048
	global_load_dwordx4 v[16:19], v0, s[78:79] offset:3072
	global_load_dwordx4 v[100:103], v0, s[80:81] offset:0
	global_load_dwordx4 v[104:107], v0, s[80:81] offset:1024
	global_load_dwordx4 v[108:111], v0, s[80:81] offset:2048
	global_load_dwordx4 v[112:115], v0, s[80:81] offset:3072
	s_lshl_b32 s86, s68, 11
	s_add_u32 s70, s44, s86
	s_addc_u32 s71, s45, 0
	s_add_u32 s72, s50, s86
	s_addc_u32 s73, s51, 0
	s_mov_b64 s[74:75], s[72:73]
	s_add_u32 s76, s44, s86
	s_addc_u32 s77, s45, 0
	s_cmpk_lt_u32 s68, 0x200
	s_cselect_b32 s82, 1, 0
	global_load_dwordx2 v[20:21], v1, s[70:71] offset:0
	global_load_dwordx2 v[22:23], v1, s[70:71] offset:512
	global_load_dwordx2 v[24:25], v1, s[70:71] offset:1024
	global_load_dwordx2 v[26:27], v1, s[70:71] offset:1536
	global_load_dwordx2 v[28:29], v1, s[72:73] offset:0
	global_load_dwordx2 v[30:31], v1, s[72:73] offset:512
	global_load_dwordx2 v[32:33], v1, s[72:73] offset:1024
	global_load_dwordx2 v[34:35], v1, s[72:73] offset:1536
	s_add_u32 s70, s70, 0x400000
	s_addc_u32 s71, s71, 0
	s_add_u32 s72, s72, 0x400000
	s_addc_u32 s73, s73, 0
	global_load_dwordx2 v[36:37], v1, s[70:71] offset:0
	global_load_dwordx2 v[38:39], v1, s[70:71] offset:512
	global_load_dwordx2 v[40:41], v1, s[70:71] offset:1024
	global_load_dwordx2 v[42:43], v1, s[70:71] offset:1536
	global_load_dwordx2 v[44:45], v1, s[72:73] offset:0
	global_load_dwordx2 v[46:47], v1, s[72:73] offset:512
	global_load_dwordx2 v[48:49], v1, s[72:73] offset:1024
	global_load_dwordx2 v[50:51], v1, s[72:73] offset:1536
	s_add_u32 s70, s70, 0x400000
	s_addc_u32 s71, s71, 0
	s_add_u32 s72, s72, 0x400000
	s_addc_u32 s73, s73, 0
	global_load_dwordx2 v[52:53], v1, s[70:71] offset:0
	global_load_dwordx2 v[54:55], v1, s[70:71] offset:512
	global_load_dwordx2 v[56:57], v1, s[70:71] offset:1024
	global_load_dwordx2 v[58:59], v1, s[70:71] offset:1536
	global_load_dwordx2 v[60:61], v1, s[72:73] offset:0
	global_load_dwordx2 v[62:63], v1, s[72:73] offset:512
	global_load_dwordx2 v[64:65], v1, s[72:73] offset:1024
	global_load_dwordx2 v[66:67], v1, s[72:73] offset:1536
	s_add_u32 s70, s70, 0x400000
	s_addc_u32 s71, s71, 0
	s_add_u32 s72, s72, 0x400000
	s_addc_u32 s73, s73, 0
	global_load_dwordx2 v[184:185], v1, s[70:71] offset:0
	global_load_dwordx2 v[186:187], v1, s[70:71] offset:512
	global_load_dwordx2 v[188:189], v1, s[70:71] offset:1024
	global_load_dwordx2 v[190:191], v1, s[70:71] offset:1536
	global_load_dwordx2 v[192:193], v1, s[72:73] offset:0
	global_load_dwordx2 v[194:195], v1, s[72:73] offset:512
	global_load_dwordx2 v[196:197], v1, s[72:73] offset:1024
	global_load_dwordx2 v[198:199], v1, s[72:73] offset:1536
	s_add_u32 s70, s70, 0x400000
	s_addc_u32 s71, s71, 0
	s_add_u32 s72, s72, 0x400000
	s_addc_u32 s73, s73, 0
	s_waitcnt vmcnt(24)
	v_lshlrev_b32_e32 v68, 16, v20
	v_and_b32_e32 v69, 0xffff0000, v20
	v_lshlrev_b32_e32 v70, 16, v21
	v_and_b32_e32 v71, 0xffff0000, v21
	v_lshlrev_b32_e32 v72, 16, v22
	v_and_b32_e32 v73, 0xffff0000, v22
	v_lshlrev_b32_e32 v74, 16, v23
	v_and_b32_e32 v75, 0xffff0000, v23
	v_lshlrev_b32_e32 v76, 16, v24
	v_and_b32_e32 v77, 0xffff0000, v24
	v_lshlrev_b32_e32 v78, 16, v25
	v_and_b32_e32 v79, 0xffff0000, v25
	v_lshlrev_b32_e32 v80, 16, v26
	v_and_b32_e32 v81, 0xffff0000, v26
	v_lshlrev_b32_e32 v82, 16, v27
	v_and_b32_e32 v83, 0xffff0000, v27
	v_mul_f32_e32 v86, v68, v68
	v_mul_f32_e32 v87, v72, v72
	v_mul_f32_e32 v88, v76, v76
	v_mul_f32_e32 v89, v80, v80
	v_fmac_f32_e32 v86, v69, v69
	v_fmac_f32_e32 v87, v73, v73
	v_fmac_f32_e32 v88, v77, v77
	v_fmac_f32_e32 v89, v81, v81
	v_fmac_f32_e32 v86, v70, v70
	v_fmac_f32_e32 v87, v74, v74
	v_fmac_f32_e32 v88, v78, v78
	v_fmac_f32_e32 v89, v82, v82
	v_fmac_f32_e32 v86, v71, v71
	v_fmac_f32_e32 v87, v75, v75
	v_fmac_f32_e32 v88, v79, v79
	v_fmac_f32_e32 v89, v83, v83
	v_add_f32_e32 v84, v86, v87
	v_add_f32_e32 v84, v84, v88
	v_add_f32_e32 v84, v84, v89
	v_lshlrev_b32_e32 v160, 16, v28
	v_and_b32_e32 v161, 0xffff0000, v28
	v_add_f32_dpp v84, v84, v84 quad_perm:[1,0,3,2] row_mask:0xf bank_mask:0xf
	v_lshlrev_b32_e32 v162, 16, v29
	v_and_b32_e32 v163, 0xffff0000, v29
	v_add_f32_dpp v84, v84, v84 quad_perm:[2,3,0,1] row_mask:0xf bank_mask:0xf
	v_lshlrev_b32_e32 v164, 16, v30
	v_and_b32_e32 v165, 0xffff0000, v30
	v_add_f32_dpp v84, v84, v84 row_half_mirror row_mask:0xf bank_mask:0xf
	v_lshlrev_b32_e32 v166, 16, v31
	v_and_b32_e32 v167, 0xffff0000, v31
	v_add_f32_dpp v84, v84, v84 row_mirror row_mask:0xf bank_mask:0xf
	v_lshlrev_b32_e32 v168, 16, v32
	v_and_b32_e32 v169, 0xffff0000, v32
	v_add_f32_dpp v84, v84, v84 row_bcast:15 row_mask:0xa bank_mask:0xf
	v_lshlrev_b32_e32 v170, 16, v33
	v_and_b32_e32 v171, 0xffff0000, v33
	v_add_f32_dpp v84, v84, v84 row_bcast:31 row_mask:0xc bank_mask:0xf
	v_lshlrev_b32_e32 v172, 16, v34
	v_and_b32_e32 v173, 0xffff0000, v34
	v_lshlrev_b32_e32 v174, 16, v35
	v_and_b32_e32 v175, 0xffff0000, v35
	s_nop 0
	v_readlane_b32 s83, v84, 63
	s_nop 2
	v_fma_f32 v84, s83, v2, v3
	v_rsq_f32_e32 v84, v84
	s_nop 0
	v_mul_f32_e32 v68, v68, v84
	v_mul_f32_e32 v69, v69, v84
	v_mul_f32_e32 v70, v70, v84
	v_mul_f32_e32 v71, v71, v84
	v_mul_f32_e32 v72, v72, v84
	v_mul_f32_e32 v73, v73, v84
	v_mul_f32_e32 v74, v74, v84
	v_mul_f32_e32 v75, v75, v84
	v_mul_f32_e32 v76, v76, v84
	v_mul_f32_e32 v77, v77, v84
	v_mul_f32_e32 v78, v78, v84
	v_mul_f32_e32 v79, v79, v84
	v_mul_f32_e32 v80, v80, v84
	v_mul_f32_e32 v81, v81, v84
	v_mul_f32_e32 v82, v82, v84
	v_mul_f32_e32 v83, v83, v84
	v_fma_f32 v68, v68, v4, v160
	v_fma_f32 v69, v69, v5, v161
	v_fma_f32 v70, v70, v6, v162
	v_fma_f32 v71, v71, v7, v163
	v_fma_f32 v72, v72, v8, v164
	v_fma_f32 v73, v73, v9, v165
	v_fma_f32 v74, v74, v10, v166
	v_fma_f32 v75, v75, v11, v167
	v_fma_f32 v76, v76, v12, v168
	v_fma_f32 v77, v77, v13, v169
	v_fma_f32 v78, v78, v14, v170
	v_fma_f32 v79, v79, v15, v171
	v_fma_f32 v80, v80, v16, v172
	v_fma_f32 v81, v81, v17, v173
	v_fma_f32 v82, v82, v18, v174
	v_fma_f32 v83, v83, v19, v175
	v_mul_f32_e32 v86, v68, v68
	v_mul_f32_e32 v87, v72, v72
	v_mul_f32_e32 v88, v76, v76
	v_mul_f32_e32 v89, v80, v80
	v_fmac_f32_e32 v86, v69, v69
	v_fmac_f32_e32 v87, v73, v73
	v_fmac_f32_e32 v88, v77, v77
	v_fmac_f32_e32 v89, v81, v81
	v_fmac_f32_e32 v86, v70, v70
	v_fmac_f32_e32 v87, v74, v74
	v_fmac_f32_e32 v88, v78, v78
	v_fmac_f32_e32 v89, v82, v82
	v_fmac_f32_e32 v86, v71, v71
	v_fmac_f32_e32 v87, v75, v75
	v_fmac_f32_e32 v88, v79, v79
	v_fmac_f32_e32 v89, v83, v83
	v_add_f32_e32 v85, v86, v87
	v_add_f32_e32 v85, v85, v88
	v_add_f32_e32 v85, v85, v89
	v_cvt_pk_bf16_f32 v90, v68, v69
	v_cvt_pk_bf16_f32 v91, v70, v71
	v_add_f32_dpp v85, v85, v85 quad_perm:[1,0,3,2] row_mask:0xf bank_mask:0xf
	v_cvt_pk_bf16_f32 v92, v72, v73
	v_cvt_pk_bf16_f32 v93, v74, v75
	v_add_f32_dpp v85, v85, v85 quad_perm:[2,3,0,1] row_mask:0xf bank_mask:0xf
	v_cvt_pk_bf16_f32 v94, v76, v77
	v_cvt_pk_bf16_f32 v95, v78, v79
	v_add_f32_dpp v85, v85, v85 row_half_mirror row_mask:0xf bank_mask:0xf
	v_cvt_pk_bf16_f32 v96, v80, v81
	v_cvt_pk_bf16_f32 v97, v82, v83
	v_add_f32_dpp v85, v85, v85 row_mirror row_mask:0xf bank_mask:0xf
	s_nop 1
	v_add_f32_dpp v85, v85, v85 row_bcast:15 row_mask:0xa bank_mask:0xf
	s_nop 1
	v_add_f32_dpp v85, v85, v85 row_bcast:31 row_mask:0xc bank_mask:0xf
	global_store_dwordx2 v1, v[90:91], s[74:75] offset:0
	global_store_dwordx2 v1, v[92:93], s[74:75] offset:512
	global_store_dwordx2 v1, v[94:95], s[74:75] offset:1024
	global_store_dwordx2 v1, v[96:97], s[74:75] offset:1536
	v_readlane_b32 s84, v85, 63
	s_add_u32 s74, s74, 0x400000
	s_addc_u32 s75, s75, 0
	s_nop 0
	v_fma_f32 v85, s84, v2, v3
	v_rsq_f32_e32 v85, v85
	s_nop 0
	v_mul_f32_e32 v68, v68, v85
	v_mul_f32_e32 v69, v69, v85
	v_mul_f32_e32 v70, v70, v85
	v_mul_f32_e32 v71, v71, v85
	v_mul_f32_e32 v72, v72, v85
	v_mul_f32_e32 v73, v73, v85
	v_mul_f32_e32 v74, v74, v85
	v_mul_f32_e32 v75, v75, v85
	v_mul_f32_e32 v76, v76, v85
	v_mul_f32_e32 v77, v77, v85
	v_mul_f32_e32 v78, v78, v85
	v_mul_f32_e32 v79, v79, v85
	v_mul_f32_e32 v80, v80, v85
	v_mul_f32_e32 v81, v81, v85
	v_mul_f32_e32 v82, v82, v85
	v_mul_f32_e32 v83, v83, v85
	v_mul_f32_e32 v68, v68, v100
	v_mul_f32_e32 v69, v69, v101
	v_mul_f32_e32 v70, v70, v102
	v_mul_f32_e32 v71, v71, v103
	v_mul_f32_e32 v72, v72, v104
	v_mul_f32_e32 v73, v73, v105
	v_mul_f32_e32 v74, v74, v106
	v_mul_f32_e32 v75, v75, v107
	v_mul_f32_e32 v76, v76, v108
	v_mul_f32_e32 v77, v77, v109
	v_mul_f32_e32 v78, v78, v110
	v_mul_f32_e32 v79, v79, v111
	v_mul_f32_e32 v80, v80, v112
	v_mul_f32_e32 v81, v81, v113
	v_mul_f32_e32 v82, v82, v114
	v_mul_f32_e32 v83, v83, v115
	v_cvt_pk_bf16_f32 v176, v68, v69
	v_cvt_pk_bf16_f32 v177, v70, v71
	v_cvt_pk_bf16_f32 v178, v72, v73
	v_cvt_pk_bf16_f32 v179, v74, v75
	v_cvt_pk_bf16_f32 v180, v76, v77
	v_cvt_pk_bf16_f32 v181, v78, v79
	v_cvt_pk_bf16_f32 v182, v80, v81
	v_cvt_pk_bf16_f32 v183, v82, v83
	global_store_dwordx2 v1, v[176:177], s[76:77] offset:0
	global_store_dwordx2 v1, v[178:179], s[76:77] offset:512
	global_store_dwordx2 v1, v[180:181], s[76:77] offset:1024
	global_store_dwordx2 v1, v[182:183], s[76:77] offset:1536
	s_add_u32 s76, s76, 0x400000
	s_addc_u32 s77, s77, 0
	global_load_dwordx2 v[20:21], v1, s[70:71] offset:0
	global_load_dwordx2 v[22:23], v1, s[70:71] offset:512
	global_load_dwordx2 v[24:25], v1, s[70:71] offset:1024
	global_load_dwordx2 v[26:27], v1, s[70:71] offset:1536
	global_load_dwordx2 v[28:29], v1, s[72:73] offset:0
	global_load_dwordx2 v[30:31], v1, s[72:73] offset:512
	global_load_dwordx2 v[32:33], v1, s[72:73] offset:1024
	global_load_dwordx2 v[34:35], v1, s[72:73] offset:1536
	s_add_u32 s70, s70, 0x400000
	s_addc_u32 s71, s71, 0
	s_add_u32 s72, s72, 0x400000
	s_addc_u32 s73, s73, 0
	s_waitcnt vmcnt(32)
	v_lshlrev_b32_e32 v68, 16, v36
	v_and_b32_e32 v69, 0xffff0000, v36
	v_lshlrev_b32_e32 v70, 16, v37
	v_and_b32_e32 v71, 0xffff0000, v37
	v_lshlrev_b32_e32 v72, 16, v38
	v_and_b32_e32 v73, 0xffff0000, v38
	v_lshlrev_b32_e32 v74, 16, v39
	v_and_b32_e32 v75, 0xffff0000, v39
	v_lshlrev_b32_e32 v76, 16, v40
	v_and_b32_e32 v77, 0xffff0000, v40
	v_lshlrev_b32_e32 v78, 16, v41
	v_and_b32_e32 v79, 0xffff0000, v41
	v_lshlrev_b32_e32 v80, 16, v42
	v_and_b32_e32 v81, 0xffff0000, v42
	v_lshlrev_b32_e32 v82, 16, v43
	v_and_b32_e32 v83, 0xffff0000, v43
	v_mul_f32_e32 v86, v68, v68
	v_mul_f32_e32 v87, v72, v72
	v_mul_f32_e32 v88, v76, v76
	v_mul_f32_e32 v89, v80, v80
	v_fmac_f32_e32 v86, v69, v69
	v_fmac_f32_e32 v87, v73, v73
	v_fmac_f32_e32 v88, v77, v77
	v_fmac_f32_e32 v89, v81, v81
	v_fmac_f32_e32 v86, v70, v70
	v_fmac_f32_e32 v87, v74, v74
	v_fmac_f32_e32 v88, v78, v78
	v_fmac_f32_e32 v89, v82, v82
	v_fmac_f32_e32 v86, v71, v71
	v_fmac_f32_e32 v87, v75, v75
	v_fmac_f32_e32 v88, v79, v79
	v_fmac_f32_e32 v89, v83, v83
	v_add_f32_e32 v84, v86, v87
	v_add_f32_e32 v84, v84, v88
	v_add_f32_e32 v84, v84, v89
	v_lshlrev_b32_e32 v160, 16, v44
	v_and_b32_e32 v161, 0xffff0000, v44
	v_add_f32_dpp v84, v84, v84 quad_perm:[1,0,3,2] row_mask:0xf bank_mask:0xf
	v_lshlrev_b32_e32 v162, 16, v45
	v_and_b32_e32 v163, 0xffff0000, v45
	v_add_f32_dpp v84, v84, v84 quad_perm:[2,3,0,1] row_mask:0xf bank_mask:0xf
	v_lshlrev_b32_e32 v164, 16, v46
	v_and_b32_e32 v165, 0xffff0000, v46
	v_add_f32_dpp v84, v84, v84 row_half_mirror row_mask:0xf bank_mask:0xf
	v_lshlrev_b32_e32 v166, 16, v47
	v_and_b32_e32 v167, 0xffff0000, v47
	v_add_f32_dpp v84, v84, v84 row_mirror row_mask:0xf bank_mask:0xf
	v_lshlrev_b32_e32 v168, 16, v48
	v_and_b32_e32 v169, 0xffff0000, v48
	v_add_f32_dpp v84, v84, v84 row_bcast:15 row_mask:0xa bank_mask:0xf
	v_lshlrev_b32_e32 v170, 16, v49
	v_and_b32_e32 v171, 0xffff0000, v49
	v_add_f32_dpp v84, v84, v84 row_bcast:31 row_mask:0xc bank_mask:0xf
	v_lshlrev_b32_e32 v172, 16, v50
	v_and_b32_e32 v173, 0xffff0000, v50
	v_lshlrev_b32_e32 v174, 16, v51
	v_and_b32_e32 v175, 0xffff0000, v51
	s_nop 0
	v_readlane_b32 s83, v84, 63
	s_nop 2
	v_fma_f32 v84, s83, v2, v3
	v_rsq_f32_e32 v84, v84
	s_nop 0
	v_mul_f32_e32 v68, v68, v84
	v_mul_f32_e32 v69, v69, v84
	v_mul_f32_e32 v70, v70, v84
	v_mul_f32_e32 v71, v71, v84
	v_mul_f32_e32 v72, v72, v84
	v_mul_f32_e32 v73, v73, v84
	v_mul_f32_e32 v74, v74, v84
	v_mul_f32_e32 v75, v75, v84
	v_mul_f32_e32 v76, v76, v84
	v_mul_f32_e32 v77, v77, v84
	v_mul_f32_e32 v78, v78, v84
	v_mul_f32_e32 v79, v79, v84
	v_mul_f32_e32 v80, v80, v84
	v_mul_f32_e32 v81, v81, v84
	v_mul_f32_e32 v82, v82, v84
	v_mul_f32_e32 v83, v83, v84
	v_fma_f32 v68, v68, v4, v160
	v_fma_f32 v69, v69, v5, v161
	v_fma_f32 v70, v70, v6, v162
	v_fma_f32 v71, v71, v7, v163
	v_fma_f32 v72, v72, v8, v164
	v_fma_f32 v73, v73, v9, v165
	v_fma_f32 v74, v74, v10, v166
	v_fma_f32 v75, v75, v11, v167
	v_fma_f32 v76, v76, v12, v168
	v_fma_f32 v77, v77, v13, v169
	v_fma_f32 v78, v78, v14, v170
	v_fma_f32 v79, v79, v15, v171
	v_fma_f32 v80, v80, v16, v172
	v_fma_f32 v81, v81, v17, v173
	v_fma_f32 v82, v82, v18, v174
	v_fma_f32 v83, v83, v19, v175
	v_mul_f32_e32 v86, v68, v68
	v_mul_f32_e32 v87, v72, v72
	v_mul_f32_e32 v88, v76, v76
	v_mul_f32_e32 v89, v80, v80
	v_fmac_f32_e32 v86, v69, v69
	v_fmac_f32_e32 v87, v73, v73
	v_fmac_f32_e32 v88, v77, v77
	v_fmac_f32_e32 v89, v81, v81
	v_fmac_f32_e32 v86, v70, v70
	v_fmac_f32_e32 v87, v74, v74
	v_fmac_f32_e32 v88, v78, v78
	v_fmac_f32_e32 v89, v82, v82
	v_fmac_f32_e32 v86, v71, v71
	v_fmac_f32_e32 v87, v75, v75
	v_fmac_f32_e32 v88, v79, v79
	v_fmac_f32_e32 v89, v83, v83
	v_add_f32_e32 v85, v86, v87
	v_add_f32_e32 v85, v85, v88
	v_add_f32_e32 v85, v85, v89
	v_cvt_pk_bf16_f32 v90, v68, v69
	v_cvt_pk_bf16_f32 v91, v70, v71
	v_add_f32_dpp v85, v85, v85 quad_perm:[1,0,3,2] row_mask:0xf bank_mask:0xf
	v_cvt_pk_bf16_f32 v92, v72, v73
	v_cvt_pk_bf16_f32 v93, v74, v75
	v_add_f32_dpp v85, v85, v85 quad_perm:[2,3,0,1] row_mask:0xf bank_mask:0xf
	v_cvt_pk_bf16_f32 v94, v76, v77
	v_cvt_pk_bf16_f32 v95, v78, v79
	v_add_f32_dpp v85, v85, v85 row_half_mirror row_mask:0xf bank_mask:0xf
	v_cvt_pk_bf16_f32 v96, v80, v81
	v_cvt_pk_bf16_f32 v97, v82, v83
	v_add_f32_dpp v85, v85, v85 row_mirror row_mask:0xf bank_mask:0xf
	s_nop 1
	v_add_f32_dpp v85, v85, v85 row_bcast:15 row_mask:0xa bank_mask:0xf
	s_nop 1
	v_add_f32_dpp v85, v85, v85 row_bcast:31 row_mask:0xc bank_mask:0xf
	global_store_dwordx2 v1, v[90:91], s[74:75] offset:0
	global_store_dwordx2 v1, v[92:93], s[74:75] offset:512
	global_store_dwordx2 v1, v[94:95], s[74:75] offset:1024
	global_store_dwordx2 v1, v[96:97], s[74:75] offset:1536
	v_readlane_b32 s84, v85, 63
	s_add_u32 s74, s74, 0x400000
	s_addc_u32 s75, s75, 0
	s_nop 0
	v_fma_f32 v85, s84, v2, v3
	v_rsq_f32_e32 v85, v85
	s_nop 0
	v_mul_f32_e32 v68, v68, v85
	v_mul_f32_e32 v69, v69, v85
	v_mul_f32_e32 v70, v70, v85
	v_mul_f32_e32 v71, v71, v85
	v_mul_f32_e32 v72, v72, v85
	v_mul_f32_e32 v73, v73, v85
	v_mul_f32_e32 v74, v74, v85
	v_mul_f32_e32 v75, v75, v85
	v_mul_f32_e32 v76, v76, v85
	v_mul_f32_e32 v77, v77, v85
	v_mul_f32_e32 v78, v78, v85
	v_mul_f32_e32 v79, v79, v85
	v_mul_f32_e32 v80, v80, v85
	v_mul_f32_e32 v81, v81, v85
	v_mul_f32_e32 v82, v82, v85
	v_mul_f32_e32 v83, v83, v85
	v_mul_f32_e32 v68, v68, v100
	v_mul_f32_e32 v69, v69, v101
	v_mul_f32_e32 v70, v70, v102
	v_mul_f32_e32 v71, v71, v103
	v_mul_f32_e32 v72, v72, v104
	v_mul_f32_e32 v73, v73, v105
	v_mul_f32_e32 v74, v74, v106
	v_mul_f32_e32 v75, v75, v107
	v_mul_f32_e32 v76, v76, v108
	v_mul_f32_e32 v77, v77, v109
	v_mul_f32_e32 v78, v78, v110
	v_mul_f32_e32 v79, v79, v111
	v_mul_f32_e32 v80, v80, v112
	v_mul_f32_e32 v81, v81, v113
	v_mul_f32_e32 v82, v82, v114
	v_mul_f32_e32 v83, v83, v115
	v_cvt_pk_bf16_f32 v176, v68, v69
	v_cvt_pk_bf16_f32 v177, v70, v71
	v_cvt_pk_bf16_f32 v178, v72, v73
	v_cvt_pk_bf16_f32 v179, v74, v75
	v_cvt_pk_bf16_f32 v180, v76, v77
	v_cvt_pk_bf16_f32 v181, v78, v79
	v_cvt_pk_bf16_f32 v182, v80, v81
	v_cvt_pk_bf16_f32 v183, v82, v83
	global_store_dwordx2 v1, v[176:177], s[76:77] offset:0
	global_store_dwordx2 v1, v[178:179], s[76:77] offset:512
	global_store_dwordx2 v1, v[180:181], s[76:77] offset:1024
	global_store_dwordx2 v1, v[182:183], s[76:77] offset:1536
	s_add_u32 s76, s76, 0x400000
	s_addc_u32 s77, s77, 0
	global_load_dwordx2 v[36:37], v1, s[70:71] offset:0
	global_load_dwordx2 v[38:39], v1, s[70:71] offset:512
	global_load_dwordx2 v[40:41], v1, s[70:71] offset:1024
	global_load_dwordx2 v[42:43], v1, s[70:71] offset:1536
	global_load_dwordx2 v[44:45], v1, s[72:73] offset:0
	global_load_dwordx2 v[46:47], v1, s[72:73] offset:512
	global_load_dwordx2 v[48:49], v1, s[72:73] offset:1024
	global_load_dwordx2 v[50:51], v1, s[72:73] offset:1536
	s_add_u32 s70, s70, 0x400000
	s_addc_u32 s71, s71, 0
	s_add_u32 s72, s72, 0x400000
	s_addc_u32 s73, s73, 0
	s_waitcnt vmcnt(40)
	v_lshlrev_b32_e32 v68, 16, v52
	v_and_b32_e32 v69, 0xffff0000, v52
	v_lshlrev_b32_e32 v70, 16, v53
	v_and_b32_e32 v71, 0xffff0000, v53
	v_lshlrev_b32_e32 v72, 16, v54
	v_and_b32_e32 v73, 0xffff0000, v54
	v_lshlrev_b32_e32 v74, 16, v55
	v_and_b32_e32 v75, 0xffff0000, v55
	v_lshlrev_b32_e32 v76, 16, v56
	v_and_b32_e32 v77, 0xffff0000, v56
	v_lshlrev_b32_e32 v78, 16, v57
	v_and_b32_e32 v79, 0xffff0000, v57
	v_lshlrev_b32_e32 v80, 16, v58
	v_and_b32_e32 v81, 0xffff0000, v58
	v_lshlrev_b32_e32 v82, 16, v59
	v_and_b32_e32 v83, 0xffff0000, v59
	v_mul_f32_e32 v86, v68, v68
	v_mul_f32_e32 v87, v72, v72
	v_mul_f32_e32 v88, v76, v76
	v_mul_f32_e32 v89, v80, v80
	v_fmac_f32_e32 v86, v69, v69
	v_fmac_f32_e32 v87, v73, v73
	v_fmac_f32_e32 v88, v77, v77
	v_fmac_f32_e32 v89, v81, v81
	v_fmac_f32_e32 v86, v70, v70
	v_fmac_f32_e32 v87, v74, v74
	v_fmac_f32_e32 v88, v78, v78
	v_fmac_f32_e32 v89, v82, v82
	v_fmac_f32_e32 v86, v71, v71
	v_fmac_f32_e32 v87, v75, v75
	v_fmac_f32_e32 v88, v79, v79
	v_fmac_f32_e32 v89, v83, v83
	v_add_f32_e32 v84, v86, v87
	v_add_f32_e32 v84, v84, v88
	v_add_f32_e32 v84, v84, v89
	v_lshlrev_b32_e32 v160, 16, v60
	v_and_b32_e32 v161, 0xffff0000, v60
	v_add_f32_dpp v84, v84, v84 quad_perm:[1,0,3,2] row_mask:0xf bank_mask:0xf
	v_lshlrev_b32_e32 v162, 16, v61
	v_and_b32_e32 v163, 0xffff0000, v61
	v_add_f32_dpp v84, v84, v84 quad_perm:[2,3,0,1] row_mask:0xf bank_mask:0xf
	v_lshlrev_b32_e32 v164, 16, v62
	v_and_b32_e32 v165, 0xffff0000, v62
	v_add_f32_dpp v84, v84, v84 row_half_mirror row_mask:0xf bank_mask:0xf
	v_lshlrev_b32_e32 v166, 16, v63
	v_and_b32_e32 v167, 0xffff0000, v63
	v_add_f32_dpp v84, v84, v84 row_mirror row_mask:0xf bank_mask:0xf
	v_lshlrev_b32_e32 v168, 16, v64
	v_and_b32_e32 v169, 0xffff0000, v64
	v_add_f32_dpp v84, v84, v84 row_bcast:15 row_mask:0xa bank_mask:0xf
	v_lshlrev_b32_e32 v170, 16, v65
	v_and_b32_e32 v171, 0xffff0000, v65
	v_add_f32_dpp v84, v84, v84 row_bcast:31 row_mask:0xc bank_mask:0xf
	v_lshlrev_b32_e32 v172, 16, v66
	v_and_b32_e32 v173, 0xffff0000, v66
	v_lshlrev_b32_e32 v174, 16, v67
	v_and_b32_e32 v175, 0xffff0000, v67
	s_nop 0
	v_readlane_b32 s83, v84, 63
	s_nop 2
	v_fma_f32 v84, s83, v2, v3
	v_rsq_f32_e32 v84, v84
	s_nop 0
	v_mul_f32_e32 v68, v68, v84
	v_mul_f32_e32 v69, v69, v84
	v_mul_f32_e32 v70, v70, v84
	v_mul_f32_e32 v71, v71, v84
	v_mul_f32_e32 v72, v72, v84
	v_mul_f32_e32 v73, v73, v84
	v_mul_f32_e32 v74, v74, v84
	v_mul_f32_e32 v75, v75, v84
	v_mul_f32_e32 v76, v76, v84
	v_mul_f32_e32 v77, v77, v84
	v_mul_f32_e32 v78, v78, v84
	v_mul_f32_e32 v79, v79, v84
	v_mul_f32_e32 v80, v80, v84
	v_mul_f32_e32 v81, v81, v84
	v_mul_f32_e32 v82, v82, v84
	v_mul_f32_e32 v83, v83, v84
	v_fma_f32 v68, v68, v4, v160
	v_fma_f32 v69, v69, v5, v161
	v_fma_f32 v70, v70, v6, v162
	v_fma_f32 v71, v71, v7, v163
	v_fma_f32 v72, v72, v8, v164
	v_fma_f32 v73, v73, v9, v165
	v_fma_f32 v74, v74, v10, v166
	v_fma_f32 v75, v75, v11, v167
	v_fma_f32 v76, v76, v12, v168
	v_fma_f32 v77, v77, v13, v169
	v_fma_f32 v78, v78, v14, v170
	v_fma_f32 v79, v79, v15, v171
	v_fma_f32 v80, v80, v16, v172
	v_fma_f32 v81, v81, v17, v173
	v_fma_f32 v82, v82, v18, v174
	v_fma_f32 v83, v83, v19, v175
	v_mul_f32_e32 v86, v68, v68
	v_mul_f32_e32 v87, v72, v72
	v_mul_f32_e32 v88, v76, v76
	v_mul_f32_e32 v89, v80, v80
	v_fmac_f32_e32 v86, v69, v69
	v_fmac_f32_e32 v87, v73, v73
	v_fmac_f32_e32 v88, v77, v77
	v_fmac_f32_e32 v89, v81, v81
	v_fmac_f32_e32 v86, v70, v70
	v_fmac_f32_e32 v87, v74, v74
	v_fmac_f32_e32 v88, v78, v78
	v_fmac_f32_e32 v89, v82, v82
	v_fmac_f32_e32 v86, v71, v71
	v_fmac_f32_e32 v87, v75, v75
	v_fmac_f32_e32 v88, v79, v79
	v_fmac_f32_e32 v89, v83, v83
	v_add_f32_e32 v85, v86, v87
	v_add_f32_e32 v85, v85, v88
	v_add_f32_e32 v85, v85, v89
	v_cvt_pk_bf16_f32 v90, v68, v69
	v_cvt_pk_bf16_f32 v91, v70, v71
	v_add_f32_dpp v85, v85, v85 quad_perm:[1,0,3,2] row_mask:0xf bank_mask:0xf
	v_cvt_pk_bf16_f32 v92, v72, v73
	v_cvt_pk_bf16_f32 v93, v74, v75
	v_add_f32_dpp v85, v85, v85 quad_perm:[2,3,0,1] row_mask:0xf bank_mask:0xf
	v_cvt_pk_bf16_f32 v94, v76, v77
	v_cvt_pk_bf16_f32 v95, v78, v79
	v_add_f32_dpp v85, v85, v85 row_half_mirror row_mask:0xf bank_mask:0xf
	v_cvt_pk_bf16_f32 v96, v80, v81
	v_cvt_pk_bf16_f32 v97, v82, v83
	v_add_f32_dpp v85, v85, v85 row_mirror row_mask:0xf bank_mask:0xf
	s_nop 1
	v_add_f32_dpp v85, v85, v85 row_bcast:15 row_mask:0xa bank_mask:0xf
	s_nop 1
	v_add_f32_dpp v85, v85, v85 row_bcast:31 row_mask:0xc bank_mask:0xf
	global_store_dwordx2 v1, v[90:91], s[74:75] offset:0
	global_store_dwordx2 v1, v[92:93], s[74:75] offset:512
	global_store_dwordx2 v1, v[94:95], s[74:75] offset:1024
	global_store_dwordx2 v1, v[96:97], s[74:75] offset:1536
	v_readlane_b32 s84, v85, 63
	s_add_u32 s74, s74, 0x400000
	s_addc_u32 s75, s75, 0
	s_nop 0
	v_fma_f32 v85, s84, v2, v3
	v_rsq_f32_e32 v85, v85
	s_nop 0
	v_mul_f32_e32 v68, v68, v85
	v_mul_f32_e32 v69, v69, v85
	v_mul_f32_e32 v70, v70, v85
	v_mul_f32_e32 v71, v71, v85
	v_mul_f32_e32 v72, v72, v85
	v_mul_f32_e32 v73, v73, v85
	v_mul_f32_e32 v74, v74, v85
	v_mul_f32_e32 v75, v75, v85
	v_mul_f32_e32 v76, v76, v85
	v_mul_f32_e32 v77, v77, v85
	v_mul_f32_e32 v78, v78, v85
	v_mul_f32_e32 v79, v79, v85
	v_mul_f32_e32 v80, v80, v85
	v_mul_f32_e32 v81, v81, v85
	v_mul_f32_e32 v82, v82, v85
	v_mul_f32_e32 v83, v83, v85
	v_mul_f32_e32 v68, v68, v100
	v_mul_f32_e32 v69, v69, v101
	v_mul_f32_e32 v70, v70, v102
	v_mul_f32_e32 v71, v71, v103
	v_mul_f32_e32 v72, v72, v104
	v_mul_f32_e32 v73, v73, v105
	v_mul_f32_e32 v74, v74, v106
	v_mul_f32_e32 v75, v75, v107
	v_mul_f32_e32 v76, v76, v108
	v_mul_f32_e32 v77, v77, v109
	v_mul_f32_e32 v78, v78, v110
	v_mul_f32_e32 v79, v79, v111
	v_mul_f32_e32 v80, v80, v112
	v_mul_f32_e32 v81, v81, v113
	v_mul_f32_e32 v82, v82, v114
	v_mul_f32_e32 v83, v83, v115
	v_cvt_pk_bf16_f32 v176, v68, v69
	v_cvt_pk_bf16_f32 v177, v70, v71
	v_cvt_pk_bf16_f32 v178, v72, v73
	v_cvt_pk_bf16_f32 v179, v74, v75
	v_cvt_pk_bf16_f32 v180, v76, v77
	v_cvt_pk_bf16_f32 v181, v78, v79
	v_cvt_pk_bf16_f32 v182, v80, v81
	v_cvt_pk_bf16_f32 v183, v82, v83
	global_store_dwordx2 v1, v[176:177], s[76:77] offset:0
	global_store_dwordx2 v1, v[178:179], s[76:77] offset:512
	global_store_dwordx2 v1, v[180:181], s[76:77] offset:1024
	global_store_dwordx2 v1, v[182:183], s[76:77] offset:1536
	s_add_u32 s76, s76, 0x400000
	s_addc_u32 s77, s77, 0
	global_load_dwordx2 v[52:53], v1, s[70:71] offset:0
	global_load_dwordx2 v[54:55], v1, s[70:71] offset:512
	global_load_dwordx2 v[56:57], v1, s[70:71] offset:1024
	global_load_dwordx2 v[58:59], v1, s[70:71] offset:1536
	global_load_dwordx2 v[60:61], v1, s[72:73] offset:0
	global_load_dwordx2 v[62:63], v1, s[72:73] offset:512
	global_load_dwordx2 v[64:65], v1, s[72:73] offset:1024
	global_load_dwordx2 v[66:67], v1, s[72:73] offset:1536
	s_add_u32 s70, s70, 0x400000
	s_addc_u32 s71, s71, 0
	s_add_u32 s72, s72, 0x400000
	s_addc_u32 s73, s73, 0
	s_waitcnt vmcnt(48)
	v_lshlrev_b32_e32 v68, 16, v184
	v_and_b32_e32 v69, 0xffff0000, v184
	v_lshlrev_b32_e32 v70, 16, v185
	v_and_b32_e32 v71, 0xffff0000, v185
	v_lshlrev_b32_e32 v72, 16, v186
	v_and_b32_e32 v73, 0xffff0000, v186
	v_lshlrev_b32_e32 v74, 16, v187
	v_and_b32_e32 v75, 0xffff0000, v187
	v_lshlrev_b32_e32 v76, 16, v188
	v_and_b32_e32 v77, 0xffff0000, v188
	v_lshlrev_b32_e32 v78, 16, v189
	v_and_b32_e32 v79, 0xffff0000, v189
	v_lshlrev_b32_e32 v80, 16, v190
	v_and_b32_e32 v81, 0xffff0000, v190
	v_lshlrev_b32_e32 v82, 16, v191
	v_and_b32_e32 v83, 0xffff0000, v191
	v_mul_f32_e32 v86, v68, v68
	v_mul_f32_e32 v87, v72, v72
	v_mul_f32_e32 v88, v76, v76
	v_mul_f32_e32 v89, v80, v80
	v_fmac_f32_e32 v86, v69, v69
	v_fmac_f32_e32 v87, v73, v73
	v_fmac_f32_e32 v88, v77, v77
	v_fmac_f32_e32 v89, v81, v81
	v_fmac_f32_e32 v86, v70, v70
	v_fmac_f32_e32 v87, v74, v74
	v_fmac_f32_e32 v88, v78, v78
	v_fmac_f32_e32 v89, v82, v82
	v_fmac_f32_e32 v86, v71, v71
	v_fmac_f32_e32 v87, v75, v75
	v_fmac_f32_e32 v88, v79, v79
	v_fmac_f32_e32 v89, v83, v83
	v_add_f32_e32 v84, v86, v87
	v_add_f32_e32 v84, v84, v88
	v_add_f32_e32 v84, v84, v89
	v_lshlrev_b32_e32 v160, 16, v192
	v_and_b32_e32 v161, 0xffff0000, v192
	v_add_f32_dpp v84, v84, v84 quad_perm:[1,0,3,2] row_mask:0xf bank_mask:0xf
	v_lshlrev_b32_e32 v162, 16, v193
	v_and_b32_e32 v163, 0xffff0000, v193
	v_add_f32_dpp v84, v84, v84 quad_perm:[2,3,0,1] row_mask:0xf bank_mask:0xf
	v_lshlrev_b32_e32 v164, 16, v194
	v_and_b32_e32 v165, 0xffff0000, v194
	v_add_f32_dpp v84, v84, v84 row_half_mirror row_mask:0xf bank_mask:0xf
	v_lshlrev_b32_e32 v166, 16, v195
	v_and_b32_e32 v167, 0xffff0000, v195
	v_add_f32_dpp v84, v84, v84 row_mirror row_mask:0xf bank_mask:0xf
	v_lshlrev_b32_e32 v168, 16, v196
	v_and_b32_e32 v169, 0xffff0000, v196
	v_add_f32_dpp v84, v84, v84 row_bcast:15 row_mask:0xa bank_mask:0xf
	v_lshlrev_b32_e32 v170, 16, v197
	v_and_b32_e32 v171, 0xffff0000, v197
	v_add_f32_dpp v84, v84, v84 row_bcast:31 row_mask:0xc bank_mask:0xf
	v_lshlrev_b32_e32 v172, 16, v198
	v_and_b32_e32 v173, 0xffff0000, v198
	v_lshlrev_b32_e32 v174, 16, v199
	v_and_b32_e32 v175, 0xffff0000, v199
	s_nop 0
	v_readlane_b32 s83, v84, 63
	s_nop 2
	v_fma_f32 v84, s83, v2, v3
	v_rsq_f32_e32 v84, v84
	s_nop 0
	v_mul_f32_e32 v68, v68, v84
	v_mul_f32_e32 v69, v69, v84
	v_mul_f32_e32 v70, v70, v84
	v_mul_f32_e32 v71, v71, v84
	v_mul_f32_e32 v72, v72, v84
	v_mul_f32_e32 v73, v73, v84
	v_mul_f32_e32 v74, v74, v84
	v_mul_f32_e32 v75, v75, v84
	v_mul_f32_e32 v76, v76, v84
	v_mul_f32_e32 v77, v77, v84
	v_mul_f32_e32 v78, v78, v84
	v_mul_f32_e32 v79, v79, v84
	v_mul_f32_e32 v80, v80, v84
	v_mul_f32_e32 v81, v81, v84
	v_mul_f32_e32 v82, v82, v84
	v_mul_f32_e32 v83, v83, v84
	v_fma_f32 v68, v68, v4, v160
	v_fma_f32 v69, v69, v5, v161
	v_fma_f32 v70, v70, v6, v162
	v_fma_f32 v71, v71, v7, v163
	v_fma_f32 v72, v72, v8, v164
	v_fma_f32 v73, v73, v9, v165
	v_fma_f32 v74, v74, v10, v166
	v_fma_f32 v75, v75, v11, v167
	v_fma_f32 v76, v76, v12, v168
	v_fma_f32 v77, v77, v13, v169
	v_fma_f32 v78, v78, v14, v170
	v_fma_f32 v79, v79, v15, v171
	v_fma_f32 v80, v80, v16, v172
	v_fma_f32 v81, v81, v17, v173
	v_fma_f32 v82, v82, v18, v174
	v_fma_f32 v83, v83, v19, v175
	v_mul_f32_e32 v86, v68, v68
	v_mul_f32_e32 v87, v72, v72
	v_mul_f32_e32 v88, v76, v76
	v_mul_f32_e32 v89, v80, v80
	v_fmac_f32_e32 v86, v69, v69
	v_fmac_f32_e32 v87, v73, v73
	v_fmac_f32_e32 v88, v77, v77
	v_fmac_f32_e32 v89, v81, v81
	v_fmac_f32_e32 v86, v70, v70
	v_fmac_f32_e32 v87, v74, v74
	v_fmac_f32_e32 v88, v78, v78
	v_fmac_f32_e32 v89, v82, v82
	v_fmac_f32_e32 v86, v71, v71
	v_fmac_f32_e32 v87, v75, v75
	v_fmac_f32_e32 v88, v79, v79
	v_fmac_f32_e32 v89, v83, v83
	v_add_f32_e32 v85, v86, v87
	v_add_f32_e32 v85, v85, v88
	v_add_f32_e32 v85, v85, v89
	v_cvt_pk_bf16_f32 v90, v68, v69
	v_cvt_pk_bf16_f32 v91, v70, v71
	v_add_f32_dpp v85, v85, v85 quad_perm:[1,0,3,2] row_mask:0xf bank_mask:0xf
	v_cvt_pk_bf16_f32 v92, v72, v73
	v_cvt_pk_bf16_f32 v93, v74, v75
	v_add_f32_dpp v85, v85, v85 quad_perm:[2,3,0,1] row_mask:0xf bank_mask:0xf
	v_cvt_pk_bf16_f32 v94, v76, v77
	v_cvt_pk_bf16_f32 v95, v78, v79
	v_add_f32_dpp v85, v85, v85 row_half_mirror row_mask:0xf bank_mask:0xf
	v_cvt_pk_bf16_f32 v96, v80, v81
	v_cvt_pk_bf16_f32 v97, v82, v83
	v_add_f32_dpp v85, v85, v85 row_mirror row_mask:0xf bank_mask:0xf
	s_nop 1
	v_add_f32_dpp v85, v85, v85 row_bcast:15 row_mask:0xa bank_mask:0xf
	s_nop 1
	v_add_f32_dpp v85, v85, v85 row_bcast:31 row_mask:0xc bank_mask:0xf
	global_store_dwordx2 v1, v[90:91], s[74:75] offset:0
	global_store_dwordx2 v1, v[92:93], s[74:75] offset:512
	global_store_dwordx2 v1, v[94:95], s[74:75] offset:1024
	global_store_dwordx2 v1, v[96:97], s[74:75] offset:1536
	v_readlane_b32 s84, v85, 63
	s_add_u32 s74, s74, 0x400000
	s_addc_u32 s75, s75, 0
	s_nop 0
	v_fma_f32 v85, s84, v2, v3
	v_rsq_f32_e32 v85, v85
	s_nop 0
	v_mul_f32_e32 v68, v68, v85
	v_mul_f32_e32 v69, v69, v85
	v_mul_f32_e32 v70, v70, v85
	v_mul_f32_e32 v71, v71, v85
	v_mul_f32_e32 v72, v72, v85
	v_mul_f32_e32 v73, v73, v85
	v_mul_f32_e32 v74, v74, v85
	v_mul_f32_e32 v75, v75, v85
	v_mul_f32_e32 v76, v76, v85
	v_mul_f32_e32 v77, v77, v85
	v_mul_f32_e32 v78, v78, v85
	v_mul_f32_e32 v79, v79, v85
	v_mul_f32_e32 v80, v80, v85
	v_mul_f32_e32 v81, v81, v85
	v_mul_f32_e32 v82, v82, v85
	v_mul_f32_e32 v83, v83, v85
	v_mul_f32_e32 v68, v68, v100
	v_mul_f32_e32 v69, v69, v101
	v_mul_f32_e32 v70, v70, v102
	v_mul_f32_e32 v71, v71, v103
	v_mul_f32_e32 v72, v72, v104
	v_mul_f32_e32 v73, v73, v105
	v_mul_f32_e32 v74, v74, v106
	v_mul_f32_e32 v75, v75, v107
	v_mul_f32_e32 v76, v76, v108
	v_mul_f32_e32 v77, v77, v109
	v_mul_f32_e32 v78, v78, v110
	v_mul_f32_e32 v79, v79, v111
	v_mul_f32_e32 v80, v80, v112
	v_mul_f32_e32 v81, v81, v113
	v_mul_f32_e32 v82, v82, v114
	v_mul_f32_e32 v83, v83, v115
	v_cvt_pk_bf16_f32 v176, v68, v69
	v_cvt_pk_bf16_f32 v177, v70, v71
	v_cvt_pk_bf16_f32 v178, v72, v73
	v_cvt_pk_bf16_f32 v179, v74, v75
	v_cvt_pk_bf16_f32 v180, v76, v77
	v_cvt_pk_bf16_f32 v181, v78, v79
	v_cvt_pk_bf16_f32 v182, v80, v81
	v_cvt_pk_bf16_f32 v183, v82, v83
	global_store_dwordx2 v1, v[176:177], s[76:77] offset:0
	global_store_dwordx2 v1, v[178:179], s[76:77] offset:512
	global_store_dwordx2 v1, v[180:181], s[76:77] offset:1024
	global_store_dwordx2 v1, v[182:183], s[76:77] offset:1536
	s_add_u32 s76, s76, 0x400000
	s_addc_u32 s77, s77, 0
	global_load_dwordx2 v[184:185], v1, s[70:71] offset:0
	global_load_dwordx2 v[186:187], v1, s[70:71] offset:512
	global_load_dwordx2 v[188:189], v1, s[70:71] offset:1024
	global_load_dwordx2 v[190:191], v1, s[70:71] offset:1536
	global_load_dwordx2 v[192:193], v1, s[72:73] offset:0
	global_load_dwordx2 v[194:195], v1, s[72:73] offset:512
	global_load_dwordx2 v[196:197], v1, s[72:73] offset:1024
	global_load_dwordx2 v[198:199], v1, s[72:73] offset:1536
	s_add_u32 s70, s70, 0x400000
	s_addc_u32 s71, s71, 0
	s_add_u32 s72, s72, 0x400000
	s_addc_u32 s73, s73, 0
	s_waitcnt vmcnt(48)
	v_lshlrev_b32_e32 v68, 16, v20
	v_and_b32_e32 v69, 0xffff0000, v20
	v_lshlrev_b32_e32 v70, 16, v21
	v_and_b32_e32 v71, 0xffff0000, v21
	v_lshlrev_b32_e32 v72, 16, v22
	v_and_b32_e32 v73, 0xffff0000, v22
	v_lshlrev_b32_e32 v74, 16, v23
	v_and_b32_e32 v75, 0xffff0000, v23
	v_lshlrev_b32_e32 v76, 16, v24
	v_and_b32_e32 v77, 0xffff0000, v24
	v_lshlrev_b32_e32 v78, 16, v25
	v_and_b32_e32 v79, 0xffff0000, v25
	v_lshlrev_b32_e32 v80, 16, v26
	v_and_b32_e32 v81, 0xffff0000, v26
	v_lshlrev_b32_e32 v82, 16, v27
	v_and_b32_e32 v83, 0xffff0000, v27
	v_mul_f32_e32 v86, v68, v68
	v_mul_f32_e32 v87, v72, v72
	v_mul_f32_e32 v88, v76, v76
	v_mul_f32_e32 v89, v80, v80
	v_fmac_f32_e32 v86, v69, v69
	v_fmac_f32_e32 v87, v73, v73
	v_fmac_f32_e32 v88, v77, v77
	v_fmac_f32_e32 v89, v81, v81
	v_fmac_f32_e32 v86, v70, v70
	v_fmac_f32_e32 v87, v74, v74
	v_fmac_f32_e32 v88, v78, v78
	v_fmac_f32_e32 v89, v82, v82
	v_fmac_f32_e32 v86, v71, v71
	v_fmac_f32_e32 v87, v75, v75
	v_fmac_f32_e32 v88, v79, v79
	v_fmac_f32_e32 v89, v83, v83
	v_add_f32_e32 v84, v86, v87
	v_add_f32_e32 v84, v84, v88
	v_add_f32_e32 v84, v84, v89
	v_lshlrev_b32_e32 v160, 16, v28
	v_and_b32_e32 v161, 0xffff0000, v28
	v_add_f32_dpp v84, v84, v84 quad_perm:[1,0,3,2] row_mask:0xf bank_mask:0xf
	v_lshlrev_b32_e32 v162, 16, v29
	v_and_b32_e32 v163, 0xffff0000, v29
	v_add_f32_dpp v84, v84, v84 quad_perm:[2,3,0,1] row_mask:0xf bank_mask:0xf
	v_lshlrev_b32_e32 v164, 16, v30
	v_and_b32_e32 v165, 0xffff0000, v30
	v_add_f32_dpp v84, v84, v84 row_half_mirror row_mask:0xf bank_mask:0xf
	v_lshlrev_b32_e32 v166, 16, v31
	v_and_b32_e32 v167, 0xffff0000, v31
	v_add_f32_dpp v84, v84, v84 row_mirror row_mask:0xf bank_mask:0xf
	v_lshlrev_b32_e32 v168, 16, v32
	v_and_b32_e32 v169, 0xffff0000, v32
	v_add_f32_dpp v84, v84, v84 row_bcast:15 row_mask:0xa bank_mask:0xf
	v_lshlrev_b32_e32 v170, 16, v33
	v_and_b32_e32 v171, 0xffff0000, v33
	v_add_f32_dpp v84, v84, v84 row_bcast:31 row_mask:0xc bank_mask:0xf
	v_lshlrev_b32_e32 v172, 16, v34
	v_and_b32_e32 v173, 0xffff0000, v34
	v_lshlrev_b32_e32 v174, 16, v35
	v_and_b32_e32 v175, 0xffff0000, v35
	s_nop 0
	v_readlane_b32 s83, v84, 63
	s_nop 2
	v_fma_f32 v84, s83, v2, v3
	v_rsq_f32_e32 v84, v84
	s_nop 0
	v_mul_f32_e32 v68, v68, v84
	v_mul_f32_e32 v69, v69, v84
	v_mul_f32_e32 v70, v70, v84
	v_mul_f32_e32 v71, v71, v84
	v_mul_f32_e32 v72, v72, v84
	v_mul_f32_e32 v73, v73, v84
	v_mul_f32_e32 v74, v74, v84
	v_mul_f32_e32 v75, v75, v84
	v_mul_f32_e32 v76, v76, v84
	v_mul_f32_e32 v77, v77, v84
	v_mul_f32_e32 v78, v78, v84
	v_mul_f32_e32 v79, v79, v84
	v_mul_f32_e32 v80, v80, v84
	v_mul_f32_e32 v81, v81, v84
	v_mul_f32_e32 v82, v82, v84
	v_mul_f32_e32 v83, v83, v84
	v_fma_f32 v68, v68, v4, v160
	v_fma_f32 v69, v69, v5, v161
	v_fma_f32 v70, v70, v6, v162
	v_fma_f32 v71, v71, v7, v163
	v_fma_f32 v72, v72, v8, v164
	v_fma_f32 v73, v73, v9, v165
	v_fma_f32 v74, v74, v10, v166
	v_fma_f32 v75, v75, v11, v167
	v_fma_f32 v76, v76, v12, v168
	v_fma_f32 v77, v77, v13, v169
	v_fma_f32 v78, v78, v14, v170
	v_fma_f32 v79, v79, v15, v171
	v_fma_f32 v80, v80, v16, v172
	v_fma_f32 v81, v81, v17, v173
	v_fma_f32 v82, v82, v18, v174
	v_fma_f32 v83, v83, v19, v175
	v_mul_f32_e32 v86, v68, v68
	v_mul_f32_e32 v87, v72, v72
	v_mul_f32_e32 v88, v76, v76
	v_mul_f32_e32 v89, v80, v80
	v_fmac_f32_e32 v86, v69, v69
	v_fmac_f32_e32 v87, v73, v73
	v_fmac_f32_e32 v88, v77, v77
	v_fmac_f32_e32 v89, v81, v81
	v_fmac_f32_e32 v86, v70, v70
	v_fmac_f32_e32 v87, v74, v74
	v_fmac_f32_e32 v88, v78, v78
	v_fmac_f32_e32 v89, v82, v82
	v_fmac_f32_e32 v86, v71, v71
	v_fmac_f32_e32 v87, v75, v75
	v_fmac_f32_e32 v88, v79, v79
	v_fmac_f32_e32 v89, v83, v83
	v_add_f32_e32 v85, v86, v87
	v_add_f32_e32 v85, v85, v88
	v_add_f32_e32 v85, v85, v89
	v_cvt_pk_bf16_f32 v90, v68, v69
	v_cvt_pk_bf16_f32 v91, v70, v71
	v_add_f32_dpp v85, v85, v85 quad_perm:[1,0,3,2] row_mask:0xf bank_mask:0xf
	v_cvt_pk_bf16_f32 v92, v72, v73
	v_cvt_pk_bf16_f32 v93, v74, v75
	v_add_f32_dpp v85, v85, v85 quad_perm:[2,3,0,1] row_mask:0xf bank_mask:0xf
	v_cvt_pk_bf16_f32 v94, v76, v77
	v_cvt_pk_bf16_f32 v95, v78, v79
	v_add_f32_dpp v85, v85, v85 row_half_mirror row_mask:0xf bank_mask:0xf
	v_cvt_pk_bf16_f32 v96, v80, v81
	v_cvt_pk_bf16_f32 v97, v82, v83
	v_add_f32_dpp v85, v85, v85 row_mirror row_mask:0xf bank_mask:0xf
	s_nop 1
	v_add_f32_dpp v85, v85, v85 row_bcast:15 row_mask:0xa bank_mask:0xf
	s_nop 1
	v_add_f32_dpp v85, v85, v85 row_bcast:31 row_mask:0xc bank_mask:0xf
	global_store_dwordx2 v1, v[90:91], s[74:75] offset:0
	global_store_dwordx2 v1, v[92:93], s[74:75] offset:512
	global_store_dwordx2 v1, v[94:95], s[74:75] offset:1024
	global_store_dwordx2 v1, v[96:97], s[74:75] offset:1536
	v_readlane_b32 s84, v85, 63
	s_add_u32 s74, s74, 0x400000
	s_addc_u32 s75, s75, 0
	s_nop 0
	v_fma_f32 v85, s84, v2, v3
	v_rsq_f32_e32 v85, v85
	s_nop 0
	v_mul_f32_e32 v68, v68, v85
	v_mul_f32_e32 v69, v69, v85
	v_mul_f32_e32 v70, v70, v85
	v_mul_f32_e32 v71, v71, v85
	v_mul_f32_e32 v72, v72, v85
	v_mul_f32_e32 v73, v73, v85
	v_mul_f32_e32 v74, v74, v85
	v_mul_f32_e32 v75, v75, v85
	v_mul_f32_e32 v76, v76, v85
	v_mul_f32_e32 v77, v77, v85
	v_mul_f32_e32 v78, v78, v85
	v_mul_f32_e32 v79, v79, v85
	v_mul_f32_e32 v80, v80, v85
	v_mul_f32_e32 v81, v81, v85
	v_mul_f32_e32 v82, v82, v85
	v_mul_f32_e32 v83, v83, v85
	v_mul_f32_e32 v68, v68, v100
	v_mul_f32_e32 v69, v69, v101
	v_mul_f32_e32 v70, v70, v102
	v_mul_f32_e32 v71, v71, v103
	v_mul_f32_e32 v72, v72, v104
	v_mul_f32_e32 v73, v73, v105
	v_mul_f32_e32 v74, v74, v106
	v_mul_f32_e32 v75, v75, v107
	v_mul_f32_e32 v76, v76, v108
	v_mul_f32_e32 v77, v77, v109
	v_mul_f32_e32 v78, v78, v110
	v_mul_f32_e32 v79, v79, v111
	v_mul_f32_e32 v80, v80, v112
	v_mul_f32_e32 v81, v81, v113
	v_mul_f32_e32 v82, v82, v114
	v_mul_f32_e32 v83, v83, v115
	v_cvt_pk_bf16_f32 v176, v68, v69
	v_cvt_pk_bf16_f32 v177, v70, v71
	v_cvt_pk_bf16_f32 v178, v72, v73
	v_cvt_pk_bf16_f32 v179, v74, v75
	v_cvt_pk_bf16_f32 v180, v76, v77
	v_cvt_pk_bf16_f32 v181, v78, v79
	v_cvt_pk_bf16_f32 v182, v80, v81
	v_cvt_pk_bf16_f32 v183, v82, v83
	global_store_dwordx2 v1, v[176:177], s[76:77] offset:0
	global_store_dwordx2 v1, v[178:179], s[76:77] offset:512
	global_store_dwordx2 v1, v[180:181], s[76:77] offset:1024
	global_store_dwordx2 v1, v[182:183], s[76:77] offset:1536
	s_add_u32 s76, s76, 0x400000
	s_addc_u32 s77, s77, 0
	s_cmp_eq_u32 s82, 0
	s_cbranch_scc0 .Lrows_p9_r8ok
	s_sub_u32 s70, s70, 0x400000
	s_subb_u32 s71, s71, 0
	s_sub_u32 s72, s72, 0x400000
	s_subb_u32 s73, s73, 0

.LBB0_1201:
	s_cmp_lt_i32 s24, 14
	s_cselect_b64 s[4:5], -1, 0
	s_cmp_gt_i32 s25, 13
	s_cselect_b64 s[6:7], -1, 0
	s_and_b64 s[4:5], s[4:5], s[6:7]
	s_andn2_b64 vcc, exec, s[4:5]
	s_cbranch_vccnz .LBB0_1263
	s_mov_b64 exec, -1
	s_load_dword s3, s[0:1], 0x148
	s_add_u32 s6, s0, 0x148
	s_addc_u32 s7, s1, 0
	s_load_dwordx2 s[78:79], s[0:1], 0x30
	s_load_dwordx2 s[80:81], s[0:1], 0x38
	v_lshrrev_b32_e32 v0, 6, v129
	v_and_b32_e32 v1, 63, v129
	v_readfirstlane_b32 s68, v0
	v_lshlrev_b32_e32 v0, 4, v1
	v_lshlrev_b32_e32 v1, 3, v1
	v_mov_b32_e32 v2, 0x3a800000
	v_mov_b32_e32 v3, 0x358637bd
	s_lshl_b32 s69, s2, 3
	s_add_u32 s68, s68, s69
	s_waitcnt lgkmcnt(0)
	s_add_u32 s78, s78, 0x1000
	s_addc_u32 s79, s79, 0
	s_add_u32 s80, s80, 0x1000
	s_addc_u32 s81, s81, 0
	global_load_dwordx4 v[4:7], v0, s[78:79] offset:0
	global_load_dwordx4 v[8:11], v0, s[78:79] offset:1024
	global_load_dwordx4 v[12:15], v0, s[78:79] offset:2048
	global_load_dwordx4 v[16:19], v0, s[78:79] offset:3072
	global_load_dwordx4 v[100:103], v0, s[80:81] offset:0
	global_load_dwordx4 v[104:107], v0, s[80:81] offset:1024
	global_load_dwordx4 v[108:111], v0, s[80:81] offset:2048
	global_load_dwordx4 v[112:115], v0, s[80:81] offset:3072
	s_lshl_b32 s86, s68, 11
	s_add_u32 s70, s46, s86
	s_addc_u32 s71, s47, 0
	s_add_u32 s72, s50, s86
	s_addc_u32 s73, s51, 0
	s_mov_b64 s[74:75], s[72:73]
	s_add_u32 s76, s44, s86
	s_addc_u32 s77, s45, 0
	s_cmpk_lt_u32 s68, 0x200
	s_cselect_b32 s82, 1, 0
	global_load_dwordx2 v[20:21], v1, s[70:71] offset:0
	global_load_dwordx2 v[22:23], v1, s[70:71] offset:512
	global_load_dwordx2 v[24:25], v1, s[70:71] offset:1024
	global_load_dwordx2 v[26:27], v1, s[70:71] offset:1536
	global_load_dwordx2 v[28:29], v1, s[72:73] offset:0
	global_load_dwordx2 v[30:31], v1, s[72:73] offset:512
	global_load_dwordx2 v[32:33], v1, s[72:73] offset:1024
	global_load_dwordx2 v[34:35], v1, s[72:73] offset:1536
	s_add_u32 s70, s70, 0x400000
	s_addc_u32 s71, s71, 0
	s_add_u32 s72, s72, 0x400000
	s_addc_u32 s73, s73, 0
	global_load_dwordx2 v[36:37], v1, s[70:71] offset:0
	global_load_dwordx2 v[38:39], v1, s[70:71] offset:512
	global_load_dwordx2 v[40:41], v1, s[70:71] offset:1024
	global_load_dwordx2 v[42:43], v1, s[70:71] offset:1536
	global_load_dwordx2 v[44:45], v1, s[72:73] offset:0
	global_load_dwordx2 v[46:47], v1, s[72:73] offset:512
	global_load_dwordx2 v[48:49], v1, s[72:73] offset:1024
	global_load_dwordx2 v[50:51], v1, s[72:73] offset:1536
	s_add_u32 s70, s70, 0x400000
	s_addc_u32 s71, s71, 0
	s_add_u32 s72, s72, 0x400000
	s_addc_u32 s73, s73, 0
	global_load_dwordx2 v[52:53], v1, s[70:71] offset:0
	global_load_dwordx2 v[54:55], v1, s[70:71] offset:512
	global_load_dwordx2 v[56:57], v1, s[70:71] offset:1024
	global_load_dwordx2 v[58:59], v1, s[70:71] offset:1536
	global_load_dwordx2 v[60:61], v1, s[72:73] offset:0
	global_load_dwordx2 v[62:63], v1, s[72:73] offset:512
	global_load_dwordx2 v[64:65], v1, s[72:73] offset:1024
	global_load_dwordx2 v[66:67], v1, s[72:73] offset:1536
	s_add_u32 s70, s70, 0x400000
	s_addc_u32 s71, s71, 0
	s_add_u32 s72, s72, 0x400000
	s_addc_u32 s73, s73, 0
	global_load_dwordx2 v[184:185], v1, s[70:71] offset:0
	global_load_dwordx2 v[186:187], v1, s[70:71] offset:512
	global_load_dwordx2 v[188:189], v1, s[70:71] offset:1024
	global_load_dwordx2 v[190:191], v1, s[70:71] offset:1536
	global_load_dwordx2 v[192:193], v1, s[72:73] offset:0
	global_load_dwordx2 v[194:195], v1, s[72:73] offset:512
	global_load_dwordx2 v[196:197], v1, s[72:73] offset:1024
	global_load_dwordx2 v[198:199], v1, s[72:73] offset:1536
	s_add_u32 s70, s70, 0x400000
	s_addc_u32 s71, s71, 0
	s_add_u32 s72, s72, 0x400000
	s_addc_u32 s73, s73, 0
	s_waitcnt vmcnt(24)
	v_lshlrev_b32_e32 v68, 16, v20
	v_and_b32_e32 v69, 0xffff0000, v20
	v_lshlrev_b32_e32 v70, 16, v21
	v_and_b32_e32 v71, 0xffff0000, v21
	v_lshlrev_b32_e32 v72, 16, v22
	v_and_b32_e32 v73, 0xffff0000, v22
	v_lshlrev_b32_e32 v74, 16, v23
	v_and_b32_e32 v75, 0xffff0000, v23
	v_lshlrev_b32_e32 v76, 16, v24
	v_and_b32_e32 v77, 0xffff0000, v24
	v_lshlrev_b32_e32 v78, 16, v25
	v_and_b32_e32 v79, 0xffff0000, v25
	v_lshlrev_b32_e32 v80, 16, v26
	v_and_b32_e32 v81, 0xffff0000, v26
	v_lshlrev_b32_e32 v82, 16, v27
	v_and_b32_e32 v83, 0xffff0000, v27
	v_mul_f32_e32 v86, v68, v68
	v_mul_f32_e32 v87, v72, v72
	v_mul_f32_e32 v88, v76, v76
	v_mul_f32_e32 v89, v80, v80
	v_fmac_f32_e32 v86, v69, v69
	v_fmac_f32_e32 v87, v73, v73
	v_fmac_f32_e32 v88, v77, v77
	v_fmac_f32_e32 v89, v81, v81
	v_fmac_f32_e32 v86, v70, v70
	v_fmac_f32_e32 v87, v74, v74
	v_fmac_f32_e32 v88, v78, v78
	v_fmac_f32_e32 v89, v82, v82
	v_fmac_f32_e32 v86, v71, v71
	v_fmac_f32_e32 v87, v75, v75
	v_fmac_f32_e32 v88, v79, v79
	v_fmac_f32_e32 v89, v83, v83
	v_add_f32_e32 v84, v86, v87
	v_add_f32_e32 v84, v84, v88
	v_add_f32_e32 v84, v84, v89
	v_lshlrev_b32_e32 v160, 16, v28
	v_and_b32_e32 v161, 0xffff0000, v28
	v_add_f32_dpp v84, v84, v84 quad_perm:[1,0,3,2] row_mask:0xf bank_mask:0xf
	v_lshlrev_b32_e32 v162, 16, v29
	v_and_b32_e32 v163, 0xffff0000, v29
	v_add_f32_dpp v84, v84, v84 quad_perm:[2,3,0,1] row_mask:0xf bank_mask:0xf
	v_lshlrev_b32_e32 v164, 16, v30
	v_and_b32_e32 v165, 0xffff0000, v30
	v_add_f32_dpp v84, v84, v84 row_half_mirror row_mask:0xf bank_mask:0xf
	v_lshlrev_b32_e32 v166, 16, v31
	v_and_b32_e32 v167, 0xffff0000, v31
	v_add_f32_dpp v84, v84, v84 row_mirror row_mask:0xf bank_mask:0xf
	v_lshlrev_b32_e32 v168, 16, v32
	v_and_b32_e32 v169, 0xffff0000, v32
	v_add_f32_dpp v84, v84, v84 row_bcast:15 row_mask:0xa bank_mask:0xf
	v_lshlrev_b32_e32 v170, 16, v33
	v_and_b32_e32 v171, 0xffff0000, v33
	v_add_f32_dpp v84, v84, v84 row_bcast:31 row_mask:0xc bank_mask:0xf
	v_lshlrev_b32_e32 v172, 16, v34
	v_and_b32_e32 v173, 0xffff0000, v34
	v_lshlrev_b32_e32 v174, 16, v35
	v_and_b32_e32 v175, 0xffff0000, v35
	s_nop 0
	v_readlane_b32 s83, v84, 63
	s_nop 2
	v_fma_f32 v84, s83, v2, v3
	v_rsq_f32_e32 v84, v84
	s_nop 0
	v_mul_f32_e32 v68, v68, v84
	v_mul_f32_e32 v69, v69, v84
	v_mul_f32_e32 v70, v70, v84
	v_mul_f32_e32 v71, v71, v84
	v_mul_f32_e32 v72, v72, v84
	v_mul_f32_e32 v73, v73, v84
	v_mul_f32_e32 v74, v74, v84
	v_mul_f32_e32 v75, v75, v84
	v_mul_f32_e32 v76, v76, v84
	v_mul_f32_e32 v77, v77, v84
	v_mul_f32_e32 v78, v78, v84
	v_mul_f32_e32 v79, v79, v84
	v_mul_f32_e32 v80, v80, v84
	v_mul_f32_e32 v81, v81, v84
	v_mul_f32_e32 v82, v82, v84
	v_mul_f32_e32 v83, v83, v84
	v_fma_f32 v68, v68, v4, v160
	v_fma_f32 v69, v69, v5, v161
	v_fma_f32 v70, v70, v6, v162
	v_fma_f32 v71, v71, v7, v163
	v_fma_f32 v72, v72, v8, v164
	v_fma_f32 v73, v73, v9, v165
	v_fma_f32 v74, v74, v10, v166
	v_fma_f32 v75, v75, v11, v167
	v_fma_f32 v76, v76, v12, v168
	v_fma_f32 v77, v77, v13, v169
	v_fma_f32 v78, v78, v14, v170
	v_fma_f32 v79, v79, v15, v171
	v_fma_f32 v80, v80, v16, v172
	v_fma_f32 v81, v81, v17, v173
	v_fma_f32 v82, v82, v18, v174
	v_fma_f32 v83, v83, v19, v175
	v_mul_f32_e32 v86, v68, v68
	v_mul_f32_e32 v87, v72, v72
	v_mul_f32_e32 v88, v76, v76
	v_mul_f32_e32 v89, v80, v80
	v_fmac_f32_e32 v86, v69, v69
	v_fmac_f32_e32 v87, v73, v73
	v_fmac_f32_e32 v88, v77, v77
	v_fmac_f32_e32 v89, v81, v81
	v_fmac_f32_e32 v86, v70, v70
	v_fmac_f32_e32 v87, v74, v74
	v_fmac_f32_e32 v88, v78, v78
	v_fmac_f32_e32 v89, v82, v82
	v_fmac_f32_e32 v86, v71, v71
	v_fmac_f32_e32 v87, v75, v75
	v_fmac_f32_e32 v88, v79, v79
	v_fmac_f32_e32 v89, v83, v83
	v_add_f32_e32 v85, v86, v87
	v_add_f32_e32 v85, v85, v88
	v_add_f32_e32 v85, v85, v89
	v_cvt_pk_bf16_f32 v90, v68, v69
	v_cvt_pk_bf16_f32 v91, v70, v71
	v_add_f32_dpp v85, v85, v85 quad_perm:[1,0,3,2] row_mask:0xf bank_mask:0xf
	v_cvt_pk_bf16_f32 v92, v72, v73
	v_cvt_pk_bf16_f32 v93, v74, v75
	v_add_f32_dpp v85, v85, v85 quad_perm:[2,3,0,1] row_mask:0xf bank_mask:0xf
	v_cvt_pk_bf16_f32 v94, v76, v77
	v_cvt_pk_bf16_f32 v95, v78, v79
	v_add_f32_dpp v85, v85, v85 row_half_mirror row_mask:0xf bank_mask:0xf
	v_cvt_pk_bf16_f32 v96, v80, v81
	v_cvt_pk_bf16_f32 v97, v82, v83
	v_add_f32_dpp v85, v85, v85 row_mirror row_mask:0xf bank_mask:0xf
	s_nop 1
	v_add_f32_dpp v85, v85, v85 row_bcast:15 row_mask:0xa bank_mask:0xf
	s_nop 1
	v_add_f32_dpp v85, v85, v85 row_bcast:31 row_mask:0xc bank_mask:0xf
	global_store_dwordx2 v1, v[90:91], s[74:75] offset:0
	global_store_dwordx2 v1, v[92:93], s[74:75] offset:512
	global_store_dwordx2 v1, v[94:95], s[74:75] offset:1024
	global_store_dwordx2 v1, v[96:97], s[74:75] offset:1536
	v_readlane_b32 s84, v85, 63
	s_add_u32 s74, s74, 0x400000
	s_addc_u32 s75, s75, 0
	s_nop 0
	v_fma_f32 v85, s84, v2, v3
	v_rsq_f32_e32 v85, v85
	s_nop 0
	v_mul_f32_e32 v68, v68, v85
	v_mul_f32_e32 v69, v69, v85
	v_mul_f32_e32 v70, v70, v85
	v_mul_f32_e32 v71, v71, v85
	v_mul_f32_e32 v72, v72, v85
	v_mul_f32_e32 v73, v73, v85
	v_mul_f32_e32 v74, v74, v85
	v_mul_f32_e32 v75, v75, v85
	v_mul_f32_e32 v76, v76, v85
	v_mul_f32_e32 v77, v77, v85
	v_mul_f32_e32 v78, v78, v85
	v_mul_f32_e32 v79, v79, v85
	v_mul_f32_e32 v80, v80, v85
	v_mul_f32_e32 v81, v81, v85
	v_mul_f32_e32 v82, v82, v85
	v_mul_f32_e32 v83, v83, v85
	v_mul_f32_e32 v68, v68, v100
	v_mul_f32_e32 v69, v69, v101
	v_mul_f32_e32 v70, v70, v102
	v_mul_f32_e32 v71, v71, v103
	v_mul_f32_e32 v72, v72, v104
	v_mul_f32_e32 v73, v73, v105
	v_mul_f32_e32 v74, v74, v106
	v_mul_f32_e32 v75, v75, v107
	v_mul_f32_e32 v76, v76, v108
	v_mul_f32_e32 v77, v77, v109
	v_mul_f32_e32 v78, v78, v110
	v_mul_f32_e32 v79, v79, v111
	v_mul_f32_e32 v80, v80, v112
	v_mul_f32_e32 v81, v81, v113
	v_mul_f32_e32 v82, v82, v114
	v_mul_f32_e32 v83, v83, v115
	v_cvt_pk_bf16_f32 v176, v68, v69
	v_cvt_pk_bf16_f32 v177, v70, v71
	v_cvt_pk_bf16_f32 v178, v72, v73
	v_cvt_pk_bf16_f32 v179, v74, v75
	v_cvt_pk_bf16_f32 v180, v76, v77
	v_cvt_pk_bf16_f32 v181, v78, v79
	v_cvt_pk_bf16_f32 v182, v80, v81
	v_cvt_pk_bf16_f32 v183, v82, v83
	global_store_dwordx2 v1, v[176:177], s[76:77] offset:0
	global_store_dwordx2 v1, v[178:179], s[76:77] offset:512
	global_store_dwordx2 v1, v[180:181], s[76:77] offset:1024
	global_store_dwordx2 v1, v[182:183], s[76:77] offset:1536
	s_add_u32 s76, s76, 0x400000
	s_addc_u32 s77, s77, 0
	global_load_dwordx2 v[20:21], v1, s[70:71] offset:0
	global_load_dwordx2 v[22:23], v1, s[70:71] offset:512
	global_load_dwordx2 v[24:25], v1, s[70:71] offset:1024
	global_load_dwordx2 v[26:27], v1, s[70:71] offset:1536
	global_load_dwordx2 v[28:29], v1, s[72:73] offset:0
	global_load_dwordx2 v[30:31], v1, s[72:73] offset:512
	global_load_dwordx2 v[32:33], v1, s[72:73] offset:1024
	global_load_dwordx2 v[34:35], v1, s[72:73] offset:1536
	s_add_u32 s70, s70, 0x400000
	s_addc_u32 s71, s71, 0
	s_add_u32 s72, s72, 0x400000
	s_addc_u32 s73, s73, 0
	s_waitcnt vmcnt(32)
	v_lshlrev_b32_e32 v68, 16, v36
	v_and_b32_e32 v69, 0xffff0000, v36
	v_lshlrev_b32_e32 v70, 16, v37
	v_and_b32_e32 v71, 0xffff0000, v37
	v_lshlrev_b32_e32 v72, 16, v38
	v_and_b32_e32 v73, 0xffff0000, v38
	v_lshlrev_b32_e32 v74, 16, v39
	v_and_b32_e32 v75, 0xffff0000, v39
	v_lshlrev_b32_e32 v76, 16, v40
	v_and_b32_e32 v77, 0xffff0000, v40
	v_lshlrev_b32_e32 v78, 16, v41
	v_and_b32_e32 v79, 0xffff0000, v41
	v_lshlrev_b32_e32 v80, 16, v42
	v_and_b32_e32 v81, 0xffff0000, v42
	v_lshlrev_b32_e32 v82, 16, v43
	v_and_b32_e32 v83, 0xffff0000, v43
	v_mul_f32_e32 v86, v68, v68
	v_mul_f32_e32 v87, v72, v72
	v_mul_f32_e32 v88, v76, v76
	v_mul_f32_e32 v89, v80, v80
	v_fmac_f32_e32 v86, v69, v69
	v_fmac_f32_e32 v87, v73, v73
	v_fmac_f32_e32 v88, v77, v77
	v_fmac_f32_e32 v89, v81, v81
	v_fmac_f32_e32 v86, v70, v70
	v_fmac_f32_e32 v87, v74, v74
	v_fmac_f32_e32 v88, v78, v78
	v_fmac_f32_e32 v89, v82, v82
	v_fmac_f32_e32 v86, v71, v71
	v_fmac_f32_e32 v87, v75, v75
	v_fmac_f32_e32 v88, v79, v79
	v_fmac_f32_e32 v89, v83, v83
	v_add_f32_e32 v84, v86, v87
	v_add_f32_e32 v84, v84, v88
	v_add_f32_e32 v84, v84, v89
	v_lshlrev_b32_e32 v160, 16, v44
	v_and_b32_e32 v161, 0xffff0000, v44
	v_add_f32_dpp v84, v84, v84 quad_perm:[1,0,3,2] row_mask:0xf bank_mask:0xf
	v_lshlrev_b32_e32 v162, 16, v45
	v_and_b32_e32 v163, 0xffff0000, v45
	v_add_f32_dpp v84, v84, v84 quad_perm:[2,3,0,1] row_mask:0xf bank_mask:0xf
	v_lshlrev_b32_e32 v164, 16, v46
	v_and_b32_e32 v165, 0xffff0000, v46
	v_add_f32_dpp v84, v84, v84 row_half_mirror row_mask:0xf bank_mask:0xf
	v_lshlrev_b32_e32 v166, 16, v47
	v_and_b32_e32 v167, 0xffff0000, v47
	v_add_f32_dpp v84, v84, v84 row_mirror row_mask:0xf bank_mask:0xf
	v_lshlrev_b32_e32 v168, 16, v48
	v_and_b32_e32 v169, 0xffff0000, v48
	v_add_f32_dpp v84, v84, v84 row_bcast:15 row_mask:0xa bank_mask:0xf
	v_lshlrev_b32_e32 v170, 16, v49
	v_and_b32_e32 v171, 0xffff0000, v49
	v_add_f32_dpp v84, v84, v84 row_bcast:31 row_mask:0xc bank_mask:0xf
	v_lshlrev_b32_e32 v172, 16, v50
	v_and_b32_e32 v173, 0xffff0000, v50
	v_lshlrev_b32_e32 v174, 16, v51
	v_and_b32_e32 v175, 0xffff0000, v51
	s_nop 0
	v_readlane_b32 s83, v84, 63
	s_nop 2
	v_fma_f32 v84, s83, v2, v3
	v_rsq_f32_e32 v84, v84
	s_nop 0
	v_mul_f32_e32 v68, v68, v84
	v_mul_f32_e32 v69, v69, v84
	v_mul_f32_e32 v70, v70, v84
	v_mul_f32_e32 v71, v71, v84
	v_mul_f32_e32 v72, v72, v84
	v_mul_f32_e32 v73, v73, v84
	v_mul_f32_e32 v74, v74, v84
	v_mul_f32_e32 v75, v75, v84
	v_mul_f32_e32 v76, v76, v84
	v_mul_f32_e32 v77, v77, v84
	v_mul_f32_e32 v78, v78, v84
	v_mul_f32_e32 v79, v79, v84
	v_mul_f32_e32 v80, v80, v84
	v_mul_f32_e32 v81, v81, v84
	v_mul_f32_e32 v82, v82, v84
	v_mul_f32_e32 v83, v83, v84
	v_fma_f32 v68, v68, v4, v160
	v_fma_f32 v69, v69, v5, v161
	v_fma_f32 v70, v70, v6, v162
	v_fma_f32 v71, v71, v7, v163
	v_fma_f32 v72, v72, v8, v164
	v_fma_f32 v73, v73, v9, v165
	v_fma_f32 v74, v74, v10, v166
	v_fma_f32 v75, v75, v11, v167
	v_fma_f32 v76, v76, v12, v168
	v_fma_f32 v77, v77, v13, v169
	v_fma_f32 v78, v78, v14, v170
	v_fma_f32 v79, v79, v15, v171
	v_fma_f32 v80, v80, v16, v172
	v_fma_f32 v81, v81, v17, v173
	v_fma_f32 v82, v82, v18, v174
	v_fma_f32 v83, v83, v19, v175
	v_mul_f32_e32 v86, v68, v68
	v_mul_f32_e32 v87, v72, v72
	v_mul_f32_e32 v88, v76, v76
	v_mul_f32_e32 v89, v80, v80
	v_fmac_f32_e32 v86, v69, v69
	v_fmac_f32_e32 v87, v73, v73
	v_fmac_f32_e32 v88, v77, v77
	v_fmac_f32_e32 v89, v81, v81
	v_fmac_f32_e32 v86, v70, v70
	v_fmac_f32_e32 v87, v74, v74
	v_fmac_f32_e32 v88, v78, v78
	v_fmac_f32_e32 v89, v82, v82
	v_fmac_f32_e32 v86, v71, v71
	v_fmac_f32_e32 v87, v75, v75
	v_fmac_f32_e32 v88, v79, v79
	v_fmac_f32_e32 v89, v83, v83
	v_add_f32_e32 v85, v86, v87
	v_add_f32_e32 v85, v85, v88
	v_add_f32_e32 v85, v85, v89
	v_cvt_pk_bf16_f32 v90, v68, v69
	v_cvt_pk_bf16_f32 v91, v70, v71
	v_add_f32_dpp v85, v85, v85 quad_perm:[1,0,3,2] row_mask:0xf bank_mask:0xf
	v_cvt_pk_bf16_f32 v92, v72, v73
	v_cvt_pk_bf16_f32 v93, v74, v75
	v_add_f32_dpp v85, v85, v85 quad_perm:[2,3,0,1] row_mask:0xf bank_mask:0xf
	v_cvt_pk_bf16_f32 v94, v76, v77
	v_cvt_pk_bf16_f32 v95, v78, v79
	v_add_f32_dpp v85, v85, v85 row_half_mirror row_mask:0xf bank_mask:0xf
	v_cvt_pk_bf16_f32 v96, v80, v81
	v_cvt_pk_bf16_f32 v97, v82, v83
	v_add_f32_dpp v85, v85, v85 row_mirror row_mask:0xf bank_mask:0xf
	s_nop 1
	v_add_f32_dpp v85, v85, v85 row_bcast:15 row_mask:0xa bank_mask:0xf
	s_nop 1
	v_add_f32_dpp v85, v85, v85 row_bcast:31 row_mask:0xc bank_mask:0xf
	global_store_dwordx2 v1, v[90:91], s[74:75] offset:0
	global_store_dwordx2 v1, v[92:93], s[74:75] offset:512
	global_store_dwordx2 v1, v[94:95], s[74:75] offset:1024
	global_store_dwordx2 v1, v[96:97], s[74:75] offset:1536
	v_readlane_b32 s84, v85, 63
	s_add_u32 s74, s74, 0x400000
	s_addc_u32 s75, s75, 0
	s_nop 0
	v_fma_f32 v85, s84, v2, v3
	v_rsq_f32_e32 v85, v85
	s_nop 0
	v_mul_f32_e32 v68, v68, v85
	v_mul_f32_e32 v69, v69, v85
	v_mul_f32_e32 v70, v70, v85
	v_mul_f32_e32 v71, v71, v85
	v_mul_f32_e32 v72, v72, v85
	v_mul_f32_e32 v73, v73, v85
	v_mul_f32_e32 v74, v74, v85
	v_mul_f32_e32 v75, v75, v85
	v_mul_f32_e32 v76, v76, v85
	v_mul_f32_e32 v77, v77, v85
	v_mul_f32_e32 v78, v78, v85
	v_mul_f32_e32 v79, v79, v85
	v_mul_f32_e32 v80, v80, v85
	v_mul_f32_e32 v81, v81, v85
	v_mul_f32_e32 v82, v82, v85
	v_mul_f32_e32 v83, v83, v85
	v_mul_f32_e32 v68, v68, v100
	v_mul_f32_e32 v69, v69, v101
	v_mul_f32_e32 v70, v70, v102
	v_mul_f32_e32 v71, v71, v103
	v_mul_f32_e32 v72, v72, v104
	v_mul_f32_e32 v73, v73, v105
	v_mul_f32_e32 v74, v74, v106
	v_mul_f32_e32 v75, v75, v107
	v_mul_f32_e32 v76, v76, v108
	v_mul_f32_e32 v77, v77, v109
	v_mul_f32_e32 v78, v78, v110
	v_mul_f32_e32 v79, v79, v111
	v_mul_f32_e32 v80, v80, v112
	v_mul_f32_e32 v81, v81, v113
	v_mul_f32_e32 v82, v82, v114
	v_mul_f32_e32 v83, v83, v115
	v_cvt_pk_bf16_f32 v176, v68, v69
	v_cvt_pk_bf16_f32 v177, v70, v71
	v_cvt_pk_bf16_f32 v178, v72, v73
	v_cvt_pk_bf16_f32 v179, v74, v75
	v_cvt_pk_bf16_f32 v180, v76, v77
	v_cvt_pk_bf16_f32 v181, v78, v79
	v_cvt_pk_bf16_f32 v182, v80, v81
	v_cvt_pk_bf16_f32 v183, v82, v83
	global_store_dwordx2 v1, v[176:177], s[76:77] offset:0
	global_store_dwordx2 v1, v[178:179], s[76:77] offset:512
	global_store_dwordx2 v1, v[180:181], s[76:77] offset:1024
	global_store_dwordx2 v1, v[182:183], s[76:77] offset:1536
	s_add_u32 s76, s76, 0x400000
	s_addc_u32 s77, s77, 0
	global_load_dwordx2 v[36:37], v1, s[70:71] offset:0
	global_load_dwordx2 v[38:39], v1, s[70:71] offset:512
	global_load_dwordx2 v[40:41], v1, s[70:71] offset:1024
	global_load_dwordx2 v[42:43], v1, s[70:71] offset:1536
	global_load_dwordx2 v[44:45], v1, s[72:73] offset:0
	global_load_dwordx2 v[46:47], v1, s[72:73] offset:512
	global_load_dwordx2 v[48:49], v1, s[72:73] offset:1024
	global_load_dwordx2 v[50:51], v1, s[72:73] offset:1536
	s_add_u32 s70, s70, 0x400000
	s_addc_u32 s71, s71, 0
	s_add_u32 s72, s72, 0x400000
	s_addc_u32 s73, s73, 0
	s_waitcnt vmcnt(40)
	v_lshlrev_b32_e32 v68, 16, v52
	v_and_b32_e32 v69, 0xffff0000, v52
	v_lshlrev_b32_e32 v70, 16, v53
	v_and_b32_e32 v71, 0xffff0000, v53
	v_lshlrev_b32_e32 v72, 16, v54
	v_and_b32_e32 v73, 0xffff0000, v54
	v_lshlrev_b32_e32 v74, 16, v55
	v_and_b32_e32 v75, 0xffff0000, v55
	v_lshlrev_b32_e32 v76, 16, v56
	v_and_b32_e32 v77, 0xffff0000, v56
	v_lshlrev_b32_e32 v78, 16, v57
	v_and_b32_e32 v79, 0xffff0000, v57
	v_lshlrev_b32_e32 v80, 16, v58
	v_and_b32_e32 v81, 0xffff0000, v58
	v_lshlrev_b32_e32 v82, 16, v59
	v_and_b32_e32 v83, 0xffff0000, v59
	v_mul_f32_e32 v86, v68, v68
	v_mul_f32_e32 v87, v72, v72
	v_mul_f32_e32 v88, v76, v76
	v_mul_f32_e32 v89, v80, v80
	v_fmac_f32_e32 v86, v69, v69
	v_fmac_f32_e32 v87, v73, v73
	v_fmac_f32_e32 v88, v77, v77
	v_fmac_f32_e32 v89, v81, v81
	v_fmac_f32_e32 v86, v70, v70
	v_fmac_f32_e32 v87, v74, v74
	v_fmac_f32_e32 v88, v78, v78
	v_fmac_f32_e32 v89, v82, v82
	v_fmac_f32_e32 v86, v71, v71
	v_fmac_f32_e32 v87, v75, v75
	v_fmac_f32_e32 v88, v79, v79
	v_fmac_f32_e32 v89, v83, v83
	v_add_f32_e32 v84, v86, v87
	v_add_f32_e32 v84, v84, v88
	v_add_f32_e32 v84, v84, v89
	v_lshlrev_b32_e32 v160, 16, v60
	v_and_b32_e32 v161, 0xffff0000, v60
	v_add_f32_dpp v84, v84, v84 quad_perm:[1,0,3,2] row_mask:0xf bank_mask:0xf
	v_lshlrev_b32_e32 v162, 16, v61
	v_and_b32_e32 v163, 0xffff0000, v61
	v_add_f32_dpp v84, v84, v84 quad_perm:[2,3,0,1] row_mask:0xf bank_mask:0xf
	v_lshlrev_b32_e32 v164, 16, v62
	v_and_b32_e32 v165, 0xffff0000, v62
	v_add_f32_dpp v84, v84, v84 row_half_mirror row_mask:0xf bank_mask:0xf
	v_lshlrev_b32_e32 v166, 16, v63
	v_and_b32_e32 v167, 0xffff0000, v63
	v_add_f32_dpp v84, v84, v84 row_mirror row_mask:0xf bank_mask:0xf
	v_lshlrev_b32_e32 v168, 16, v64
	v_and_b32_e32 v169, 0xffff0000, v64
	v_add_f32_dpp v84, v84, v84 row_bcast:15 row_mask:0xa bank_mask:0xf
	v_lshlrev_b32_e32 v170, 16, v65
	v_and_b32_e32 v171, 0xffff0000, v65
	v_add_f32_dpp v84, v84, v84 row_bcast:31 row_mask:0xc bank_mask:0xf
	v_lshlrev_b32_e32 v172, 16, v66
	v_and_b32_e32 v173, 0xffff0000, v66
	v_lshlrev_b32_e32 v174, 16, v67
	v_and_b32_e32 v175, 0xffff0000, v67
	s_nop 0
	v_readlane_b32 s83, v84, 63
	s_nop 2
	v_fma_f32 v84, s83, v2, v3
	v_rsq_f32_e32 v84, v84
	s_nop 0
	v_mul_f32_e32 v68, v68, v84
	v_mul_f32_e32 v69, v69, v84
	v_mul_f32_e32 v70, v70, v84
	v_mul_f32_e32 v71, v71, v84
	v_mul_f32_e32 v72, v72, v84
	v_mul_f32_e32 v73, v73, v84
	v_mul_f32_e32 v74, v74, v84
	v_mul_f32_e32 v75, v75, v84
	v_mul_f32_e32 v76, v76, v84
	v_mul_f32_e32 v77, v77, v84
	v_mul_f32_e32 v78, v78, v84
	v_mul_f32_e32 v79, v79, v84
	v_mul_f32_e32 v80, v80, v84
	v_mul_f32_e32 v81, v81, v84
	v_mul_f32_e32 v82, v82, v84
	v_mul_f32_e32 v83, v83, v84
	v_fma_f32 v68, v68, v4, v160
	v_fma_f32 v69, v69, v5, v161
	v_fma_f32 v70, v70, v6, v162
	v_fma_f32 v71, v71, v7, v163
	v_fma_f32 v72, v72, v8, v164
	v_fma_f32 v73, v73, v9, v165
	v_fma_f32 v74, v74, v10, v166
	v_fma_f32 v75, v75, v11, v167
	v_fma_f32 v76, v76, v12, v168
	v_fma_f32 v77, v77, v13, v169
	v_fma_f32 v78, v78, v14, v170
	v_fma_f32 v79, v79, v15, v171
	v_fma_f32 v80, v80, v16, v172
	v_fma_f32 v81, v81, v17, v173
	v_fma_f32 v82, v82, v18, v174
	v_fma_f32 v83, v83, v19, v175
	v_mul_f32_e32 v86, v68, v68
	v_mul_f32_e32 v87, v72, v72
	v_mul_f32_e32 v88, v76, v76
	v_mul_f32_e32 v89, v80, v80
	v_fmac_f32_e32 v86, v69, v69
	v_fmac_f32_e32 v87, v73, v73
	v_fmac_f32_e32 v88, v77, v77
	v_fmac_f32_e32 v89, v81, v81
	v_fmac_f32_e32 v86, v70, v70
	v_fmac_f32_e32 v87, v74, v74
	v_fmac_f32_e32 v88, v78, v78
	v_fmac_f32_e32 v89, v82, v82
	v_fmac_f32_e32 v86, v71, v71
	v_fmac_f32_e32 v87, v75, v75
	v_fmac_f32_e32 v88, v79, v79
	v_fmac_f32_e32 v89, v83, v83
	v_add_f32_e32 v85, v86, v87
	v_add_f32_e32 v85, v85, v88
	v_add_f32_e32 v85, v85, v89
	v_cvt_pk_bf16_f32 v90, v68, v69
	v_cvt_pk_bf16_f32 v91, v70, v71
	v_add_f32_dpp v85, v85, v85 quad_perm:[1,0,3,2] row_mask:0xf bank_mask:0xf
	v_cvt_pk_bf16_f32 v92, v72, v73
	v_cvt_pk_bf16_f32 v93, v74, v75
	v_add_f32_dpp v85, v85, v85 quad_perm:[2,3,0,1] row_mask:0xf bank_mask:0xf
	v_cvt_pk_bf16_f32 v94, v76, v77
	v_cvt_pk_bf16_f32 v95, v78, v79
	v_add_f32_dpp v85, v85, v85 row_half_mirror row_mask:0xf bank_mask:0xf
	v_cvt_pk_bf16_f32 v96, v80, v81
	v_cvt_pk_bf16_f32 v97, v82, v83
	v_add_f32_dpp v85, v85, v85 row_mirror row_mask:0xf bank_mask:0xf
	s_nop 1
	v_add_f32_dpp v85, v85, v85 row_bcast:15 row_mask:0xa bank_mask:0xf
	s_nop 1
	v_add_f32_dpp v85, v85, v85 row_bcast:31 row_mask:0xc bank_mask:0xf
	global_store_dwordx2 v1, v[90:91], s[74:75] offset:0
	global_store_dwordx2 v1, v[92:93], s[74:75] offset:512
	global_store_dwordx2 v1, v[94:95], s[74:75] offset:1024
	global_store_dwordx2 v1, v[96:97], s[74:75] offset:1536
	v_readlane_b32 s84, v85, 63
	s_add_u32 s74, s74, 0x400000
	s_addc_u32 s75, s75, 0
	s_nop 0
	v_fma_f32 v85, s84, v2, v3
	v_rsq_f32_e32 v85, v85
	s_nop 0
	v_mul_f32_e32 v68, v68, v85
	v_mul_f32_e32 v69, v69, v85
	v_mul_f32_e32 v70, v70, v85
	v_mul_f32_e32 v71, v71, v85
	v_mul_f32_e32 v72, v72, v85
	v_mul_f32_e32 v73, v73, v85
	v_mul_f32_e32 v74, v74, v85
	v_mul_f32_e32 v75, v75, v85
	v_mul_f32_e32 v76, v76, v85
	v_mul_f32_e32 v77, v77, v85
	v_mul_f32_e32 v78, v78, v85
	v_mul_f32_e32 v79, v79, v85
	v_mul_f32_e32 v80, v80, v85
	v_mul_f32_e32 v81, v81, v85
	v_mul_f32_e32 v82, v82, v85
	v_mul_f32_e32 v83, v83, v85
	v_mul_f32_e32 v68, v68, v100
	v_mul_f32_e32 v69, v69, v101
	v_mul_f32_e32 v70, v70, v102
	v_mul_f32_e32 v71, v71, v103
	v_mul_f32_e32 v72, v72, v104
	v_mul_f32_e32 v73, v73, v105
	v_mul_f32_e32 v74, v74, v106
	v_mul_f32_e32 v75, v75, v107
	v_mul_f32_e32 v76, v76, v108
	v_mul_f32_e32 v77, v77, v109
	v_mul_f32_e32 v78, v78, v110
	v_mul_f32_e32 v79, v79, v111
	v_mul_f32_e32 v80, v80, v112
	v_mul_f32_e32 v81, v81, v113
	v_mul_f32_e32 v82, v82, v114
	v_mul_f32_e32 v83, v83, v115
	v_cvt_pk_bf16_f32 v176, v68, v69
	v_cvt_pk_bf16_f32 v177, v70, v71
	v_cvt_pk_bf16_f32 v178, v72, v73
	v_cvt_pk_bf16_f32 v179, v74, v75
	v_cvt_pk_bf16_f32 v180, v76, v77
	v_cvt_pk_bf16_f32 v181, v78, v79
	v_cvt_pk_bf16_f32 v182, v80, v81
	v_cvt_pk_bf16_f32 v183, v82, v83
	global_store_dwordx2 v1, v[176:177], s[76:77] offset:0
	global_store_dwordx2 v1, v[178:179], s[76:77] offset:512
	global_store_dwordx2 v1, v[180:181], s[76:77] offset:1024
	global_store_dwordx2 v1, v[182:183], s[76:77] offset:1536
	s_add_u32 s76, s76, 0x400000
	s_addc_u32 s77, s77, 0
	global_load_dwordx2 v[52:53], v1, s[70:71] offset:0
	global_load_dwordx2 v[54:55], v1, s[70:71] offset:512
	global_load_dwordx2 v[56:57], v1, s[70:71] offset:1024
	global_load_dwordx2 v[58:59], v1, s[70:71] offset:1536
	global_load_dwordx2 v[60:61], v1, s[72:73] offset:0
	global_load_dwordx2 v[62:63], v1, s[72:73] offset:512
	global_load_dwordx2 v[64:65], v1, s[72:73] offset:1024
	global_load_dwordx2 v[66:67], v1, s[72:73] offset:1536
	s_add_u32 s70, s70, 0x400000
	s_addc_u32 s71, s71, 0
	s_add_u32 s72, s72, 0x400000
	s_addc_u32 s73, s73, 0
	s_waitcnt vmcnt(48)
	v_lshlrev_b32_e32 v68, 16, v184
	v_and_b32_e32 v69, 0xffff0000, v184
	v_lshlrev_b32_e32 v70, 16, v185
	v_and_b32_e32 v71, 0xffff0000, v185
	v_lshlrev_b32_e32 v72, 16, v186
	v_and_b32_e32 v73, 0xffff0000, v186
	v_lshlrev_b32_e32 v74, 16, v187
	v_and_b32_e32 v75, 0xffff0000, v187
	v_lshlrev_b32_e32 v76, 16, v188
	v_and_b32_e32 v77, 0xffff0000, v188
	v_lshlrev_b32_e32 v78, 16, v189
	v_and_b32_e32 v79, 0xffff0000, v189
	v_lshlrev_b32_e32 v80, 16, v190
	v_and_b32_e32 v81, 0xffff0000, v190
	v_lshlrev_b32_e32 v82, 16, v191
	v_and_b32_e32 v83, 0xffff0000, v191
	v_mul_f32_e32 v86, v68, v68
	v_mul_f32_e32 v87, v72, v72
	v_mul_f32_e32 v88, v76, v76
	v_mul_f32_e32 v89, v80, v80
	v_fmac_f32_e32 v86, v69, v69
	v_fmac_f32_e32 v87, v73, v73
	v_fmac_f32_e32 v88, v77, v77
	v_fmac_f32_e32 v89, v81, v81
	v_fmac_f32_e32 v86, v70, v70
	v_fmac_f32_e32 v87, v74, v74
	v_fmac_f32_e32 v88, v78, v78
	v_fmac_f32_e32 v89, v82, v82
	v_fmac_f32_e32 v86, v71, v71
	v_fmac_f32_e32 v87, v75, v75
	v_fmac_f32_e32 v88, v79, v79
	v_fmac_f32_e32 v89, v83, v83
	v_add_f32_e32 v84, v86, v87
	v_add_f32_e32 v84, v84, v88
	v_add_f32_e32 v84, v84, v89
	v_lshlrev_b32_e32 v160, 16, v192
	v_and_b32_e32 v161, 0xffff0000, v192
	v_add_f32_dpp v84, v84, v84 quad_perm:[1,0,3,2] row_mask:0xf bank_mask:0xf
	v_lshlrev_b32_e32 v162, 16, v193
	v_and_b32_e32 v163, 0xffff0000, v193
	v_add_f32_dpp v84, v84, v84 quad_perm:[2,3,0,1] row_mask:0xf bank_mask:0xf
	v_lshlrev_b32_e32 v164, 16, v194
	v_and_b32_e32 v165, 0xffff0000, v194
	v_add_f32_dpp v84, v84, v84 row_half_mirror row_mask:0xf bank_mask:0xf
	v_lshlrev_b32_e32 v166, 16, v195
	v_and_b32_e32 v167, 0xffff0000, v195
	v_add_f32_dpp v84, v84, v84 row_mirror row_mask:0xf bank_mask:0xf
	v_lshlrev_b32_e32 v168, 16, v196
	v_and_b32_e32 v169, 0xffff0000, v196
	v_add_f32_dpp v84, v84, v84 row_bcast:15 row_mask:0xa bank_mask:0xf
	v_lshlrev_b32_e32 v170, 16, v197
	v_and_b32_e32 v171, 0xffff0000, v197
	v_add_f32_dpp v84, v84, v84 row_bcast:31 row_mask:0xc bank_mask:0xf
	v_lshlrev_b32_e32 v172, 16, v198
	v_and_b32_e32 v173, 0xffff0000, v198
	v_lshlrev_b32_e32 v174, 16, v199
	v_and_b32_e32 v175, 0xffff0000, v199
	s_nop 0
	v_readlane_b32 s83, v84, 63
	s_nop 2
	v_fma_f32 v84, s83, v2, v3
	v_rsq_f32_e32 v84, v84
	s_nop 0
	v_mul_f32_e32 v68, v68, v84
	v_mul_f32_e32 v69, v69, v84
	v_mul_f32_e32 v70, v70, v84
	v_mul_f32_e32 v71, v71, v84
	v_mul_f32_e32 v72, v72, v84
	v_mul_f32_e32 v73, v73, v84
	v_mul_f32_e32 v74, v74, v84
	v_mul_f32_e32 v75, v75, v84
	v_mul_f32_e32 v76, v76, v84
	v_mul_f32_e32 v77, v77, v84
	v_mul_f32_e32 v78, v78, v84
	v_mul_f32_e32 v79, v79, v84
	v_mul_f32_e32 v80, v80, v84
	v_mul_f32_e32 v81, v81, v84
	v_mul_f32_e32 v82, v82, v84
	v_mul_f32_e32 v83, v83, v84
	v_fma_f32 v68, v68, v4, v160
	v_fma_f32 v69, v69, v5, v161
	v_fma_f32 v70, v70, v6, v162
	v_fma_f32 v71, v71, v7, v163
	v_fma_f32 v72, v72, v8, v164
	v_fma_f32 v73, v73, v9, v165
	v_fma_f32 v74, v74, v10, v166
	v_fma_f32 v75, v75, v11, v167
	v_fma_f32 v76, v76, v12, v168
	v_fma_f32 v77, v77, v13, v169
	v_fma_f32 v78, v78, v14, v170
	v_fma_f32 v79, v79, v15, v171
	v_fma_f32 v80, v80, v16, v172
	v_fma_f32 v81, v81, v17, v173
	v_fma_f32 v82, v82, v18, v174
	v_fma_f32 v83, v83, v19, v175
	v_mul_f32_e32 v86, v68, v68
	v_mul_f32_e32 v87, v72, v72
	v_mul_f32_e32 v88, v76, v76
	v_mul_f32_e32 v89, v80, v80
	v_fmac_f32_e32 v86, v69, v69
	v_fmac_f32_e32 v87, v73, v73
	v_fmac_f32_e32 v88, v77, v77
	v_fmac_f32_e32 v89, v81, v81
	v_fmac_f32_e32 v86, v70, v70
	v_fmac_f32_e32 v87, v74, v74
	v_fmac_f32_e32 v88, v78, v78
	v_fmac_f32_e32 v89, v82, v82
	v_fmac_f32_e32 v86, v71, v71
	v_fmac_f32_e32 v87, v75, v75
	v_fmac_f32_e32 v88, v79, v79
	v_fmac_f32_e32 v89, v83, v83
	v_add_f32_e32 v85, v86, v87
	v_add_f32_e32 v85, v85, v88
	v_add_f32_e32 v85, v85, v89
	v_cvt_pk_bf16_f32 v90, v68, v69
	v_cvt_pk_bf16_f32 v91, v70, v71
	v_add_f32_dpp v85, v85, v85 quad_perm:[1,0,3,2] row_mask:0xf bank_mask:0xf
	v_cvt_pk_bf16_f32 v92, v72, v73
	v_cvt_pk_bf16_f32 v93, v74, v75
	v_add_f32_dpp v85, v85, v85 quad_perm:[2,3,0,1] row_mask:0xf bank_mask:0xf
	v_cvt_pk_bf16_f32 v94, v76, v77
	v_cvt_pk_bf16_f32 v95, v78, v79
	v_add_f32_dpp v85, v85, v85 row_half_mirror row_mask:0xf bank_mask:0xf
	v_cvt_pk_bf16_f32 v96, v80, v81
	v_cvt_pk_bf16_f32 v97, v82, v83
	v_add_f32_dpp v85, v85, v85 row_mirror row_mask:0xf bank_mask:0xf
	s_nop 1
	v_add_f32_dpp v85, v85, v85 row_bcast:15 row_mask:0xa bank_mask:0xf
	s_nop 1
	v_add_f32_dpp v85, v85, v85 row_bcast:31 row_mask:0xc bank_mask:0xf
	global_store_dwordx2 v1, v[90:91], s[74:75] offset:0
	global_store_dwordx2 v1, v[92:93], s[74:75] offset:512
	global_store_dwordx2 v1, v[94:95], s[74:75] offset:1024
	global_store_dwordx2 v1, v[96:97], s[74:75] offset:1536
	v_readlane_b32 s84, v85, 63
	s_add_u32 s74, s74, 0x400000
	s_addc_u32 s75, s75, 0
	s_nop 0
	v_fma_f32 v85, s84, v2, v3
	v_rsq_f32_e32 v85, v85
	s_nop 0
	v_mul_f32_e32 v68, v68, v85
	v_mul_f32_e32 v69, v69, v85
	v_mul_f32_e32 v70, v70, v85
	v_mul_f32_e32 v71, v71, v85
	v_mul_f32_e32 v72, v72, v85
	v_mul_f32_e32 v73, v73, v85
	v_mul_f32_e32 v74, v74, v85
	v_mul_f32_e32 v75, v75, v85
	v_mul_f32_e32 v76, v76, v85
	v_mul_f32_e32 v77, v77, v85
	v_mul_f32_e32 v78, v78, v85
	v_mul_f32_e32 v79, v79, v85
	v_mul_f32_e32 v80, v80, v85
	v_mul_f32_e32 v81, v81, v85
	v_mul_f32_e32 v82, v82, v85
	v_mul_f32_e32 v83, v83, v85
	v_mul_f32_e32 v68, v68, v100
	v_mul_f32_e32 v69, v69, v101
	v_mul_f32_e32 v70, v70, v102
	v_mul_f32_e32 v71, v71, v103
	v_mul_f32_e32 v72, v72, v104
	v_mul_f32_e32 v73, v73, v105
	v_mul_f32_e32 v74, v74, v106
	v_mul_f32_e32 v75, v75, v107
	v_mul_f32_e32 v76, v76, v108
	v_mul_f32_e32 v77, v77, v109
	v_mul_f32_e32 v78, v78, v110
	v_mul_f32_e32 v79, v79, v111
	v_mul_f32_e32 v80, v80, v112
	v_mul_f32_e32 v81, v81, v113
	v_mul_f32_e32 v82, v82, v114
	v_mul_f32_e32 v83, v83, v115
	v_cvt_pk_bf16_f32 v176, v68, v69
	v_cvt_pk_bf16_f32 v177, v70, v71
	v_cvt_pk_bf16_f32 v178, v72, v73
	v_cvt_pk_bf16_f32 v179, v74, v75
	v_cvt_pk_bf16_f32 v180, v76, v77
	v_cvt_pk_bf16_f32 v181, v78, v79
	v_cvt_pk_bf16_f32 v182, v80, v81
	v_cvt_pk_bf16_f32 v183, v82, v83
	global_store_dwordx2 v1, v[176:177], s[76:77] offset:0
	global_store_dwordx2 v1, v[178:179], s[76:77] offset:512
	global_store_dwordx2 v1, v[180:181], s[76:77] offset:1024
	global_store_dwordx2 v1, v[182:183], s[76:77] offset:1536
	s_add_u32 s76, s76, 0x400000
	s_addc_u32 s77, s77, 0
	global_load_dwordx2 v[184:185], v1, s[70:71] offset:0
	global_load_dwordx2 v[186:187], v1, s[70:71] offset:512
	global_load_dwordx2 v[188:189], v1, s[70:71] offset:1024
	global_load_dwordx2 v[190:191], v1, s[70:71] offset:1536
	global_load_dwordx2 v[192:193], v1, s[72:73] offset:0
	global_load_dwordx2 v[194:195], v1, s[72:73] offset:512
	global_load_dwordx2 v[196:197], v1, s[72:73] offset:1024
	global_load_dwordx2 v[198:199], v1, s[72:73] offset:1536
	s_add_u32 s70, s70, 0x400000
	s_addc_u32 s71, s71, 0
	s_add_u32 s72, s72, 0x400000
	s_addc_u32 s73, s73, 0
	s_waitcnt vmcnt(48)
	v_lshlrev_b32_e32 v68, 16, v20
	v_and_b32_e32 v69, 0xffff0000, v20
	v_lshlrev_b32_e32 v70, 16, v21
	v_and_b32_e32 v71, 0xffff0000, v21
	v_lshlrev_b32_e32 v72, 16, v22
	v_and_b32_e32 v73, 0xffff0000, v22
	v_lshlrev_b32_e32 v74, 16, v23
	v_and_b32_e32 v75, 0xffff0000, v23
	v_lshlrev_b32_e32 v76, 16, v24
	v_and_b32_e32 v77, 0xffff0000, v24
	v_lshlrev_b32_e32 v78, 16, v25
	v_and_b32_e32 v79, 0xffff0000, v25
	v_lshlrev_b32_e32 v80, 16, v26
	v_and_b32_e32 v81, 0xffff0000, v26
	v_lshlrev_b32_e32 v82, 16, v27
	v_and_b32_e32 v83, 0xffff0000, v27
	v_mul_f32_e32 v86, v68, v68
	v_mul_f32_e32 v87, v72, v72
	v_mul_f32_e32 v88, v76, v76
	v_mul_f32_e32 v89, v80, v80
	v_fmac_f32_e32 v86, v69, v69
	v_fmac_f32_e32 v87, v73, v73
	v_fmac_f32_e32 v88, v77, v77
	v_fmac_f32_e32 v89, v81, v81
	v_fmac_f32_e32 v86, v70, v70
	v_fmac_f32_e32 v87, v74, v74
	v_fmac_f32_e32 v88, v78, v78
	v_fmac_f32_e32 v89, v82, v82
	v_fmac_f32_e32 v86, v71, v71
	v_fmac_f32_e32 v87, v75, v75
	v_fmac_f32_e32 v88, v79, v79
	v_fmac_f32_e32 v89, v83, v83
	v_add_f32_e32 v84, v86, v87
	v_add_f32_e32 v84, v84, v88
	v_add_f32_e32 v84, v84, v89
	v_lshlrev_b32_e32 v160, 16, v28
	v_and_b32_e32 v161, 0xffff0000, v28
	v_add_f32_dpp v84, v84, v84 quad_perm:[1,0,3,2] row_mask:0xf bank_mask:0xf
	v_lshlrev_b32_e32 v162, 16, v29
	v_and_b32_e32 v163, 0xffff0000, v29
	v_add_f32_dpp v84, v84, v84 quad_perm:[2,3,0,1] row_mask:0xf bank_mask:0xf
	v_lshlrev_b32_e32 v164, 16, v30
	v_and_b32_e32 v165, 0xffff0000, v30
	v_add_f32_dpp v84, v84, v84 row_half_mirror row_mask:0xf bank_mask:0xf
	v_lshlrev_b32_e32 v166, 16, v31
	v_and_b32_e32 v167, 0xffff0000, v31
	v_add_f32_dpp v84, v84, v84 row_mirror row_mask:0xf bank_mask:0xf
	v_lshlrev_b32_e32 v168, 16, v32
	v_and_b32_e32 v169, 0xffff0000, v32
	v_add_f32_dpp v84, v84, v84 row_bcast:15 row_mask:0xa bank_mask:0xf
	v_lshlrev_b32_e32 v170, 16, v33
	v_and_b32_e32 v171, 0xffff0000, v33
	v_add_f32_dpp v84, v84, v84 row_bcast:31 row_mask:0xc bank_mask:0xf
	v_lshlrev_b32_e32 v172, 16, v34
	v_and_b32_e32 v173, 0xffff0000, v34
	v_lshlrev_b32_e32 v174, 16, v35
	v_and_b32_e32 v175, 0xffff0000, v35
	s_nop 0
	v_readlane_b32 s83, v84, 63
	s_nop 2
	v_fma_f32 v84, s83, v2, v3
	v_rsq_f32_e32 v84, v84
	s_nop 0
	v_mul_f32_e32 v68, v68, v84
	v_mul_f32_e32 v69, v69, v84
	v_mul_f32_e32 v70, v70, v84
	v_mul_f32_e32 v71, v71, v84
	v_mul_f32_e32 v72, v72, v84
	v_mul_f32_e32 v73, v73, v84
	v_mul_f32_e32 v74, v74, v84
	v_mul_f32_e32 v75, v75, v84
	v_mul_f32_e32 v76, v76, v84
	v_mul_f32_e32 v77, v77, v84
	v_mul_f32_e32 v78, v78, v84
	v_mul_f32_e32 v79, v79, v84
	v_mul_f32_e32 v80, v80, v84
	v_mul_f32_e32 v81, v81, v84
	v_mul_f32_e32 v82, v82, v84
	v_mul_f32_e32 v83, v83, v84
	v_fma_f32 v68, v68, v4, v160
	v_fma_f32 v69, v69, v5, v161
	v_fma_f32 v70, v70, v6, v162
	v_fma_f32 v71, v71, v7, v163
	v_fma_f32 v72, v72, v8, v164
	v_fma_f32 v73, v73, v9, v165
	v_fma_f32 v74, v74, v10, v166
	v_fma_f32 v75, v75, v11, v167
	v_fma_f32 v76, v76, v12, v168
	v_fma_f32 v77, v77, v13, v169
	v_fma_f32 v78, v78, v14, v170
	v_fma_f32 v79, v79, v15, v171
	v_fma_f32 v80, v80, v16, v172
	v_fma_f32 v81, v81, v17, v173
	v_fma_f32 v82, v82, v18, v174
	v_fma_f32 v83, v83, v19, v175
	v_mul_f32_e32 v86, v68, v68
	v_mul_f32_e32 v87, v72, v72
	v_mul_f32_e32 v88, v76, v76
	v_mul_f32_e32 v89, v80, v80
	v_fmac_f32_e32 v86, v69, v69
	v_fmac_f32_e32 v87, v73, v73
	v_fmac_f32_e32 v88, v77, v77
	v_fmac_f32_e32 v89, v81, v81
	v_fmac_f32_e32 v86, v70, v70
	v_fmac_f32_e32 v87, v74, v74
	v_fmac_f32_e32 v88, v78, v78
	v_fmac_f32_e32 v89, v82, v82
	v_fmac_f32_e32 v86, v71, v71
	v_fmac_f32_e32 v87, v75, v75
	v_fmac_f32_e32 v88, v79, v79
	v_fmac_f32_e32 v89, v83, v83
	v_add_f32_e32 v85, v86, v87
	v_add_f32_e32 v85, v85, v88
	v_add_f32_e32 v85, v85, v89
	v_cvt_pk_bf16_f32 v90, v68, v69
	v_cvt_pk_bf16_f32 v91, v70, v71
	v_add_f32_dpp v85, v85, v85 quad_perm:[1,0,3,2] row_mask:0xf bank_mask:0xf
	v_cvt_pk_bf16_f32 v92, v72, v73
	v_cvt_pk_bf16_f32 v93, v74, v75
	v_add_f32_dpp v85, v85, v85 quad_perm:[2,3,0,1] row_mask:0xf bank_mask:0xf
	v_cvt_pk_bf16_f32 v94, v76, v77
	v_cvt_pk_bf16_f32 v95, v78, v79
	v_add_f32_dpp v85, v85, v85 row_half_mirror row_mask:0xf bank_mask:0xf
	v_cvt_pk_bf16_f32 v96, v80, v81
	v_cvt_pk_bf16_f32 v97, v82, v83
	v_add_f32_dpp v85, v85, v85 row_mirror row_mask:0xf bank_mask:0xf
	s_nop 1
	v_add_f32_dpp v85, v85, v85 row_bcast:15 row_mask:0xa bank_mask:0xf
	s_nop 1
	v_add_f32_dpp v85, v85, v85 row_bcast:31 row_mask:0xc bank_mask:0xf
	global_store_dwordx2 v1, v[90:91], s[74:75] offset:0
	global_store_dwordx2 v1, v[92:93], s[74:75] offset:512
	global_store_dwordx2 v1, v[94:95], s[74:75] offset:1024
	global_store_dwordx2 v1, v[96:97], s[74:75] offset:1536
	v_readlane_b32 s84, v85, 63
	s_add_u32 s74, s74, 0x400000
	s_addc_u32 s75, s75, 0
	s_nop 0
	v_fma_f32 v85, s84, v2, v3
	v_rsq_f32_e32 v85, v85
	s_nop 0
	v_mul_f32_e32 v68, v68, v85
	v_mul_f32_e32 v69, v69, v85
	v_mul_f32_e32 v70, v70, v85
	v_mul_f32_e32 v71, v71, v85
	v_mul_f32_e32 v72, v72, v85
	v_mul_f32_e32 v73, v73, v85
	v_mul_f32_e32 v74, v74, v85
	v_mul_f32_e32 v75, v75, v85
	v_mul_f32_e32 v76, v76, v85
	v_mul_f32_e32 v77, v77, v85
	v_mul_f32_e32 v78, v78, v85
	v_mul_f32_e32 v79, v79, v85
	v_mul_f32_e32 v80, v80, v85
	v_mul_f32_e32 v81, v81, v85
	v_mul_f32_e32 v82, v82, v85
	v_mul_f32_e32 v83, v83, v85
	v_mul_f32_e32 v68, v68, v100
	v_mul_f32_e32 v69, v69, v101
	v_mul_f32_e32 v70, v70, v102
	v_mul_f32_e32 v71, v71, v103
	v_mul_f32_e32 v72, v72, v104
	v_mul_f32_e32 v73, v73, v105
	v_mul_f32_e32 v74, v74, v106
	v_mul_f32_e32 v75, v75, v107
	v_mul_f32_e32 v76, v76, v108
	v_mul_f32_e32 v77, v77, v109
	v_mul_f32_e32 v78, v78, v110
	v_mul_f32_e32 v79, v79, v111
	v_mul_f32_e32 v80, v80, v112
	v_mul_f32_e32 v81, v81, v113
	v_mul_f32_e32 v82, v82, v114
	v_mul_f32_e32 v83, v83, v115
	v_cvt_pk_bf16_f32 v176, v68, v69
	v_cvt_pk_bf16_f32 v177, v70, v71
	v_cvt_pk_bf16_f32 v178, v72, v73
	v_cvt_pk_bf16_f32 v179, v74, v75
	v_cvt_pk_bf16_f32 v180, v76, v77
	v_cvt_pk_bf16_f32 v181, v78, v79
	v_cvt_pk_bf16_f32 v182, v80, v81
	v_cvt_pk_bf16_f32 v183, v82, v83
	global_store_dwordx2 v1, v[176:177], s[76:77] offset:0
	global_store_dwordx2 v1, v[178:179], s[76:77] offset:512
	global_store_dwordx2 v1, v[180:181], s[76:77] offset:1024
	global_store_dwordx2 v1, v[182:183], s[76:77] offset:1536
	s_add_u32 s76, s76, 0x400000
	s_addc_u32 s77, s77, 0
	s_cmp_eq_u32 s82, 0
	s_cbranch_scc0 .Lrows_p13_r8ok
	s_sub_u32 s70, s70, 0x400000
	s_subb_u32 s71, s71, 0
	s_sub_u32 s72, s72, 0x400000
	s_subb_u32 s73, s73, 0

.LBB0_1450:
	s_cmp_lt_i32 s24, 17
	s_cselect_b64 s[4:5], -1, 0
	s_cmp_gt_i32 s25, 16
	s_cselect_b64 s[6:7], -1, 0
	s_and_b64 s[4:5], s[4:5], s[6:7]
	s_andn2_b64 vcc, exec, s[4:5]
	s_cbranch_vccnz .LBB0_1512
	s_mov_b64 exec, -1
	s_load_dword s8, s[0:1], 0x148
	s_add_u32 s4, s0, 0x148
	s_addc_u32 s5, s1, 0
	s_load_dwordx2 s[78:79], s[0:1], 0x40
	v_lshrrev_b32_e32 v0, 6, v129
	v_and_b32_e32 v1, 63, v129
	v_readfirstlane_b32 s68, v0
	v_lshlrev_b32_e32 v0, 4, v1
	v_lshlrev_b32_e32 v1, 3, v1
	v_mov_b32_e32 v2, 0x3a800000
	v_mov_b32_e32 v3, 0x358637bd
	s_lshl_b32 s69, s2, 3
	s_add_u32 s68, s68, s69
	s_waitcnt lgkmcnt(0)
	s_add_u32 s78, s78, 0x1000
	s_addc_u32 s79, s79, 0
	global_load_dwordx4 v[4:7], v0, s[78:79] offset:0
	global_load_dwordx4 v[8:11], v0, s[78:79] offset:1024
	global_load_dwordx4 v[12:15], v0, s[78:79] offset:2048
	global_load_dwordx4 v[16:19], v0, s[78:79] offset:3072
	s_lshl_b32 s86, s68, 11
	s_add_u32 s70, s44, s86
	s_addc_u32 s71, s45, 0
	s_add_u32 s72, s50, s86
	s_addc_u32 s73, s51, 0
	s_lshl_b32 s87, s68, 12
	s_add_u32 s76, s58, s87
	s_addc_u32 s77, s59, 0
	s_cmpk_lt_u32 s68, 0x200
	s_cselect_b32 s82, 1, 0
	global_load_dwordx2 v[20:21], v1, s[70:71] offset:0
	global_load_dwordx2 v[22:23], v1, s[70:71] offset:512
	global_load_dwordx2 v[24:25], v1, s[70:71] offset:1024
	global_load_dwordx2 v[26:27], v1, s[70:71] offset:1536
	global_load_dwordx2 v[28:29], v1, s[72:73] offset:0
	global_load_dwordx2 v[30:31], v1, s[72:73] offset:512
	global_load_dwordx2 v[32:33], v1, s[72:73] offset:1024
	global_load_dwordx2 v[34:35], v1, s[72:73] offset:1536
	s_add_u32 s70, s70, 0x400000
	s_addc_u32 s71, s71, 0
	s_add_u32 s72, s72, 0x400000
	s_addc_u32 s73, s73, 0
	global_load_dwordx2 v[36:37], v1, s[70:71] offset:0
	global_load_dwordx2 v[38:39], v1, s[70:71] offset:512
	global_load_dwordx2 v[40:41], v1, s[70:71] offset:1024
	global_load_dwordx2 v[42:43], v1, s[70:71] offset:1536
	global_load_dwordx2 v[44:45], v1, s[72:73] offset:0
	global_load_dwordx2 v[46:47], v1, s[72:73] offset:512
	global_load_dwordx2 v[48:49], v1, s[72:73] offset:1024
	global_load_dwordx2 v[50:51], v1, s[72:73] offset:1536
	s_add_u32 s70, s70, 0x400000
	s_addc_u32 s71, s71, 0
	s_add_u32 s72, s72, 0x400000
	s_addc_u32 s73, s73, 0
	global_load_dwordx2 v[52:53], v1, s[70:71] offset:0
	global_load_dwordx2 v[54:55], v1, s[70:71] offset:512
	global_load_dwordx2 v[56:57], v1, s[70:71] offset:1024
	global_load_dwordx2 v[58:59], v1, s[70:71] offset:1536
	global_load_dwordx2 v[60:61], v1, s[72:73] offset:0
	global_load_dwordx2 v[62:63], v1, s[72:73] offset:512
	global_load_dwordx2 v[64:65], v1, s[72:73] offset:1024
	global_load_dwordx2 v[66:67], v1, s[72:73] offset:1536
	s_add_u32 s70, s70, 0x400000
	s_addc_u32 s71, s71, 0
	s_add_u32 s72, s72, 0x400000
	s_addc_u32 s73, s73, 0
	global_load_dwordx2 v[184:185], v1, s[70:71] offset:0
	global_load_dwordx2 v[186:187], v1, s[70:71] offset:512
	global_load_dwordx2 v[188:189], v1, s[70:71] offset:1024
	global_load_dwordx2 v[190:191], v1, s[70:71] offset:1536
	global_load_dwordx2 v[192:193], v1, s[72:73] offset:0
	global_load_dwordx2 v[194:195], v1, s[72:73] offset:512
	global_load_dwordx2 v[196:197], v1, s[72:73] offset:1024
	global_load_dwordx2 v[198:199], v1, s[72:73] offset:1536
	s_add_u32 s70, s70, 0x400000
	s_addc_u32 s71, s71, 0
	s_add_u32 s72, s72, 0x400000
	s_addc_u32 s73, s73, 0
	s_waitcnt vmcnt(24)
	v_lshlrev_b32_e32 v68, 16, v20
	v_and_b32_e32 v69, 0xffff0000, v20
	v_lshlrev_b32_e32 v70, 16, v21
	v_and_b32_e32 v71, 0xffff0000, v21
	v_lshlrev_b32_e32 v72, 16, v22
	v_and_b32_e32 v73, 0xffff0000, v22
	v_lshlrev_b32_e32 v74, 16, v23
	v_and_b32_e32 v75, 0xffff0000, v23
	v_lshlrev_b32_e32 v76, 16, v24
	v_and_b32_e32 v77, 0xffff0000, v24
	v_lshlrev_b32_e32 v78, 16, v25
	v_and_b32_e32 v79, 0xffff0000, v25
	v_lshlrev_b32_e32 v80, 16, v26
	v_and_b32_e32 v81, 0xffff0000, v26
	v_lshlrev_b32_e32 v82, 16, v27
	v_and_b32_e32 v83, 0xffff0000, v27
	v_mul_f32_e32 v86, v68, v68
	v_mul_f32_e32 v87, v72, v72
	v_mul_f32_e32 v88, v76, v76
	v_mul_f32_e32 v89, v80, v80
	v_fmac_f32_e32 v86, v69, v69
	v_fmac_f32_e32 v87, v73, v73
	v_fmac_f32_e32 v88, v77, v77
	v_fmac_f32_e32 v89, v81, v81
	v_fmac_f32_e32 v86, v70, v70
	v_fmac_f32_e32 v87, v74, v74
	v_fmac_f32_e32 v88, v78, v78
	v_fmac_f32_e32 v89, v82, v82
	v_fmac_f32_e32 v86, v71, v71
	v_fmac_f32_e32 v87, v75, v75
	v_fmac_f32_e32 v88, v79, v79
	v_fmac_f32_e32 v89, v83, v83
	v_add_f32_e32 v84, v86, v87
	v_add_f32_e32 v84, v84, v88
	v_add_f32_e32 v84, v84, v89
	v_lshlrev_b32_e32 v160, 16, v28
	v_and_b32_e32 v161, 0xffff0000, v28
	v_add_f32_dpp v84, v84, v84 quad_perm:[1,0,3,2] row_mask:0xf bank_mask:0xf
	v_lshlrev_b32_e32 v162, 16, v29
	v_and_b32_e32 v163, 0xffff0000, v29
	v_add_f32_dpp v84, v84, v84 quad_perm:[2,3,0,1] row_mask:0xf bank_mask:0xf
	v_lshlrev_b32_e32 v164, 16, v30
	v_and_b32_e32 v165, 0xffff0000, v30
	v_add_f32_dpp v84, v84, v84 row_half_mirror row_mask:0xf bank_mask:0xf
	v_lshlrev_b32_e32 v166, 16, v31
	v_and_b32_e32 v167, 0xffff0000, v31
	v_add_f32_dpp v84, v84, v84 row_mirror row_mask:0xf bank_mask:0xf
	v_lshlrev_b32_e32 v168, 16, v32
	v_and_b32_e32 v169, 0xffff0000, v32
	v_add_f32_dpp v84, v84, v84 row_bcast:15 row_mask:0xa bank_mask:0xf
	v_lshlrev_b32_e32 v170, 16, v33
	v_and_b32_e32 v171, 0xffff0000, v33
	v_add_f32_dpp v84, v84, v84 row_bcast:31 row_mask:0xc bank_mask:0xf
	v_lshlrev_b32_e32 v172, 16, v34
	v_and_b32_e32 v173, 0xffff0000, v34
	v_lshlrev_b32_e32 v174, 16, v35
	v_and_b32_e32 v175, 0xffff0000, v35
	s_nop 0
	v_readlane_b32 s83, v84, 63
	s_nop 2
	v_fma_f32 v84, s83, v2, v3
	v_rsq_f32_e32 v84, v84
	s_nop 0
	v_mul_f32_e32 v68, v68, v84
	v_mul_f32_e32 v69, v69, v84
	v_mul_f32_e32 v70, v70, v84
	v_mul_f32_e32 v71, v71, v84
	v_mul_f32_e32 v72, v72, v84
	v_mul_f32_e32 v73, v73, v84
	v_mul_f32_e32 v74, v74, v84
	v_mul_f32_e32 v75, v75, v84
	v_mul_f32_e32 v76, v76, v84
	v_mul_f32_e32 v77, v77, v84
	v_mul_f32_e32 v78, v78, v84
	v_mul_f32_e32 v79, v79, v84
	v_mul_f32_e32 v80, v80, v84
	v_mul_f32_e32 v81, v81, v84
	v_mul_f32_e32 v82, v82, v84
	v_mul_f32_e32 v83, v83, v84
	v_fma_f32 v68, v68, v4, v160
	v_fma_f32 v69, v69, v5, v161
	v_fma_f32 v70, v70, v6, v162
	v_fma_f32 v71, v71, v7, v163
	v_fma_f32 v72, v72, v8, v164
	v_fma_f32 v73, v73, v9, v165
	v_fma_f32 v74, v74, v10, v166
	v_fma_f32 v75, v75, v11, v167
	v_fma_f32 v76, v76, v12, v168
	v_fma_f32 v77, v77, v13, v169
	v_fma_f32 v78, v78, v14, v170
	v_fma_f32 v79, v79, v15, v171
	v_fma_f32 v80, v80, v16, v172
	v_fma_f32 v81, v81, v17, v173
	v_fma_f32 v82, v82, v18, v174
	v_fma_f32 v83, v83, v19, v175
	global_store_dwordx4 v0, v[68:71], s[76:77] offset:0
	global_store_dwordx4 v0, v[72:75], s[76:77] offset:1024
	global_store_dwordx4 v0, v[76:79], s[76:77] offset:2048
	global_store_dwordx4 v0, v[80:83], s[76:77] offset:3072
	s_add_u32 s76, s76, 0x800000
	s_addc_u32 s77, s77, 0
	global_load_dwordx2 v[20:21], v1, s[70:71] offset:0
	global_load_dwordx2 v[22:23], v1, s[70:71] offset:512
	global_load_dwordx2 v[24:25], v1, s[70:71] offset:1024
	global_load_dwordx2 v[26:27], v1, s[70:71] offset:1536
	global_load_dwordx2 v[28:29], v1, s[72:73] offset:0
	global_load_dwordx2 v[30:31], v1, s[72:73] offset:512
	global_load_dwordx2 v[32:33], v1, s[72:73] offset:1024
	global_load_dwordx2 v[34:35], v1, s[72:73] offset:1536
	s_add_u32 s70, s70, 0x400000
	s_addc_u32 s71, s71, 0
	s_add_u32 s72, s72, 0x400000
	s_addc_u32 s73, s73, 0
	s_waitcnt vmcnt(28)
	v_lshlrev_b32_e32 v68, 16, v36
	v_and_b32_e32 v69, 0xffff0000, v36
	v_lshlrev_b32_e32 v70, 16, v37
	v_and_b32_e32 v71, 0xffff0000, v37
	v_lshlrev_b32_e32 v72, 16, v38
	v_and_b32_e32 v73, 0xffff0000, v38
	v_lshlrev_b32_e32 v74, 16, v39
	v_and_b32_e32 v75, 0xffff0000, v39
	v_lshlrev_b32_e32 v76, 16, v40
	v_and_b32_e32 v77, 0xffff0000, v40
	v_lshlrev_b32_e32 v78, 16, v41
	v_and_b32_e32 v79, 0xffff0000, v41
	v_lshlrev_b32_e32 v80, 16, v42
	v_and_b32_e32 v81, 0xffff0000, v42
	v_lshlrev_b32_e32 v82, 16, v43
	v_and_b32_e32 v83, 0xffff0000, v43
	v_mul_f32_e32 v86, v68, v68
	v_mul_f32_e32 v87, v72, v72
	v_mul_f32_e32 v88, v76, v76
	v_mul_f32_e32 v89, v80, v80
	v_fmac_f32_e32 v86, v69, v69
	v_fmac_f32_e32 v87, v73, v73
	v_fmac_f32_e32 v88, v77, v77
	v_fmac_f32_e32 v89, v81, v81
	v_fmac_f32_e32 v86, v70, v70
	v_fmac_f32_e32 v87, v74, v74
	v_fmac_f32_e32 v88, v78, v78
	v_fmac_f32_e32 v89, v82, v82
	v_fmac_f32_e32 v86, v71, v71
	v_fmac_f32_e32 v87, v75, v75
	v_fmac_f32_e32 v88, v79, v79
	v_fmac_f32_e32 v89, v83, v83
	v_add_f32_e32 v84, v86, v87
	v_add_f32_e32 v84, v84, v88
	v_add_f32_e32 v84, v84, v89
	v_lshlrev_b32_e32 v160, 16, v44
	v_and_b32_e32 v161, 0xffff0000, v44
	v_add_f32_dpp v84, v84, v84 quad_perm:[1,0,3,2] row_mask:0xf bank_mask:0xf
	v_lshlrev_b32_e32 v162, 16, v45
	v_and_b32_e32 v163, 0xffff0000, v45
	v_add_f32_dpp v84, v84, v84 quad_perm:[2,3,0,1] row_mask:0xf bank_mask:0xf
	v_lshlrev_b32_e32 v164, 16, v46
	v_and_b32_e32 v165, 0xffff0000, v46
	v_add_f32_dpp v84, v84, v84 row_half_mirror row_mask:0xf bank_mask:0xf
	v_lshlrev_b32_e32 v166, 16, v47
	v_and_b32_e32 v167, 0xffff0000, v47
	v_add_f32_dpp v84, v84, v84 row_mirror row_mask:0xf bank_mask:0xf
	v_lshlrev_b32_e32 v168, 16, v48
	v_and_b32_e32 v169, 0xffff0000, v48
	v_add_f32_dpp v84, v84, v84 row_bcast:15 row_mask:0xa bank_mask:0xf
	v_lshlrev_b32_e32 v170, 16, v49
	v_and_b32_e32 v171, 0xffff0000, v49
	v_add_f32_dpp v84, v84, v84 row_bcast:31 row_mask:0xc bank_mask:0xf
	v_lshlrev_b32_e32 v172, 16, v50
	v_and_b32_e32 v173, 0xffff0000, v50
	v_lshlrev_b32_e32 v174, 16, v51
	v_and_b32_e32 v175, 0xffff0000, v51
	s_nop 0
	v_readlane_b32 s83, v84, 63
	s_nop 2
	v_fma_f32 v84, s83, v2, v3
	v_rsq_f32_e32 v84, v84
	s_nop 0
	v_mul_f32_e32 v68, v68, v84
	v_mul_f32_e32 v69, v69, v84
	v_mul_f32_e32 v70, v70, v84
	v_mul_f32_e32 v71, v71, v84
	v_mul_f32_e32 v72, v72, v84
	v_mul_f32_e32 v73, v73, v84
	v_mul_f32_e32 v74, v74, v84
	v_mul_f32_e32 v75, v75, v84
	v_mul_f32_e32 v76, v76, v84
	v_mul_f32_e32 v77, v77, v84
	v_mul_f32_e32 v78, v78, v84
	v_mul_f32_e32 v79, v79, v84
	v_mul_f32_e32 v80, v80, v84
	v_mul_f32_e32 v81, v81, v84
	v_mul_f32_e32 v82, v82, v84
	v_mul_f32_e32 v83, v83, v84
	v_fma_f32 v68, v68, v4, v160
	v_fma_f32 v69, v69, v5, v161
	v_fma_f32 v70, v70, v6, v162
	v_fma_f32 v71, v71, v7, v163
	v_fma_f32 v72, v72, v8, v164
	v_fma_f32 v73, v73, v9, v165
	v_fma_f32 v74, v74, v10, v166
	v_fma_f32 v75, v75, v11, v167
	v_fma_f32 v76, v76, v12, v168
	v_fma_f32 v77, v77, v13, v169
	v_fma_f32 v78, v78, v14, v170
	v_fma_f32 v79, v79, v15, v171
	v_fma_f32 v80, v80, v16, v172
	v_fma_f32 v81, v81, v17, v173
	v_fma_f32 v82, v82, v18, v174
	v_fma_f32 v83, v83, v19, v175
	global_store_dwordx4 v0, v[68:71], s[76:77] offset:0
	global_store_dwordx4 v0, v[72:75], s[76:77] offset:1024
	global_store_dwordx4 v0, v[76:79], s[76:77] offset:2048
	global_store_dwordx4 v0, v[80:83], s[76:77] offset:3072
	s_add_u32 s76, s76, 0x800000
	s_addc_u32 s77, s77, 0
	global_load_dwordx2 v[36:37], v1, s[70:71] offset:0
	global_load_dwordx2 v[38:39], v1, s[70:71] offset:512
	global_load_dwordx2 v[40:41], v1, s[70:71] offset:1024
	global_load_dwordx2 v[42:43], v1, s[70:71] offset:1536
	global_load_dwordx2 v[44:45], v1, s[72:73] offset:0
	global_load_dwordx2 v[46:47], v1, s[72:73] offset:512
	global_load_dwordx2 v[48:49], v1, s[72:73] offset:1024
	global_load_dwordx2 v[50:51], v1, s[72:73] offset:1536
	s_add_u32 s70, s70, 0x400000
	s_addc_u32 s71, s71, 0
	s_add_u32 s72, s72, 0x400000
	s_addc_u32 s73, s73, 0
	s_waitcnt vmcnt(32)
	v_lshlrev_b32_e32 v68, 16, v52
	v_and_b32_e32 v69, 0xffff0000, v52
	v_lshlrev_b32_e32 v70, 16, v53
	v_and_b32_e32 v71, 0xffff0000, v53
	v_lshlrev_b32_e32 v72, 16, v54
	v_and_b32_e32 v73, 0xffff0000, v54
	v_lshlrev_b32_e32 v74, 16, v55
	v_and_b32_e32 v75, 0xffff0000, v55
	v_lshlrev_b32_e32 v76, 16, v56
	v_and_b32_e32 v77, 0xffff0000, v56
	v_lshlrev_b32_e32 v78, 16, v57
	v_and_b32_e32 v79, 0xffff0000, v57
	v_lshlrev_b32_e32 v80, 16, v58
	v_and_b32_e32 v81, 0xffff0000, v58
	v_lshlrev_b32_e32 v82, 16, v59
	v_and_b32_e32 v83, 0xffff0000, v59
	v_mul_f32_e32 v86, v68, v68
	v_mul_f32_e32 v87, v72, v72
	v_mul_f32_e32 v88, v76, v76
	v_mul_f32_e32 v89, v80, v80
	v_fmac_f32_e32 v86, v69, v69
	v_fmac_f32_e32 v87, v73, v73
	v_fmac_f32_e32 v88, v77, v77
	v_fmac_f32_e32 v89, v81, v81
	v_fmac_f32_e32 v86, v70, v70
	v_fmac_f32_e32 v87, v74, v74
	v_fmac_f32_e32 v88, v78, v78
	v_fmac_f32_e32 v89, v82, v82
	v_fmac_f32_e32 v86, v71, v71
	v_fmac_f32_e32 v87, v75, v75
	v_fmac_f32_e32 v88, v79, v79
	v_fmac_f32_e32 v89, v83, v83
	v_add_f32_e32 v84, v86, v87
	v_add_f32_e32 v84, v84, v88
	v_add_f32_e32 v84, v84, v89
	v_lshlrev_b32_e32 v160, 16, v60
	v_and_b32_e32 v161, 0xffff0000, v60
	v_add_f32_dpp v84, v84, v84 quad_perm:[1,0,3,2] row_mask:0xf bank_mask:0xf
	v_lshlrev_b32_e32 v162, 16, v61
	v_and_b32_e32 v163, 0xffff0000, v61
	v_add_f32_dpp v84, v84, v84 quad_perm:[2,3,0,1] row_mask:0xf bank_mask:0xf
	v_lshlrev_b32_e32 v164, 16, v62
	v_and_b32_e32 v165, 0xffff0000, v62
	v_add_f32_dpp v84, v84, v84 row_half_mirror row_mask:0xf bank_mask:0xf
	v_lshlrev_b32_e32 v166, 16, v63
	v_and_b32_e32 v167, 0xffff0000, v63
	v_add_f32_dpp v84, v84, v84 row_mirror row_mask:0xf bank_mask:0xf
	v_lshlrev_b32_e32 v168, 16, v64
	v_and_b32_e32 v169, 0xffff0000, v64
	v_add_f32_dpp v84, v84, v84 row_bcast:15 row_mask:0xa bank_mask:0xf
	v_lshlrev_b32_e32 v170, 16, v65
	v_and_b32_e32 v171, 0xffff0000, v65
	v_add_f32_dpp v84, v84, v84 row_bcast:31 row_mask:0xc bank_mask:0xf
	v_lshlrev_b32_e32 v172, 16, v66
	v_and_b32_e32 v173, 0xffff0000, v66
	v_lshlrev_b32_e32 v174, 16, v67
	v_and_b32_e32 v175, 0xffff0000, v67
	s_nop 0
	v_readlane_b32 s83, v84, 63
	s_nop 2
	v_fma_f32 v84, s83, v2, v3
	v_rsq_f32_e32 v84, v84
	s_nop 0
	v_mul_f32_e32 v68, v68, v84
	v_mul_f32_e32 v69, v69, v84
	v_mul_f32_e32 v70, v70, v84
	v_mul_f32_e32 v71, v71, v84
	v_mul_f32_e32 v72, v72, v84
	v_mul_f32_e32 v73, v73, v84
	v_mul_f32_e32 v74, v74, v84
	v_mul_f32_e32 v75, v75, v84
	v_mul_f32_e32 v76, v76, v84
	v_mul_f32_e32 v77, v77, v84
	v_mul_f32_e32 v78, v78, v84
	v_mul_f32_e32 v79, v79, v84
	v_mul_f32_e32 v80, v80, v84
	v_mul_f32_e32 v81, v81, v84
	v_mul_f32_e32 v82, v82, v84
	v_mul_f32_e32 v83, v83, v84
	v_fma_f32 v68, v68, v4, v160
	v_fma_f32 v69, v69, v5, v161
	v_fma_f32 v70, v70, v6, v162
	v_fma_f32 v71, v71, v7, v163
	v_fma_f32 v72, v72, v8, v164
	v_fma_f32 v73, v73, v9, v165
	v_fma_f32 v74, v74, v10, v166
	v_fma_f32 v75, v75, v11, v167
	v_fma_f32 v76, v76, v12, v168
	v_fma_f32 v77, v77, v13, v169
	v_fma_f32 v78, v78, v14, v170
	v_fma_f32 v79, v79, v15, v171
	v_fma_f32 v80, v80, v16, v172
	v_fma_f32 v81, v81, v17, v173
	v_fma_f32 v82, v82, v18, v174
	v_fma_f32 v83, v83, v19, v175
	global_store_dwordx4 v0, v[68:71], s[76:77] offset:0
	global_store_dwordx4 v0, v[72:75], s[76:77] offset:1024
	global_store_dwordx4 v0, v[76:79], s[76:77] offset:2048
	global_store_dwordx4 v0, v[80:83], s[76:77] offset:3072
	s_add_u32 s76, s76, 0x800000
	s_addc_u32 s77, s77, 0
	global_load_dwordx2 v[52:53], v1, s[70:71] offset:0
	global_load_dwordx2 v[54:55], v1, s[70:71] offset:512
	global_load_dwordx2 v[56:57], v1, s[70:71] offset:1024
	global_load_dwordx2 v[58:59], v1, s[70:71] offset:1536
	global_load_dwordx2 v[60:61], v1, s[72:73] offset:0
	global_load_dwordx2 v[62:63], v1, s[72:73] offset:512
	global_load_dwordx2 v[64:65], v1, s[72:73] offset:1024
	global_load_dwordx2 v[66:67], v1, s[72:73] offset:1536
	s_add_u32 s70, s70, 0x400000
	s_addc_u32 s71, s71, 0
	s_add_u32 s72, s72, 0x400000
	s_addc_u32 s73, s73, 0
	s_waitcnt vmcnt(36)
	v_lshlrev_b32_e32 v68, 16, v184
	v_and_b32_e32 v69, 0xffff0000, v184
	v_lshlrev_b32_e32 v70, 16, v185
	v_and_b32_e32 v71, 0xffff0000, v185
	v_lshlrev_b32_e32 v72, 16, v186
	v_and_b32_e32 v73, 0xffff0000, v186
	v_lshlrev_b32_e32 v74, 16, v187
	v_and_b32_e32 v75, 0xffff0000, v187
	v_lshlrev_b32_e32 v76, 16, v188
	v_and_b32_e32 v77, 0xffff0000, v188
	v_lshlrev_b32_e32 v78, 16, v189
	v_and_b32_e32 v79, 0xffff0000, v189
	v_lshlrev_b32_e32 v80, 16, v190
	v_and_b32_e32 v81, 0xffff0000, v190
	v_lshlrev_b32_e32 v82, 16, v191
	v_and_b32_e32 v83, 0xffff0000, v191
	v_mul_f32_e32 v86, v68, v68
	v_mul_f32_e32 v87, v72, v72
	v_mul_f32_e32 v88, v76, v76
	v_mul_f32_e32 v89, v80, v80
	v_fmac_f32_e32 v86, v69, v69
	v_fmac_f32_e32 v87, v73, v73
	v_fmac_f32_e32 v88, v77, v77
	v_fmac_f32_e32 v89, v81, v81
	v_fmac_f32_e32 v86, v70, v70
	v_fmac_f32_e32 v87, v74, v74
	v_fmac_f32_e32 v88, v78, v78
	v_fmac_f32_e32 v89, v82, v82
	v_fmac_f32_e32 v86, v71, v71
	v_fmac_f32_e32 v87, v75, v75
	v_fmac_f32_e32 v88, v79, v79
	v_fmac_f32_e32 v89, v83, v83
	v_add_f32_e32 v84, v86, v87
	v_add_f32_e32 v84, v84, v88
	v_add_f32_e32 v84, v84, v89
	v_lshlrev_b32_e32 v160, 16, v192
	v_and_b32_e32 v161, 0xffff0000, v192
	v_add_f32_dpp v84, v84, v84 quad_perm:[1,0,3,2] row_mask:0xf bank_mask:0xf
	v_lshlrev_b32_e32 v162, 16, v193
	v_and_b32_e32 v163, 0xffff0000, v193
	v_add_f32_dpp v84, v84, v84 quad_perm:[2,3,0,1] row_mask:0xf bank_mask:0xf
	v_lshlrev_b32_e32 v164, 16, v194
	v_and_b32_e32 v165, 0xffff0000, v194
	v_add_f32_dpp v84, v84, v84 row_half_mirror row_mask:0xf bank_mask:0xf
	v_lshlrev_b32_e32 v166, 16, v195
	v_and_b32_e32 v167, 0xffff0000, v195
	v_add_f32_dpp v84, v84, v84 row_mirror row_mask:0xf bank_mask:0xf
	v_lshlrev_b32_e32 v168, 16, v196
	v_and_b32_e32 v169, 0xffff0000, v196
	v_add_f32_dpp v84, v84, v84 row_bcast:15 row_mask:0xa bank_mask:0xf
	v_lshlrev_b32_e32 v170, 16, v197
	v_and_b32_e32 v171, 0xffff0000, v197
	v_add_f32_dpp v84, v84, v84 row_bcast:31 row_mask:0xc bank_mask:0xf
	v_lshlrev_b32_e32 v172, 16, v198
	v_and_b32_e32 v173, 0xffff0000, v198
	v_lshlrev_b32_e32 v174, 16, v199
	v_and_b32_e32 v175, 0xffff0000, v199
	s_nop 0
	v_readlane_b32 s83, v84, 63
	s_nop 2
	v_fma_f32 v84, s83, v2, v3
	v_rsq_f32_e32 v84, v84
	s_nop 0
	v_mul_f32_e32 v68, v68, v84
	v_mul_f32_e32 v69, v69, v84
	v_mul_f32_e32 v70, v70, v84
	v_mul_f32_e32 v71, v71, v84
	v_mul_f32_e32 v72, v72, v84
	v_mul_f32_e32 v73, v73, v84
	v_mul_f32_e32 v74, v74, v84
	v_mul_f32_e32 v75, v75, v84
	v_mul_f32_e32 v76, v76, v84
	v_mul_f32_e32 v77, v77, v84
	v_mul_f32_e32 v78, v78, v84
	v_mul_f32_e32 v79, v79, v84
	v_mul_f32_e32 v80, v80, v84
	v_mul_f32_e32 v81, v81, v84
	v_mul_f32_e32 v82, v82, v84
	v_mul_f32_e32 v83, v83, v84
	v_fma_f32 v68, v68, v4, v160
	v_fma_f32 v69, v69, v5, v161
	v_fma_f32 v70, v70, v6, v162
	v_fma_f32 v71, v71, v7, v163
	v_fma_f32 v72, v72, v8, v164
	v_fma_f32 v73, v73, v9, v165
	v_fma_f32 v74, v74, v10, v166
	v_fma_f32 v75, v75, v11, v167
	v_fma_f32 v76, v76, v12, v168
	v_fma_f32 v77, v77, v13, v169
	v_fma_f32 v78, v78, v14, v170
	v_fma_f32 v79, v79, v15, v171
	v_fma_f32 v80, v80, v16, v172
	v_fma_f32 v81, v81, v17, v173
	v_fma_f32 v82, v82, v18, v174
	v_fma_f32 v83, v83, v19, v175
	global_store_dwordx4 v0, v[68:71], s[76:77] offset:0
	global_store_dwordx4 v0, v[72:75], s[76:77] offset:1024
	global_store_dwordx4 v0, v[76:79], s[76:77] offset:2048
	global_store_dwordx4 v0, v[80:83], s[76:77] offset:3072
	s_add_u32 s76, s76, 0x800000
	s_addc_u32 s77, s77, 0
	global_load_dwordx2 v[184:185], v1, s[70:71] offset:0
	global_load_dwordx2 v[186:187], v1, s[70:71] offset:512
	global_load_dwordx2 v[188:189], v1, s[70:71] offset:1024
	global_load_dwordx2 v[190:191], v1, s[70:71] offset:1536
	global_load_dwordx2 v[192:193], v1, s[72:73] offset:0
	global_load_dwordx2 v[194:195], v1, s[72:73] offset:512
	global_load_dwordx2 v[196:197], v1, s[72:73] offset:1024
	global_load_dwordx2 v[198:199], v1, s[72:73] offset:1536
	s_add_u32 s70, s70, 0x400000
	s_addc_u32 s71, s71, 0
	s_add_u32 s72, s72, 0x400000
	s_addc_u32 s73, s73, 0
	s_waitcnt vmcnt(36)
	v_lshlrev_b32_e32 v68, 16, v20
	v_and_b32_e32 v69, 0xffff0000, v20
	v_lshlrev_b32_e32 v70, 16, v21
	v_and_b32_e32 v71, 0xffff0000, v21
	v_lshlrev_b32_e32 v72, 16, v22
	v_and_b32_e32 v73, 0xffff0000, v22
	v_lshlrev_b32_e32 v74, 16, v23
	v_and_b32_e32 v75, 0xffff0000, v23
	v_lshlrev_b32_e32 v76, 16, v24
	v_and_b32_e32 v77, 0xffff0000, v24
	v_lshlrev_b32_e32 v78, 16, v25
	v_and_b32_e32 v79, 0xffff0000, v25
	v_lshlrev_b32_e32 v80, 16, v26
	v_and_b32_e32 v81, 0xffff0000, v26
	v_lshlrev_b32_e32 v82, 16, v27
	v_and_b32_e32 v83, 0xffff0000, v27
	v_mul_f32_e32 v86, v68, v68
	v_mul_f32_e32 v87, v72, v72
	v_mul_f32_e32 v88, v76, v76
	v_mul_f32_e32 v89, v80, v80
	v_fmac_f32_e32 v86, v69, v69
	v_fmac_f32_e32 v87, v73, v73
	v_fmac_f32_e32 v88, v77, v77
	v_fmac_f32_e32 v89, v81, v81
	v_fmac_f32_e32 v86, v70, v70
	v_fmac_f32_e32 v87, v74, v74
	v_fmac_f32_e32 v88, v78, v78
	v_fmac_f32_e32 v89, v82, v82
	v_fmac_f32_e32 v86, v71, v71
	v_fmac_f32_e32 v87, v75, v75
	v_fmac_f32_e32 v88, v79, v79
	v_fmac_f32_e32 v89, v83, v83
	v_add_f32_e32 v84, v86, v87
	v_add_f32_e32 v84, v84, v88
	v_add_f32_e32 v84, v84, v89
	v_lshlrev_b32_e32 v160, 16, v28
	v_and_b32_e32 v161, 0xffff0000, v28
	v_add_f32_dpp v84, v84, v84 quad_perm:[1,0,3,2] row_mask:0xf bank_mask:0xf
	v_lshlrev_b32_e32 v162, 16, v29
	v_and_b32_e32 v163, 0xffff0000, v29
	v_add_f32_dpp v84, v84, v84 quad_perm:[2,3,0,1] row_mask:0xf bank_mask:0xf
	v_lshlrev_b32_e32 v164, 16, v30
	v_and_b32_e32 v165, 0xffff0000, v30
	v_add_f32_dpp v84, v84, v84 row_half_mirror row_mask:0xf bank_mask:0xf
	v_lshlrev_b32_e32 v166, 16, v31
	v_and_b32_e32 v167, 0xffff0000, v31
	v_add_f32_dpp v84, v84, v84 row_mirror row_mask:0xf bank_mask:0xf
	v_lshlrev_b32_e32 v168, 16, v32
	v_and_b32_e32 v169, 0xffff0000, v32
	v_add_f32_dpp v84, v84, v84 row_bcast:15 row_mask:0xa bank_mask:0xf
	v_lshlrev_b32_e32 v170, 16, v33
	v_and_b32_e32 v171, 0xffff0000, v33
	v_add_f32_dpp v84, v84, v84 row_bcast:31 row_mask:0xc bank_mask:0xf
	v_lshlrev_b32_e32 v172, 16, v34
	v_and_b32_e32 v173, 0xffff0000, v34
	v_lshlrev_b32_e32 v174, 16, v35
	v_and_b32_e32 v175, 0xffff0000, v35
	s_nop 0
	v_readlane_b32 s83, v84, 63
	s_nop 2
	v_fma_f32 v84, s83, v2, v3
	v_rsq_f32_e32 v84, v84
	s_nop 0
	v_mul_f32_e32 v68, v68, v84
	v_mul_f32_e32 v69, v69, v84
	v_mul_f32_e32 v70, v70, v84
	v_mul_f32_e32 v71, v71, v84
	v_mul_f32_e32 v72, v72, v84
	v_mul_f32_e32 v73, v73, v84
	v_mul_f32_e32 v74, v74, v84
	v_mul_f32_e32 v75, v75, v84
	v_mul_f32_e32 v76, v76, v84
	v_mul_f32_e32 v77, v77, v84
	v_mul_f32_e32 v78, v78, v84
	v_mul_f32_e32 v79, v79, v84
	v_mul_f32_e32 v80, v80, v84
	v_mul_f32_e32 v81, v81, v84
	v_mul_f32_e32 v82, v82, v84
	v_mul_f32_e32 v83, v83, v84
	v_fma_f32 v68, v68, v4, v160
	v_fma_f32 v69, v69, v5, v161
	v_fma_f32 v70, v70, v6, v162
	v_fma_f32 v71, v71, v7, v163
	v_fma_f32 v72, v72, v8, v164
	v_fma_f32 v73, v73, v9, v165
	v_fma_f32 v74, v74, v10, v166
	v_fma_f32 v75, v75, v11, v167
	v_fma_f32 v76, v76, v12, v168
	v_fma_f32 v77, v77, v13, v169
	v_fma_f32 v78, v78, v14, v170
	v_fma_f32 v79, v79, v15, v171
	v_fma_f32 v80, v80, v16, v172
	v_fma_f32 v81, v81, v17, v173
	v_fma_f32 v82, v82, v18, v174
	v_fma_f32 v83, v83, v19, v175
	global_store_dwordx4 v0, v[68:71], s[76:77] offset:0
	global_store_dwordx4 v0, v[72:75], s[76:77] offset:1024
	global_store_dwordx4 v0, v[76:79], s[76:77] offset:2048
	global_store_dwordx4 v0, v[80:83], s[76:77] offset:3072
	s_add_u32 s76, s76, 0x800000
	s_addc_u32 s77, s77, 0
	s_cmp_eq_u32 s82, 0
	s_cbranch_scc0 .Lrows_p16_r8ok
	s_sub_u32 s70, s70, 0x400000
	s_subb_u32 s71, s71, 0
	s_sub_u32 s72, s72, 0x400000
	s_subb_u32 s73, s73, 0
.Lrows_p16_r8ok:
	global_load_dwordx2 v[20:21], v1, s[70:71] offset:0
	global_load_dwordx2 v[22:23], v1, s[70:71] offset:512
	global_load_dwordx2 v[24:25], v1, s[70:71] offset:1024
	global_load_dwordx2 v[26:27], v1, s[70:71] offset:1536
	global_load_dwordx2 v[28:29], v1, s[72:73] offset:0
	global_load_dwordx2 v[30:31], v1, s[72:73] offset:512
	global_load_dwordx2 v[32:33], v1, s[72:73] offset:1024
	global_load_dwordx2 v[34:35], v1, s[72:73] offset:1536
	s_add_u32 s70, s70, 0x400000
	s_addc_u32 s71, s71, 0
	s_add_u32 s72, s72, 0x400000
	s_addc_u32 s73, s73, 0
	s_waitcnt vmcnt(36)
	v_lshlrev_b32_e32 v68, 16, v36
	v_and_b32_e32 v69, 0xffff0000, v36
	v_lshlrev_b32_e32 v70, 16, v37
	v_and_b32_e32 v71, 0xffff0000, v37
	v_lshlrev_b32_e32 v72, 16, v38
	v_and_b32_e32 v73, 0xffff0000, v38
	v_lshlrev_b32_e32 v74, 16, v39
	v_and_b32_e32 v75, 0xffff0000, v39
	v_lshlrev_b32_e32 v76, 16, v40
	v_and_b32_e32 v77, 0xffff0000, v40
	v_lshlrev_b32_e32 v78, 16, v41
	v_and_b32_e32 v79, 0xffff0000, v41
	v_lshlrev_b32_e32 v80, 16, v42
	v_and_b32_e32 v81, 0xffff0000, v42
	v_lshlrev_b32_e32 v82, 16, v43
	v_and_b32_e32 v83, 0xffff0000, v43
	v_mul_f32_e32 v86, v68, v68
	v_mul_f32_e32 v87, v72, v72
	v_mul_f32_e32 v88, v76, v76
	v_mul_f32_e32 v89, v80, v80
	v_fmac_f32_e32 v86, v69, v69
	v_fmac_f32_e32 v87, v73, v73
	v_fmac_f32_e32 v88, v77, v77
	v_fmac_f32_e32 v89, v81, v81
	v_fmac_f32_e32 v86, v70, v70
	v_fmac_f32_e32 v87, v74, v74
	v_fmac_f32_e32 v88, v78, v78
	v_fmac_f32_e32 v89, v82, v82
	v_fmac_f32_e32 v86, v71, v71
	v_fmac_f32_e32 v87, v75, v75
	v_fmac_f32_e32 v88, v79, v79
	v_fmac_f32_e32 v89, v83, v83
	v_add_f32_e32 v84, v86, v87
	v_add_f32_e32 v84, v84, v88
	v_add_f32_e32 v84, v84, v89
	v_lshlrev_b32_e32 v160, 16, v44
	v_and_b32_e32 v161, 0xffff0000, v44
	v_add_f32_dpp v84, v84, v84 quad_perm:[1,0,3,2] row_mask:0xf bank_mask:0xf
	v_lshlrev_b32_e32 v162, 16, v45
	v_and_b32_e32 v163, 0xffff0000, v45
	v_add_f32_dpp v84, v84, v84 quad_perm:[2,3,0,1] row_mask:0xf bank_mask:0xf
	v_lshlrev_b32_e32 v164, 16, v46
	v_and_b32_e32 v165, 0xffff0000, v46
	v_add_f32_dpp v84, v84, v84 row_half_mirror row_mask:0xf bank_mask:0xf
	v_lshlrev_b32_e32 v166, 16, v47
	v_and_b32_e32 v167, 0xffff0000, v47
	v_add_f32_dpp v84, v84, v84 row_mirror row_mask:0xf bank_mask:0xf
	v_lshlrev_b32_e32 v168, 16, v48
	v_and_b32_e32 v169, 0xffff0000, v48
	v_add_f32_dpp v84, v84, v84 row_bcast:15 row_mask:0xa bank_mask:0xf
	v_lshlrev_b32_e32 v170, 16, v49
	v_and_b32_e32 v171, 0xffff0000, v49
	v_add_f32_dpp v84, v84, v84 row_bcast:31 row_mask:0xc bank_mask:0xf
	v_lshlrev_b32_e32 v172, 16, v50
	v_and_b32_e32 v173, 0xffff0000, v50
	v_lshlrev_b32_e32 v174, 16, v51
	v_and_b32_e32 v175, 0xffff0000, v51
	s_nop 0
	v_readlane_b32 s83, v84, 63
	s_nop 2
	v_fma_f32 v84, s83, v2, v3
	v_rsq_f32_e32 v84, v84
	s_nop 0
	v_mul_f32_e32 v68, v68, v84
	v_mul_f32_e32 v69, v69, v84
	v_mul_f32_e32 v70, v70, v84
	v_mul_f32_e32 v71, v71, v84
	v_mul_f32_e32 v72, v72, v84
	v_mul_f32_e32 v73, v73, v84
	v_mul_f32_e32 v74, v74, v84
	v_mul_f32_e32 v75, v75, v84
	v_mul_f32_e32 v76, v76, v84
	v_mul_f32_e32 v77, v77, v84
	v_mul_f32_e32 v78, v78, v84
	v_mul_f32_e32 v79, v79, v84
	v_mul_f32_e32 v80, v80, v84
	v_mul_f32_e32 v81, v81, v84
	v_mul_f32_e32 v82, v82, v84
	v_mul_f32_e32 v83, v83, v84
	v_fma_f32 v68, v68, v4, v160
	v_fma_f32 v69, v69, v5, v161
	v_fma_f32 v70, v70, v6, v162
	v_fma_f32 v71, v71, v7, v163
	v_fma_f32 v72, v72, v8, v164
	v_fma_f32 v73, v73, v9, v165
	v_fma_f32 v74, v74, v10, v166
	v_fma_f32 v75, v75, v11, v167
	v_fma_f32 v76, v76, v12, v168
	v_fma_f32 v77, v77, v13, v169
	v_fma_f32 v78, v78, v14, v170
	v_fma_f32 v79, v79, v15, v171
	v_fma_f32 v80, v80, v16, v172
	v_fma_f32 v81, v81, v17, v173
	v_fma_f32 v82, v82, v18, v174
	v_fma_f32 v83, v83, v19, v175
	global_store_dwordx4 v0, v[68:71], s[76:77] offset:0
	global_store_dwordx4 v0, v[72:75], s[76:77] offset:1024
	global_store_dwordx4 v0, v[76:79], s[76:77] offset:2048
	global_store_dwordx4 v0, v[80:83], s[76:77] offset:3072
	s_add_u32 s76, s76, 0x800000
	s_addc_u32 s77, s77, 0
	s_waitcnt vmcnt(28)
	v_lshlrev_b32_e32 v68, 16, v52
	v_and_b32_e32 v69, 0xffff0000, v52
	v_lshlrev_b32_e32 v70, 16, v53
	v_and_b32_e32 v71, 0xffff0000, v53
	v_lshlrev_b32_e32 v72, 16, v54
	v_and_b32_e32 v73, 0xffff0000, v54
	v_lshlrev_b32_e32 v74, 16, v55
	v_and_b32_e32 v75, 0xffff0000, v55
	v_lshlrev_b32_e32 v76, 16, v56
	v_and_b32_e32 v77, 0xffff0000, v56
	v_lshlrev_b32_e32 v78, 16, v57
	v_and_b32_e32 v79, 0xffff0000, v57
	v_lshlrev_b32_e32 v80, 16, v58
	v_and_b32_e32 v81, 0xffff0000, v58
	v_lshlrev_b32_e32 v82, 16, v59
	v_and_b32_e32 v83, 0xffff0000, v59
	v_mul_f32_e32 v86, v68, v68
	v_mul_f32_e32 v87, v72, v72
	v_mul_f32_e32 v88, v76, v76
	v_mul_f32_e32 v89, v80, v80
	v_fmac_f32_e32 v86, v69, v69
	v_fmac_f32_e32 v87, v73, v73
	v_fmac_f32_e32 v88, v77, v77
	v_fmac_f32_e32 v89, v81, v81
	v_fmac_f32_e32 v86, v70, v70
	v_fmac_f32_e32 v87, v74, v74
	v_fmac_f32_e32 v88, v78, v78
	v_fmac_f32_e32 v89, v82, v82
	v_fmac_f32_e32 v86, v71, v71
	v_fmac_f32_e32 v87, v75, v75
	v_fmac_f32_e32 v88, v79, v79
	v_fmac_f32_e32 v89, v83, v83
	v_add_f32_e32 v84, v86, v87
	v_add_f32_e32 v84, v84, v88
	v_add_f32_e32 v84, v84, v89
	v_lshlrev_b32_e32 v160, 16, v60
	v_and_b32_e32 v161, 0xffff0000, v60
	v_add_f32_dpp v84, v84, v84 quad_perm:[1,0,3,2] row_mask:0xf bank_mask:0xf
	v_lshlrev_b32_e32 v162, 16, v61
	v_and_b32_e32 v163, 0xffff0000, v61
	v_add_f32_dpp v84, v84, v84 quad_perm:[2,3,0,1] row_mask:0xf bank_mask:0xf
	v_lshlrev_b32_e32 v164, 16, v62
	v_and_b32_e32 v165, 0xffff0000, v62
	v_add_f32_dpp v84, v84, v84 row_half_mirror row_mask:0xf bank_mask:0xf
	v_lshlrev_b32_e32 v166, 16, v63
	v_and_b32_e32 v167, 0xffff0000, v63
	v_add_f32_dpp v84, v84, v84 row_mirror row_mask:0xf bank_mask:0xf
	v_lshlrev_b32_e32 v168, 16, v64
	v_and_b32_e32 v169, 0xffff0000, v64
	v_add_f32_dpp v84, v84, v84 row_bcast:15 row_mask:0xa bank_mask:0xf
	v_lshlrev_b32_e32 v170, 16, v65
	v_and_b32_e32 v171, 0xffff0000, v65
	v_add_f32_dpp v84, v84, v84 row_bcast:31 row_mask:0xc bank_mask:0xf
	v_lshlrev_b32_e32 v172, 16, v66
	v_and_b32_e32 v173, 0xffff0000, v66
	v_lshlrev_b32_e32 v174, 16, v67
	v_and_b32_e32 v175, 0xffff0000, v67
	s_nop 0
	v_readlane_b32 s83, v84, 63
	s_nop 2
	v_fma_f32 v84, s83, v2, v3
	v_rsq_f32_e32 v84, v84
	s_nop 0
	v_mul_f32_e32 v68, v68, v84
	v_mul_f32_e32 v69, v69, v84
	v_mul_f32_e32 v70, v70, v84
	v_mul_f32_e32 v71, v71, v84
	v_mul_f32_e32 v72, v72, v84
	v_mul_f32_e32 v73, v73, v84
	v_mul_f32_e32 v74, v74, v84
	v_mul_f32_e32 v75, v75, v84
	v_mul_f32_e32 v76, v76, v84
	v_mul_f32_e32 v77, v77, v84
	v_mul_f32_e32 v78, v78, v84
	v_mul_f32_e32 v79, v79, v84
	v_mul_f32_e32 v80, v80, v84
	v_mul_f32_e32 v81, v81, v84
	v_mul_f32_e32 v82, v82, v84
	v_mul_f32_e32 v83, v83, v84
	v_fma_f32 v68, v68, v4, v160
	v_fma_f32 v69, v69, v5, v161
	v_fma_f32 v70, v70, v6, v162
	v_fma_f32 v71, v71, v7, v163
	v_fma_f32 v72, v72, v8, v164
	v_fma_f32 v73, v73, v9, v165
	v_fma_f32 v74, v74, v10, v166
	v_fma_f32 v75, v75, v11, v167
	v_fma_f32 v76, v76, v12, v168
	v_fma_f32 v77, v77, v13, v169
	v_fma_f32 v78, v78, v14, v170
	v_fma_f32 v79, v79, v15, v171
	v_fma_f32 v80, v80, v16, v172
	v_fma_f32 v81, v81, v17, v173
	v_fma_f32 v82, v82, v18, v174
	v_fma_f32 v83, v83, v19, v175
	global_store_dwordx4 v0, v[68:71], s[76:77] offset:0
	global_store_dwordx4 v0, v[72:75], s[76:77] offset:1024
	global_store_dwordx4 v0, v[76:79], s[76:77] offset:2048
	global_store_dwordx4 v0, v[80:83], s[76:77] offset:3072
	s_add_u32 s76, s76, 0x800000
	s_addc_u32 s77, s77, 0
	s_waitcnt vmcnt(20)
	v_lshlrev_b32_e32 v68, 16, v184
	v_and_b32_e32 v69, 0xffff0000, v184
	v_lshlrev_b32_e32 v70, 16, v185
	v_and_b32_e32 v71, 0xffff0000, v185
	v_lshlrev_b32_e32 v72, 16, v186
	v_and_b32_e32 v73, 0xffff0000, v186
	v_lshlrev_b32_e32 v74, 16, v187
	v_and_b32_e32 v75, 0xffff0000, v187
	v_lshlrev_b32_e32 v76, 16, v188
	v_and_b32_e32 v77, 0xffff0000, v188
	v_lshlrev_b32_e32 v78, 16, v189
	v_and_b32_e32 v79, 0xffff0000, v189
	v_lshlrev_b32_e32 v80, 16, v190
	v_and_b32_e32 v81, 0xffff0000, v190
	v_lshlrev_b32_e32 v82, 16, v191
	v_and_b32_e32 v83, 0xffff0000, v191
	v_mul_f32_e32 v86, v68, v68
	v_mul_f32_e32 v87, v72, v72
	v_mul_f32_e32 v88, v76, v76
	v_mul_f32_e32 v89, v80, v80
	v_fmac_f32_e32 v86, v69, v69
	v_fmac_f32_e32 v87, v73, v73
	v_fmac_f32_e32 v88, v77, v77
	v_fmac_f32_e32 v89, v81, v81
	v_fmac_f32_e32 v86, v70, v70
	v_fmac_f32_e32 v87, v74, v74
	v_fmac_f32_e32 v88, v78, v78
	v_fmac_f32_e32 v89, v82, v82
	v_fmac_f32_e32 v86, v71, v71
	v_fmac_f32_e32 v87, v75, v75
	v_fmac_f32_e32 v88, v79, v79
	v_fmac_f32_e32 v89, v83, v83
	v_add_f32_e32 v84, v86, v87
	v_add_f32_e32 v84, v84, v88
	v_add_f32_e32 v84, v84, v89
	v_lshlrev_b32_e32 v160, 16, v192
	v_and_b32_e32 v161, 0xffff0000, v192
	v_add_f32_dpp v84, v84, v84 quad_perm:[1,0,3,2] row_mask:0xf bank_mask:0xf
	v_lshlrev_b32_e32 v162, 16, v193
	v_and_b32_e32 v163, 0xffff0000, v193
	v_add_f32_dpp v84, v84, v84 quad_perm:[2,3,0,1] row_mask:0xf bank_mask:0xf
	v_lshlrev_b32_e32 v164, 16, v194
	v_and_b32_e32 v165, 0xffff0000, v194
	v_add_f32_dpp v84, v84, v84 row_half_mirror row_mask:0xf bank_mask:0xf
	v_lshlrev_b32_e32 v166, 16, v195
	v_and_b32_e32 v167, 0xffff0000, v195
	v_add_f32_dpp v84, v84, v84 row_mirror row_mask:0xf bank_mask:0xf
	v_lshlrev_b32_e32 v168, 16, v196
	v_and_b32_e32 v169, 0xffff0000, v196
	v_add_f32_dpp v84, v84, v84 row_bcast:15 row_mask:0xa bank_mask:0xf
	v_lshlrev_b32_e32 v170, 16, v197
	v_and_b32_e32 v171, 0xffff0000, v197
	v_add_f32_dpp v84, v84, v84 row_bcast:31 row_mask:0xc bank_mask:0xf
	v_lshlrev_b32_e32 v172, 16, v198
	v_and_b32_e32 v173, 0xffff0000, v198
	v_lshlrev_b32_e32 v174, 16, v199
	v_and_b32_e32 v175, 0xffff0000, v199
	s_nop 0
	v_readlane_b32 s83, v84, 63
	s_nop 2
	v_fma_f32 v84, s83, v2, v3
	v_rsq_f32_e32 v84, v84
	s_nop 0
	v_mul_f32_e32 v68, v68, v84
	v_mul_f32_e32 v69, v69, v84
	v_mul_f32_e32 v70, v70, v84
	v_mul_f32_e32 v71, v71, v84
	v_mul_f32_e32 v72, v72, v84
	v_mul_f32_e32 v73, v73, v84
	v_mul_f32_e32 v74, v74, v84
	v_mul_f32_e32 v75, v75, v84
	v_mul_f32_e32 v76, v76, v84
	v_mul_f32_e32 v77, v77, v84
	v_mul_f32_e32 v78, v78, v84
	v_mul_f32_e32 v79, v79, v84
	v_mul_f32_e32 v80, v80, v84
	v_mul_f32_e32 v81, v81, v84
	v_mul_f32_e32 v82, v82, v84
	v_mul_f32_e32 v83, v83, v84
	v_fma_f32 v68, v68, v4, v160
	v_fma_f32 v69, v69, v5, v161
	v_fma_f32 v70, v70, v6, v162
	v_fma_f32 v71, v71, v7, v163
	v_fma_f32 v72, v72, v8, v164
	v_fma_f32 v73, v73, v9, v165
	v_fma_f32 v74, v74, v10, v166
	v_fma_f32 v75, v75, v11, v167
	v_fma_f32 v76, v76, v12, v168
	v_fma_f32 v77, v77, v13, v169
	v_fma_f32 v78, v78, v14, v170
	v_fma_f32 v79, v79, v15, v171
	v_fma_f32 v80, v80, v16, v172
	v_fma_f32 v81, v81, v17, v173
	v_fma_f32 v82, v82, v18, v174
	v_fma_f32 v83, v83, v19, v175
	global_store_dwordx4 v0, v[68:71], s[76:77] offset:0
	global_store_dwordx4 v0, v[72:75], s[76:77] offset:1024
	global_store_dwordx4 v0, v[76:79], s[76:77] offset:2048
	global_store_dwordx4 v0, v[80:83], s[76:77] offset:3072
	s_add_u32 s76, s76, 0x800000
	s_addc_u32 s77, s77, 0
	s_cmp_eq_u32 s82, 0
	s_cbranch_scc1 .Lrows_p16_done
	s_waitcnt vmcnt(12)
	v_lshlrev_b32_e32 v68, 16, v20
	v_and_b32_e32 v69, 0xffff0000, v20
	v_lshlrev_b32_e32 v70, 16, v21
	v_and_b32_e32 v71, 0xffff0000, v21
	v_lshlrev_b32_e32 v72, 16, v22
	v_and_b32_e32 v73, 0xffff0000, v22
	v_lshlrev_b32_e32 v74, 16, v23
	v_and_b32_e32 v75, 0xffff0000, v23
	v_lshlrev_b32_e32 v76, 16, v24
	v_and_b32_e32 v77, 0xffff0000, v24
	v_lshlrev_b32_e32 v78, 16, v25
	v_and_b32_e32 v79, 0xffff0000, v25
	v_lshlrev_b32_e32 v80, 16, v26
	v_and_b32_e32 v81, 0xffff0000, v26
	v_lshlrev_b32_e32 v82, 16, v27
	v_and_b32_e32 v83, 0xffff0000, v27
	v_mul_f32_e32 v86, v68, v68
	v_mul_f32_e32 v87, v72, v72
	v_mul_f32_e32 v88, v76, v76
	v_mul_f32_e32 v89, v80, v80
	v_fmac_f32_e32 v86, v69, v69
	v_fmac_f32_e32 v87, v73, v73
	v_fmac_f32_e32 v88, v77, v77
	v_fmac_f32_e32 v89, v81, v81
	v_fmac_f32_e32 v86, v70, v70
	v_fmac_f32_e32 v87, v74, v74
	v_fmac_f32_e32 v88, v78, v78
	v_fmac_f32_e32 v89, v82, v82
	v_fmac_f32_e32 v86, v71, v71
	v_fmac_f32_e32 v87, v75, v75
	v_fmac_f32_e32 v88, v79, v79
	v_fmac_f32_e32 v89, v83, v83
	v_add_f32_e32 v84, v86, v87
	v_add_f32_e32 v84, v84, v88
	v_add_f32_e32 v84, v84, v89
	v_lshlrev_b32_e32 v160, 16, v28
	v_and_b32_e32 v161, 0xffff0000, v28
	v_add_f32_dpp v84, v84, v84 quad_perm:[1,0,3,2] row_mask:0xf bank_mask:0xf
	v_lshlrev_b32_e32 v162, 16, v29
	v_and_b32_e32 v163, 0xffff0000, v29
	v_add_f32_dpp v84, v84, v84 quad_perm:[2,3,0,1] row_mask:0xf bank_mask:0xf
	v_lshlrev_b32_e32 v164, 16, v30
	v_and_b32_e32 v165, 0xffff0000, v30
	v_add_f32_dpp v84, v84, v84 row_half_mirror row_mask:0xf bank_mask:0xf
	v_lshlrev_b32_e32 v166, 16, v31
	v_and_b32_e32 v167, 0xffff0000, v31
	v_add_f32_dpp v84, v84, v84 row_mirror row_mask:0xf bank_mask:0xf
	v_lshlrev_b32_e32 v168, 16, v32
	v_and_b32_e32 v169, 0xffff0000, v32
	v_add_f32_dpp v84, v84, v84 row_bcast:15 row_mask:0xa bank_mask:0xf
	v_lshlrev_b32_e32 v170, 16, v33
	v_and_b32_e32 v171, 0xffff0000, v33
	v_add_f32_dpp v84, v84, v84 row_bcast:31 row_mask:0xc bank_mask:0xf
	v_lshlrev_b32_e32 v172, 16, v34
	v_and_b32_e32 v173, 0xffff0000, v34
	v_lshlrev_b32_e32 v174, 16, v35
	v_and_b32_e32 v175, 0xffff0000, v35
	s_nop 0
	v_readlane_b32 s83, v84, 63
	s_nop 2
	v_fma_f32 v84, s83, v2, v3
	v_rsq_f32_e32 v84, v84
	s_nop 0
	v_mul_f32_e32 v68, v68, v84
	v_mul_f32_e32 v69, v69, v84
	v_mul_f32_e32 v70, v70, v84
	v_mul_f32_e32 v71, v71, v84
	v_mul_f32_e32 v72, v72, v84
	v_mul_f32_e32 v73, v73, v84
	v_mul_f32_e32 v74, v74, v84
	v_mul_f32_e32 v75, v75, v84
	v_mul_f32_e32 v76, v76, v84
	v_mul_f32_e32 v77, v77, v84
	v_mul_f32_e32 v78, v78, v84
	v_mul_f32_e32 v79, v79, v84
	v_mul_f32_e32 v80, v80, v84
	v_mul_f32_e32 v81, v81, v84
	v_mul_f32_e32 v82, v82, v84
	v_mul_f32_e32 v83, v83, v84
	v_fma_f32 v68, v68, v4, v160
	v_fma_f32 v69, v69, v5, v161
	v_fma_f32 v70, v70, v6, v162
	v_fma_f32 v71, v71, v7, v163
	v_fma_f32 v72, v72, v8, v164
	v_fma_f32 v73, v73, v9, v165
	v_fma_f32 v74, v74, v10, v166
	v_fma_f32 v75, v75, v11, v167
	v_fma_f32 v76, v76, v12, v168
	v_fma_f32 v77, v77, v13, v169
	v_fma_f32 v78, v78, v14, v170
	v_fma_f32 v79, v79, v15, v171
	v_fma_f32 v80, v80, v16, v172
	v_fma_f32 v81, v81, v17, v173
	v_fma_f32 v82, v82, v18, v174
	v_fma_f32 v83, v83, v19, v175
	global_store_dwordx4 v0, v[68:71], s[76:77] offset:0
	global_store_dwordx4 v0, v[72:75], s[76:77] offset:1024
	global_store_dwordx4 v0, v[76:79], s[76:77] offset:2048
	global_store_dwordx4 v0, v[80:83], s[76:77] offset:3072
	s_add_u32 s76, s76, 0x800000
	s_addc_u32 s77, s77, 0
